# s_setprio 3 around the B2 chunk-scan step loops (scan waves win issue arbitration over co-resident GEMM waves)
# baseline (speedup 1.0000x reference)
; #define MFMA32(a, b, c) __builtin_amdgcn_mfma_f32_32x32x16_bf16((a), (b), (c), 0, 0, 0)
; #define B2_STORE() do { uint4* l_ = (uint4*)L + tid; \
;     l_[0] = pw0; l_[256] = pw1; l_[512] = pw2; l_[768] = pw3; l_[1024] = pq0; l_[1280] = pq1; l_[1536] = pq2; l_[1792] = pq3; \
;     l_[2048] = pk0; l_[2304] = pk1; l_[2560] = pk2; l_[2816] = pk3; l_[3072] = pa0; l_[3328] = pa1; } while (0)
; DI void phaseB2(const Params& p, int bh, char* smem, int n_begin, int n_end) {
;     ...
;   __syncthreads();
;   B2_LOAD(n_begin);
;   B2_LOADU(n_begin);
;   B2_STORE();
;   __syncthreads();
; #pragma unroll 1
;   for (int n = n_begin; n < n_end; ++n) {
;     B2_LOAD(n + 1 < 32 ? n + 1 : n);
;     f32x16 vn[2], o[2];
; #pragma unroll
;     for (int it = 0; it < 2; ++it) {
;       f32x16 aw;
; #pragma unroll
;       for (int e = 0; e < 16; ++e) aw[e] = 0.f;
; #pragma unroll
;       for (int T = 0; T < 4; ++T)
; #pragma unroll
;         for (int s = 0; s < 2; ++s) aw = MFMA32(ld16(wg + (it * 4096 + (T * 2 + s) * 512) + lo8), pack8(S[T], s), aw);
; #pragma unroll
;       for (int g = 0; g < 4; ++g) {
;         const uint2 uu = it == 0 ? (g == 0 ? pu0 : g == 1 ? pu1 : g == 2 ? pu2 : pu3) : (g == 0 ? pu4 : g == 1 ? pu5 : g == 2 ? pu6 : pu7);
;         vn[it][4 * g + 0] = __uint_as_float(uu.x << 16) - aw[4 * g + 0];
;         vn[it][4 * g + 1] = __uint_as_float(uu.x & 0xffff0000u) - aw[4 * g + 1];
;         vn[it][4 * g + 2] = __uint_as_float(uu.y << 16) - aw[4 * g + 2];
;         vn[it][4 * g + 3] = __uint_as_float(uu.y & 0xffff0000u) - aw[4 * g + 3];
;       }
;     }
.LBB0_798:
	s_setprio 3
	s_add_i32 s2, s0, 1
	s_cmp_lt_u32 s0, 31
	s_cselect_b32 s0, s2, s0
	s_add_i32 s0, s0, s10
	s_lshl_b32 s0, s0, 2
	s_or_b32 s0, s0, s9
	s_ashr_i32 s1, s0, 31
	s_lshl_b64 s[4:5], s[0:1], 13
	s_lshl_b64 s[0:1], s[0:1], 14
	v_lshl_add_u64 v[66:67], v[210:211], 0, s[0:1]
	v_add_co_u32_e32 v74, vcc, s80, v66
	global_load_dwordx4 v[98:101], v[66:67], off
	s_nop 0
	v_addc_co_u32_e32 v75, vcc, 0, v67, vcc
	v_add_co_u32_e32 v66, vcc, s81, v66
	v_lshl_add_u64 v[68:69], v[212:213], 0, s[0:1]
	s_nop 0
	v_addc_co_u32_e32 v67, vcc, 0, v67, vcc
	global_load_dwordx4 v[102:105], v[74:75], off offset:-4096
	global_load_dwordx4 v[106:109], v[74:75], off
	global_load_dwordx4 v[110:113], v[66:67], off
	global_load_dwordx4 v[114:117], v[68:69], off
	v_add_co_u32_e32 v66, vcc, s80, v68
	v_lshl_add_u64 v[70:71], v[214:215], 0, s[0:1]
	s_nop 0
	v_addc_co_u32_e32 v67, vcc, 0, v69, vcc
	global_load_dwordx4 v[118:121], v[66:67], off offset:-4096
	global_load_dwordx4 v[122:125], v[66:67], off
	v_add_co_u32_e32 v66, vcc, s81, v68
	v_lshl_add_u64 v[72:73], v[216:217], 0, s[4:5]
	s_nop 0
	v_addc_co_u32_e32 v67, vcc, 0, v69, vcc
	global_load_dwordx4 v[126:129], v[66:67], off
	global_load_dwordx4 v[130:133], v[70:71], off
	v_add_co_u32_e32 v66, vcc, s80, v70
	v_cvt_pk_bf16_f32 v198, v2, v3
	s_nop 0
	v_addc_co_u32_e32 v67, vcc, 0, v71, vcc
	global_load_dwordx4 v[134:137], v[66:67], off offset:-4096
	global_load_dwordx4 v[138:141], v[66:67], off
	v_add_co_u32_e32 v66, vcc, s81, v70
	v_cvt_pk_bf16_f32 v199, v4, v5
	s_nop 0
	v_addc_co_u32_e32 v67, vcc, 0, v71, vcc
	global_load_dwordx4 v[142:145], v[66:67], off
	global_load_dwordx4 v[146:149], v[72:73], off
	v_add_co_u32_e32 v66, vcc, s97, v72
	v_cvt_pk_bf16_f32 v200, v6, v7
	s_nop 0
	v_addc_co_u32_e32 v67, vcc, 0, v73, vcc
	global_load_dwordx4 v[150:153], v[66:67], off
	ds_read_b128 v[66:69], v242
	ds_read_b128 v[82:85], v242 offset:1024
	v_cvt_pk_bf16_f32 v201, v8, v9
	v_cvt_pk_bf16_f32 v194, v10, v11
	v_cvt_pk_bf16_f32 v195, v12, v13
	s_waitcnt lgkmcnt(1)
	v_mfma_f32_32x32x16_bf16 v[66:81], v[66:69], v[198:201], 0
	v_cvt_pk_bf16_f32 v196, v14, v15
	v_cvt_pk_bf16_f32 v197, v16, v17
	v_cvt_pk_bf16_f32 v190, v18, v19
	v_cvt_pk_bf16_f32 v191, v20, v21
	v_cvt_pk_bf16_f32 v192, v22, v23
	v_cvt_pk_bf16_f32 v193, v24, v25
	v_cvt_pk_bf16_f32 v186, v26, v27
	s_waitcnt lgkmcnt(0)
	v_mfma_f32_32x32x16_bf16 v[66:81], v[82:85], v[194:197], v[66:81]
	ds_read_b128 v[82:85], v242 offset:2048
	v_cvt_pk_bf16_f32 v187, v28, v29
	v_cvt_pk_bf16_f32 v188, v30, v31
	v_cvt_pk_bf16_f32 v189, v32, v33
	v_cvt_pk_bf16_f32 v182, v34, v35
	v_cvt_pk_bf16_f32 v183, v36, v37
	v_cvt_pk_bf16_f32 v184, v38, v39
	s_waitcnt lgkmcnt(0)
	v_mfma_f32_32x32x16_bf16 v[66:81], v[82:85], v[190:193], v[66:81]
	ds_read_b128 v[82:85], v242 offset:3072
	v_cvt_pk_bf16_f32 v185, v40, v41
	v_cvt_pk_bf16_f32 v178, v42, v43
	v_cvt_pk_bf16_f32 v179, v44, v45
	v_cvt_pk_bf16_f32 v180, v46, v47
	v_cvt_pk_bf16_f32 v181, v48, v49
	v_cvt_pk_bf16_f32 v174, v50, v51
	s_waitcnt lgkmcnt(0)
	v_mfma_f32_32x32x16_bf16 v[66:81], v[82:85], v[186:189], v[66:81]
	ds_read_b128 v[82:85], v242 offset:4096
	v_cvt_pk_bf16_f32 v175, v52, v53
	v_cvt_pk_bf16_f32 v176, v54, v55
	v_cvt_pk_bf16_f32 v177, v56, v57
	v_cvt_pk_bf16_f32 v166, v58, v59
	v_cvt_pk_bf16_f32 v167, v60, v61
	v_cvt_pk_bf16_f32 v168, v62, v63
	s_waitcnt lgkmcnt(0)
	v_mfma_f32_32x32x16_bf16 v[66:81], v[82:85], v[182:185], v[66:81]
	ds_read_b128 v[82:85], v242 offset:5120
	v_cvt_pk_bf16_f32 v169, v64, v65
	s_waitcnt vmcnt(21)
	v_lshlrev_b32_e32 v0, 16, v228
	s_cmp_lg_u32 s2, 32
	s_waitcnt lgkmcnt(0)
	v_mfma_f32_32x32x16_bf16 v[66:81], v[82:85], v[178:181], v[66:81]
	ds_read_b128 v[82:85], v242 offset:6144
	s_waitcnt lgkmcnt(0)
	v_mfma_f32_32x32x16_bf16 v[66:81], v[82:85], v[174:177], v[66:81]
	ds_read_b128 v[82:85], v242 offset:7168
	s_waitcnt lgkmcnt(0)
	v_mfma_f32_32x32x16_bf16 v[66:81], v[82:85], v[166:169], v[66:81]
	ds_read_b128 v[82:85], v242 offset:9216
	s_nop 10
	v_sub_f32_e32 v0, v0, v66
	v_and_b32_e32 v66, 0xffff0000, v228
	v_sub_f32_e32 v86, v66, v67
	v_lshlrev_b32_e32 v66, 16, v229
	v_sub_f32_e32 v87, v66, v68
	v_and_b32_e32 v66, 0xffff0000, v229
	v_sub_f32_e32 v88, v66, v69
	s_waitcnt vmcnt(20)
	v_lshlrev_b32_e32 v66, 16, v226
	v_sub_f32_e32 v89, v66, v70
	v_and_b32_e32 v66, 0xffff0000, v226
	v_sub_f32_e32 v90, v66, v71
	v_lshlrev_b32_e32 v66, 16, v227
	v_sub_f32_e32 v91, v66, v72
	v_and_b32_e32 v66, 0xffff0000, v227
	v_sub_f32_e32 v92, v66, v73
	s_waitcnt vmcnt(19)
	v_lshlrev_b32_e32 v66, 16, v224
	v_sub_f32_e32 v93, v66, v74
	v_and_b32_e32 v66, 0xffff0000, v224
	v_sub_f32_e32 v94, v66, v75
	v_lshlrev_b32_e32 v66, 16, v225
	v_sub_f32_e32 v95, v66, v76
	v_and_b32_e32 v66, 0xffff0000, v225
	v_sub_f32_e32 v96, v66, v77
	s_waitcnt vmcnt(18)
	v_lshlrev_b32_e32 v66, 16, v222
	v_sub_f32_e32 v97, v66, v78
	v_and_b32_e32 v66, 0xffff0000, v222
	v_sub_f32_e32 v154, v66, v79
	v_lshlrev_b32_e32 v66, 16, v223
	v_sub_f32_e32 v155, v66, v80
	v_and_b32_e32 v66, 0xffff0000, v223
	v_sub_f32_e32 v156, v66, v81
	ds_read_b128 v[66:69], v242 offset:8192
	s_waitcnt lgkmcnt(0)
	v_mfma_f32_32x32x16_bf16 v[66:81], v[66:69], v[198:201], 0
	v_cvt_pk_bf16_f32 v170, v0, v86
	v_cvt_pk_bf16_f32 v171, v87, v88
	v_cvt_pk_bf16_f32 v172, v89, v90
	v_cvt_pk_bf16_f32 v173, v91, v92
	v_cvt_pk_bf16_f32 v162, v93, v94
	v_cvt_pk_bf16_f32 v163, v95, v96
	v_cvt_pk_bf16_f32 v164, v97, v154
	v_mfma_f32_32x32x16_bf16 v[66:81], v[82:85], v[194:197], v[66:81]
	ds_read_b128 v[82:85], v242 offset:10240
	v_cvt_pk_bf16_f32 v165, v155, v156
	ds_bpermute_b32 v0, v243, v240
	v_add_u32_e32 v243, 4, v243
	s_waitcnt lgkmcnt(0)
; #define MFMA32(a, b, c) __builtin_amdgcn_mfma_f32_32x32x16_bf16((a), (b), (c), 0, 0, 0)
; DI void phaseB2(const Params& p, int bh, char* smem, int n_begin, int n_end) {
;     ...
;     for (int it = 0; it < 2; ++it) {
;       f32x16 aw;
; #pragma unroll
;       for (int e = 0; e < 16; ++e) aw[e] = 0.f;
; #pragma unroll
;       for (int T = 0; T < 4; ++T)
; #pragma unroll
;         for (int s = 0; s < 2; ++s) aw = MFMA32(ld16(wg + (it * 4096 + (T * 2 + s) * 512) + lo8), pack8(S[T], s), aw);
; #pragma unroll
;       for (int g = 0; g < 4; ++g) {
;         const uint2 uu = it == 0 ? (g == 0 ? pu0 : g == 1 ? pu1 : g == 2 ? pu2 : pu3) : (g == 0 ? pu4 : g == 1 ? pu5 : g == 2 ? pu6 : pu7);
;         vn[it][4 * g + 0] = __uint_as_float(uu.x << 16) - aw[4 * g + 0];
;         vn[it][4 * g + 1] = __uint_as_float(uu.x & 0xffff0000u) - aw[4 * g + 1];
;         vn[it][4 * g + 2] = __uint_as_float(uu.y << 16) - aw[4 * g + 2];
;         vn[it][4 * g + 3] = __uint_as_float(uu.y & 0xffff0000u) - aw[4 * g + 3];
;       }
;     }
;     B2_LOADU(n + 1 < 32 ? n + 1 : n);
;     bf16x8 Vb[2][2];
; #pragma unroll
;     for (int jt = 0; jt < 2; ++jt) { Vb[jt][0] = pack8(vn[jt], 0); Vb[jt][1] = pack8(vn[jt], 1); }
; #pragma unroll
;     for (int it = 0; it < 2; ++it) {
; #pragma unroll
;       for (int e = 0; e < 16; ++e) o[it][e] = 0.f;
; #pragma unroll
;       for (int T = 0; T < 4; ++T)
; #pragma unroll
;         for (int s = 0; s < 2; ++s) o[it] = MFMA32(ld16(qg + (it * 4096 + (T * 2 + s) * 512) + lo8), pack8(S[T], s), o[it]);
; #pragma unroll
;       for (int jt = 0; jt < 2; ++jt)
; #pragma unroll
;         for (int s = 0; s < 2; ++s)
;           o[it] = MFMA32(ld16(ag + (it * 2048 + (jt * 2 + s) * 512) + lo8), Vb[jt][s], o[it]);
;     }
;     const float egl = __shfl(eglv, n);
; #pragma unroll
;     for (int T = 0; T < 4; ++T) {
;       f32x16 acc;
; #pragma unroll
;       for (int e = 0; e < 16; ++e) acc[e] = S[T][e] * egl;
	v_pk_mul_f32 v[16:17], v[16:17], v[0:1] op_sel_hi:[1,0]
	v_mfma_f32_32x32x16_bf16 v[66:81], v[82:85], v[190:193], v[66:81]
	ds_read_b128 v[82:85], v242 offset:11264
	v_mul_f32_e64 v14, v14, v0
	v_mul_f32_e64 v15, v15, v0
	v_mul_f32_e64 v12, v12, v0
	v_mul_f32_e64 v13, v13, v0
	v_pk_mul_f32 v[10:11], v[10:11], v[0:1] op_sel_hi:[1,0]
	v_pk_mul_f32 v[8:9], v[8:9], v[0:1] op_sel_hi:[1,0]
	v_pk_mul_f32 v[6:7], v[6:7], v[0:1] op_sel_hi:[1,0]
	v_pk_mul_f32 v[4:5], v[4:5], v[0:1] op_sel_hi:[1,0]
	s_waitcnt lgkmcnt(0)
	v_mfma_f32_32x32x16_bf16 v[66:81], v[82:85], v[186:189], v[66:81]
	ds_read_b128 v[82:85], v242 offset:12288
	v_mul_f32_e64 v2, v2, v0
	v_mul_f32_e64 v3, v3, v0
	v_mul_f32_e64 v32, v32, v0
	v_mul_f32_e64 v33, v33, v0
	v_pk_mul_f32 v[30:31], v[30:31], v[0:1] op_sel_hi:[1,0]
	v_pk_mul_f32 v[28:29], v[28:29], v[0:1] op_sel_hi:[1,0]
	v_pk_mul_f32 v[26:27], v[26:27], v[0:1] op_sel_hi:[1,0]
	v_pk_mul_f32 v[24:25], v[24:25], v[0:1] op_sel_hi:[1,0]
	s_waitcnt lgkmcnt(0)
	v_mfma_f32_32x32x16_bf16 v[66:81], v[82:85], v[182:185], v[66:81]
	ds_read_b128 v[82:85], v242 offset:13312
	v_mul_f32_e64 v22, v22, v0
	v_mul_f32_e64 v23, v23, v0
	v_mul_f32_e64 v20, v20, v0
	v_mul_f32_e64 v21, v21, v0
	v_pk_mul_f32 v[18:19], v[18:19], v[0:1] op_sel_hi:[1,0]
	v_pk_mul_f32 v[48:49], v[48:49], v[0:1] op_sel_hi:[1,0]
	v_pk_mul_f32 v[46:47], v[46:47], v[0:1] op_sel_hi:[1,0]
	v_pk_mul_f32 v[44:45], v[44:45], v[0:1] op_sel_hi:[1,0]
	s_waitcnt lgkmcnt(0)
	v_mfma_f32_32x32x16_bf16 v[66:81], v[82:85], v[178:181], v[66:81]
	ds_read_b128 v[82:85], v242 offset:14336
	v_mul_f32_e64 v42, v42, v0
	v_mul_f32_e64 v43, v43, v0
	v_mul_f32_e64 v40, v40, v0
	v_mul_f32_e64 v41, v41, v0
	v_pk_mul_f32 v[38:39], v[38:39], v[0:1] op_sel_hi:[1,0]
	v_pk_mul_f32 v[36:37], v[36:37], v[0:1] op_sel_hi:[1,0]
	v_pk_mul_f32 v[34:35], v[34:35], v[0:1] op_sel_hi:[1,0]
	v_pk_mul_f32 v[64:65], v[64:65], v[0:1] op_sel_hi:[1,0]
	s_waitcnt lgkmcnt(0)
	v_mfma_f32_32x32x16_bf16 v[66:81], v[82:85], v[174:177], v[66:81]
	ds_read_b128 v[82:85], v242 offset:15360
	v_mul_f32_e64 v62, v62, v0
	v_mul_f32_e64 v63, v63, v0
	v_mul_f32_e64 v60, v60, v0
	v_mul_f32_e64 v61, v61, v0
	v_pk_mul_f32 v[58:59], v[58:59], v[0:1] op_sel_hi:[1,0]
	v_pk_mul_f32 v[56:57], v[56:57], v[0:1] op_sel_hi:[1,0]
	v_pk_mul_f32 v[54:55], v[54:55], v[0:1] op_sel_hi:[1,0]
	v_pk_mul_f32 v[52:53], v[52:53], v[0:1] op_sel_hi:[1,0]
	s_waitcnt lgkmcnt(0)
	v_mfma_f32_32x32x16_bf16 v[66:81], v[82:85], v[166:169], v[66:81]
	s_waitcnt vmcnt(17)
	v_lshlrev_b32_e32 v82, 16, v208
	v_and_b32_e32 v83, 0xffff0000, v208
	v_mul_f32_e64 v50, v50, v0
	v_mul_f32_e64 v51, v51, v0
	s_nop 6
	v_pk_add_f32 v[66:67], v[82:83], v[66:67] neg_lo:[0,1] neg_hi:[0,1]
	v_lshlrev_b32_e32 v82, 16, v209
	v_and_b32_e32 v83, 0xffff0000, v209
	v_pk_add_f32 v[68:69], v[82:83], v[68:69] neg_lo:[0,1] neg_hi:[0,1]
	s_waitcnt vmcnt(16)
	v_lshlrev_b32_e32 v82, 16, v206
	v_and_b32_e32 v83, 0xffff0000, v206
	v_pk_add_f32 v[70:71], v[82:83], v[70:71] neg_lo:[0,1] neg_hi:[0,1]
	v_lshlrev_b32_e32 v82, 16, v207
	v_and_b32_e32 v83, 0xffff0000, v207
	v_pk_add_f32 v[72:73], v[82:83], v[72:73] neg_lo:[0,1] neg_hi:[0,1]
	s_waitcnt vmcnt(15)
	v_lshlrev_b32_e32 v82, 16, v204
	v_and_b32_e32 v83, 0xffff0000, v204
	v_pk_add_f32 v[74:75], v[82:83], v[74:75] neg_lo:[0,1] neg_hi:[0,1]
	v_lshlrev_b32_e32 v82, 16, v205
	v_and_b32_e32 v83, 0xffff0000, v205
	v_pk_add_f32 v[76:77], v[82:83], v[76:77] neg_lo:[0,1] neg_hi:[0,1]
	s_waitcnt vmcnt(14)
	v_lshlrev_b32_e32 v82, 16, v202
	v_and_b32_e32 v83, 0xffff0000, v202
	v_pk_add_f32 v[78:79], v[82:83], v[78:79] neg_lo:[0,1] neg_hi:[0,1]
	v_lshlrev_b32_e32 v82, 16, v203
	v_and_b32_e32 v83, 0xffff0000, v203
	v_pk_add_f32 v[80:81], v[82:83], v[80:81] neg_lo:[0,1] neg_hi:[0,1]
	v_lshl_add_u64 v[82:83], v[218:219], 0, s[0:1]
	global_load_dwordx2 v[228:229], v[82:83], off
	global_load_dwordx2 v[226:227], v[82:83], off offset:512
	global_load_dwordx2 v[224:225], v[82:83], off offset:1024
	global_load_dwordx2 v[222:223], v[82:83], off offset:1536
	global_load_dwordx2 v[208:209], v[82:83], off offset:2048
	global_load_dwordx2 v[206:207], v[82:83], off offset:2560
	global_load_dwordx2 v[204:205], v[82:83], off offset:3072
	global_load_dwordx2 v[202:203], v[82:83], off offset:3584
	v_cvt_pk_bf16_f32 v158, v66, v67
	v_cvt_pk_bf16_f32 v159, v68, v69
	ds_read_b128 v[66:69], v242 offset:16384
	s_waitcnt lgkmcnt(0)
	v_mfma_f32_32x32x16_bf16 v[82:97], v[66:69], v[198:201], 0
	ds_read_b128 v[66:69], v242 offset:17408
	v_cvt_pk_bf16_f32 v160, v70, v71
	v_cvt_pk_bf16_f32 v161, v72, v73
	v_cvt_pk_bf16_f32 v154, v74, v75
	v_cvt_pk_bf16_f32 v155, v76, v77
	v_cvt_pk_bf16_f32 v156, v78, v79
	v_cvt_pk_bf16_f32 v157, v80, v81
	s_waitcnt lgkmcnt(0)
	v_mfma_f32_32x32x16_bf16 v[82:97], v[66:69], v[194:197], v[82:97]
	ds_read_b128 v[66:69], v242 offset:18432
	s_waitcnt lgkmcnt(0)
	v_mfma_f32_32x32x16_bf16 v[82:97], v[66:69], v[190:193], v[82:97]
	ds_read_b128 v[66:69], v242 offset:19456
	s_waitcnt lgkmcnt(0)
	v_mfma_f32_32x32x16_bf16 v[82:97], v[66:69], v[186:189], v[82:97]
	ds_read_b128 v[66:69], v242 offset:20480
	s_waitcnt lgkmcnt(0)
	v_mfma_f32_32x32x16_bf16 v[82:97], v[66:69], v[182:185], v[82:97]
	ds_read_b128 v[66:69], v242 offset:21504
	s_waitcnt lgkmcnt(0)
	v_mfma_f32_32x32x16_bf16 v[82:97], v[66:69], v[178:181], v[82:97]
	ds_read_b128 v[66:69], v242 offset:22528
	s_waitcnt lgkmcnt(0)
	v_mfma_f32_32x32x16_bf16 v[82:97], v[66:69], v[174:177], v[82:97]
	ds_read_b128 v[66:69], v242 offset:23552
	s_waitcnt lgkmcnt(0)
	v_mfma_f32_32x32x16_bf16 v[82:97], v[66:69], v[166:169], v[82:97]
	ds_read_b128 v[66:69], v242 offset:49152
	s_waitcnt lgkmcnt(0)
; #define MFMA32(a, b, c) __builtin_amdgcn_mfma_f32_32x32x16_bf16((a), (b), (c), 0, 0, 0)
; #define B2_STORE() do { uint4* l_ = (uint4*)L + tid; \
;     l_[0] = pw0; l_[256] = pw1; l_[512] = pw2; l_[768] = pw3; l_[1024] = pq0; l_[1280] = pq1; l_[1536] = pq2; l_[1792] = pq3; \
;     l_[2048] = pk0; l_[2304] = pk1; l_[2560] = pk2; l_[2816] = pk3; l_[3072] = pa0; l_[3328] = pa1; } while (0)
; DI void phaseB2(const Params& p, int bh, char* smem, int n_begin, int n_end) {
;     ...
; #pragma unroll
;     for (int it = 0; it < 2; ++it) {
; #pragma unroll
;       for (int e = 0; e < 16; ++e) o[it][e] = 0.f;
; #pragma unroll
;       for (int T = 0; T < 4; ++T)
; #pragma unroll
;         for (int s = 0; s < 2; ++s) o[it] = MFMA32(ld16(qg + (it * 4096 + (T * 2 + s) * 512) + lo8), pack8(S[T], s), o[it]);
; #pragma unroll
;       for (int jt = 0; jt < 2; ++jt)
; #pragma unroll
;         for (int s = 0; s < 2; ++s)
;           o[it] = MFMA32(ld16(ag + (it * 2048 + (jt * 2 + s) * 512) + lo8), Vb[jt][s], o[it]);
;     }
;     const float egl = __shfl(eglv, n);
; #pragma unroll
;     for (int T = 0; T < 4; ++T) {
;       f32x16 acc;
; #pragma unroll
;       for (int e = 0; e < 16; ++e) acc[e] = S[T][e] * egl;
; #pragma unroll
;       for (int jt = 0; jt < 2; ++jt)
; #pragma unroll
;         for (int s = 0; s < 2; ++s)
;           acc = MFMA32(ld16(kg + (T * 2048 + (jt * 2 + s) * 512) + lo8), Vb[jt][s], acc);
;       S[T] = acc;
;     }
;     asm volatile("s_waitcnt lgkmcnt(0)\n\ts_barrier" ::: "memory");
;     B2_STORE();
;     asm volatile("s_waitcnt lgkmcnt(0)\n\ts_barrier" ::: "memory");
	v_mfma_f32_32x32x16_bf16 v[82:97], v[66:69], v[170:173], v[82:97]
	ds_read_b128 v[66:69], v242 offset:50176
	s_waitcnt lgkmcnt(0)
	v_mfma_f32_32x32x16_bf16 v[82:97], v[66:69], v[162:165], v[82:97]
	ds_read_b128 v[66:69], v242 offset:51200
	s_waitcnt lgkmcnt(0)
	v_mfma_f32_32x32x16_bf16 v[82:97], v[66:69], v[158:161], v[82:97]
	ds_read_b128 v[66:69], v242 offset:52224
	s_waitcnt lgkmcnt(0)
	v_mfma_f32_32x32x16_bf16 v[82:97], v[66:69], v[154:157], v[82:97]
	ds_read_b128 v[66:69], v242 offset:24576
	s_waitcnt lgkmcnt(0)
	v_mfma_f32_32x32x16_bf16 v[66:81], v[66:69], v[198:201], 0
	ds_read_b128 v[198:201], v242 offset:25600
	s_nop 7
	v_cvt_pk_bf16_f32 v0, v82, s0
	v_add_co_u32_e32 v82, vcc, s80, v220
	s_waitcnt lgkmcnt(0)
	v_mfma_f32_32x32x16_bf16 v[66:81], v[198:201], v[194:197], v[66:81]
	ds_read_b128 v[194:197], v242 offset:26624
	s_waitcnt lgkmcnt(0)
	v_mfma_f32_32x32x16_bf16 v[66:81], v[194:197], v[190:193], v[66:81]
	ds_read_b128 v[190:193], v242 offset:27648
	s_waitcnt lgkmcnt(0)
	v_mfma_f32_32x32x16_bf16 v[66:81], v[190:193], v[186:189], v[66:81]
	ds_read_b128 v[186:189], v242 offset:28672
	s_waitcnt lgkmcnt(0)
	v_mfma_f32_32x32x16_bf16 v[66:81], v[186:189], v[182:185], v[66:81]
	ds_read_b128 v[182:185], v242 offset:29696
	s_waitcnt lgkmcnt(0)
	v_mfma_f32_32x32x16_bf16 v[66:81], v[182:185], v[178:181], v[66:81]
	ds_read_b128 v[178:181], v242 offset:30720
	s_waitcnt lgkmcnt(0)
	v_mfma_f32_32x32x16_bf16 v[66:81], v[178:181], v[174:177], v[66:81]
	ds_read_b128 v[174:177], v242 offset:31744
	s_waitcnt lgkmcnt(0)
	v_mfma_f32_32x32x16_bf16 v[66:81], v[174:177], v[166:169], v[66:81]
	ds_read_b128 v[166:169], v242 offset:53248
	s_waitcnt lgkmcnt(0)
	v_mfma_f32_32x32x16_bf16 v[66:81], v[166:169], v[170:173], v[66:81]
	ds_read_b128 v[166:169], v242 offset:54272
	s_waitcnt lgkmcnt(0)
	v_mfma_f32_32x32x16_bf16 v[66:81], v[166:169], v[162:165], v[66:81]
	ds_read_b128 v[166:169], v242 offset:55296
	s_waitcnt lgkmcnt(0)
	v_mfma_f32_32x32x16_bf16 v[66:81], v[166:169], v[158:161], v[66:81]
	ds_read_b128 v[166:169], v242 offset:56320
	s_waitcnt lgkmcnt(0)
	v_mfma_f32_32x32x16_bf16 v[66:81], v[166:169], v[154:157], v[66:81]
	ds_read_b128 v[166:169], v242 offset:32768
	s_waitcnt lgkmcnt(0)
	v_mfma_f32_32x32x16_bf16 v[2:17], v[166:169], v[170:173], v[2:17]
	ds_read_b128 v[166:169], v242 offset:33792
	s_waitcnt lgkmcnt(0)
	v_mfma_f32_32x32x16_bf16 v[2:17], v[166:169], v[162:165], v[2:17]
	ds_read_b128 v[166:169], v242 offset:34816
	s_waitcnt lgkmcnt(0)
	v_mfma_f32_32x32x16_bf16 v[2:17], v[166:169], v[158:161], v[2:17]
	ds_read_b128 v[166:169], v242 offset:35840
	s_waitcnt lgkmcnt(0)
	v_mfma_f32_32x32x16_bf16 v[2:17], v[166:169], v[154:157], v[2:17]
	ds_read_b128 v[166:169], v242 offset:36864
	s_waitcnt lgkmcnt(0)
	v_mfma_f32_32x32x16_bf16 v[18:33], v[166:169], v[170:173], v[18:33]
	ds_read_b128 v[166:169], v242 offset:37888
	s_waitcnt lgkmcnt(0)
	v_mfma_f32_32x32x16_bf16 v[18:33], v[166:169], v[162:165], v[18:33]
	ds_read_b128 v[166:169], v242 offset:38912
	s_waitcnt lgkmcnt(0)
	v_mfma_f32_32x32x16_bf16 v[18:33], v[166:169], v[158:161], v[18:33]
	ds_read_b128 v[166:169], v242 offset:39936
	s_waitcnt lgkmcnt(0)
	v_mfma_f32_32x32x16_bf16 v[18:33], v[166:169], v[154:157], v[18:33]
	ds_read_b128 v[166:169], v242 offset:40960
	s_waitcnt lgkmcnt(0)
	v_mfma_f32_32x32x16_bf16 v[34:49], v[166:169], v[170:173], v[34:49]
	ds_read_b128 v[166:169], v242 offset:41984
	s_waitcnt lgkmcnt(0)
	v_mfma_f32_32x32x16_bf16 v[34:49], v[166:169], v[162:165], v[34:49]
	ds_read_b128 v[166:169], v242 offset:43008
	s_waitcnt lgkmcnt(0)
	v_mfma_f32_32x32x16_bf16 v[34:49], v[166:169], v[158:161], v[34:49]
	ds_read_b128 v[166:169], v242 offset:44032
	s_waitcnt lgkmcnt(0)
	v_mfma_f32_32x32x16_bf16 v[34:49], v[166:169], v[154:157], v[34:49]
	ds_read_b128 v[166:169], v242 offset:45056
	s_waitcnt lgkmcnt(0)
	v_mfma_f32_32x32x16_bf16 v[50:65], v[166:169], v[170:173], v[50:65]
	ds_read_b128 v[166:169], v242 offset:46080
	s_waitcnt lgkmcnt(0)
	v_mfma_f32_32x32x16_bf16 v[50:65], v[166:169], v[162:165], v[50:65]
	ds_read_b128 v[162:165], v242 offset:47104
	s_waitcnt lgkmcnt(0)
	v_mfma_f32_32x32x16_bf16 v[50:65], v[162:165], v[158:161], v[50:65]
	ds_read_b128 v[158:161], v242 offset:48128
	s_waitcnt lgkmcnt(0)
	s_barrier
	s_waitcnt vmcnt(21)
	ds_write_b128 v241, v[98:101]
	s_waitcnt vmcnt(20)
	ds_write_b128 v241, v[102:105] offset:4096
	s_waitcnt vmcnt(19)
	ds_write_b128 v241, v[106:109] offset:8192
	s_waitcnt vmcnt(18)
	ds_write_b128 v241, v[110:113] offset:12288
	s_waitcnt vmcnt(17)
	ds_write_b128 v241, v[114:117] offset:16384
	s_waitcnt vmcnt(16)
	ds_write_b128 v241, v[118:121] offset:20480
	s_waitcnt vmcnt(15)
	ds_write_b128 v241, v[122:125] offset:24576
	s_waitcnt vmcnt(14)
	ds_write_b128 v241, v[126:129] offset:28672
	s_waitcnt vmcnt(13)
	ds_write_b128 v241, v[130:133] offset:32768
	s_waitcnt vmcnt(12)
	ds_write_b128 v241, v[134:137] offset:36864
	s_waitcnt vmcnt(11)
	ds_write_b128 v241, v[138:141] offset:40960
	s_waitcnt vmcnt(10)
	ds_write_b128 v241, v[142:145] offset:45056
	s_waitcnt vmcnt(9)
	ds_write_b128 v241, v[146:149] offset:49152
	s_waitcnt vmcnt(8)
	ds_write_b128 v241, v[150:153] offset:53248
	s_waitcnt lgkmcnt(0)
	s_barrier
; DI bf16_t f2bf(float x) { return (bf16_t)(pack2(x, 0.f) & 0xffffu); }
; DI int crow(int reg, int hh) { return (reg & 3) + 8 * (reg >> 2) + 4 * hh; }
; DI void phaseB2(const Params& p, int bh, char* smem, int n_begin, int n_end) {
;     ...
;     {
;       bf16_t* og = p.ob + (size_t)(b * SEQ + n * 64) * 512 + hd * 128 + v0 + r;
; #pragma unroll
;       for (int it = 0; it < 2; ++it)
; #pragma unroll
;         for (int e = 0; e < 16; ++e) og[(size_t)(it * 32 + crow(e, hh)) * 512] = f2bf(o[it][e]);
;     }
;   }
	global_store_short v[220:221], v0, off
	v_cvt_pk_bf16_f32 v0, v83, s0
	global_store_short v[220:221], v0, off offset:1024
	v_cvt_pk_bf16_f32 v0, v84, s0
	global_store_short v[220:221], v0, off offset:2048
	v_cvt_pk_bf16_f32 v0, v85, s0
	global_store_short v[220:221], v0, off offset:3072
	v_cvt_pk_bf16_f32 v0, v86, s0
	v_addc_co_u32_e32 v83, vcc, 0, v221, vcc
	global_store_short v[82:83], v0, off
	v_cvt_pk_bf16_f32 v0, v87, s0
	global_store_short v[82:83], v0, off offset:1024
	v_cvt_pk_bf16_f32 v0, v88, s0
	global_store_short v[82:83], v0, off offset:2048
	v_cvt_pk_bf16_f32 v0, v89, s0
	global_store_short v[82:83], v0, off offset:3072
	v_add_co_u32_e32 v82, vcc, s95, v220
	v_cvt_pk_bf16_f32 v0, v90, s0
	s_nop 0
	v_addc_co_u32_e32 v83, vcc, 0, v221, vcc
	global_store_short v[82:83], v0, off
	v_cvt_pk_bf16_f32 v0, v91, s0
	global_store_short v[82:83], v0, off offset:1024
	v_cvt_pk_bf16_f32 v0, v92, s0
	global_store_short v[82:83], v0, off offset:2048
	v_cvt_pk_bf16_f32 v0, v93, s0
	global_store_short v[82:83], v0, off offset:3072
	v_add_co_u32_e32 v82, vcc, s3, v220
	v_cvt_pk_bf16_f32 v0, v94, s0
	s_nop 0
	v_addc_co_u32_e32 v83, vcc, 0, v221, vcc
	global_store_short v[82:83], v0, off
	v_cvt_pk_bf16_f32 v0, v95, s0
	global_store_short v[82:83], v0, off offset:1024
	v_cvt_pk_bf16_f32 v0, v96, s0
	global_store_short v[82:83], v0, off offset:2048
	v_cvt_pk_bf16_f32 v0, v97, s0
	global_store_short v[82:83], v0, off offset:3072
	v_add_co_u32_e32 v82, vcc, s51, v220
	v_cvt_pk_bf16_f32 v0, v66, s0
	s_nop 0
	v_addc_co_u32_e32 v83, vcc, 0, v221, vcc
	global_store_short v[82:83], v0, off
	v_cvt_pk_bf16_f32 v0, v67, s0
	global_store_short v[82:83], v0, off offset:1024
	v_cvt_pk_bf16_f32 v0, v68, s0
	global_store_short v[82:83], v0, off offset:2048
	v_cvt_pk_bf16_f32 v0, v69, s0
	v_add_co_u32_e32 v66, vcc, s6, v220
	global_store_short v[82:83], v0, off offset:3072
	v_cvt_pk_bf16_f32 v0, v70, s0
	v_addc_co_u32_e32 v67, vcc, 0, v221, vcc
	global_store_short v[66:67], v0, off
	v_cvt_pk_bf16_f32 v0, v71, s0
	global_store_short v[66:67], v0, off offset:1024
	v_cvt_pk_bf16_f32 v0, v72, s0
	global_store_short v[66:67], v0, off offset:2048
	v_cvt_pk_bf16_f32 v0, v73, s0
	global_store_short v[66:67], v0, off offset:3072
	v_add_co_u32_e32 v66, vcc, s7, v220
	v_cvt_pk_bf16_f32 v0, v74, s0
	s_nop 0
	v_addc_co_u32_e32 v67, vcc, 0, v221, vcc
	s_waitcnt lgkmcnt(14)
	v_mfma_f32_32x32x16_bf16 v[50:65], v[158:161], v[154:157], v[50:65]
	global_store_short v[66:67], v0, off
	v_cvt_pk_bf16_f32 v0, v75, s0
	global_store_short v[66:67], v0, off offset:1024
	v_cvt_pk_bf16_f32 v0, v76, s0
	global_store_short v[66:67], v0, off offset:2048
	v_cvt_pk_bf16_f32 v0, v77, s0
	global_store_short v[66:67], v0, off offset:3072
	v_add_co_u32_e32 v66, vcc, s8, v220
	v_cvt_pk_bf16_f32 v0, v78, s0
	s_nop 0
	v_addc_co_u32_e32 v67, vcc, 0, v221, vcc
	global_store_short v[66:67], v0, off
	v_cvt_pk_bf16_f32 v0, v79, s0
	global_store_short v[66:67], v0, off offset:1024
	v_cvt_pk_bf16_f32 v0, v80, s0
	global_store_short v[66:67], v0, off offset:2048
	v_cvt_pk_bf16_f32 v0, v81, s0
	v_lshl_add_u64 v[220:221], v[220:221], 0, s[40:41]
	s_mov_b32 s0, s2
	global_store_short v[66:67], v0, off offset:3072
	s_cbranch_scc1 .LBB0_798
	s_setprio 0
	v_readlane_b32 s0, v253, 44
	v_readlane_b32 s1, v253, 45
	v_readlane_b32 s1, v254, 10
	s_add_i32 s11, s1, s0
	v_mov_b32_e32 v0, v230
	s_cmpk_gt_i32 s11, 0xfff
	s_waitcnt lgkmcnt(0)
	s_barrier
	s_cbranch_scc1 .LBB0_1236
; #define TIDX (tid_launder())
; DI void a1_select(const Params& p, const float* scrow, int t, size_t tokrow, int lane) {
;     ...
;     const unsigned long long lowmask = (1ull << lane) - 1ull;
;     const int nties = wave_sum6(__popc(active));
;     if (nties == need) {
;       const unsigned selb = above | active;
; #pragma unroll
;       for (int i = 0; i < 32; ++i) {
;         const unsigned long long sb = __ballot((selb >> i) & 1u);
;         if (lane == i) myword = sb;
;       }
;     } else
; #pragma unroll
;     for (int i = 0; i < 32; ++i) {
;       const bool tie = (active >> i) & 1u;
;       const unsigned long long tb = __ballot(tie);
;       const int pre = __popcll(tb & lowmask);
;       const bool sel = ((above >> i) & 1u) || (tie && (run + pre) < need);
;       run += __popcll(tb);
;       const unsigned long long sb = __ballot(sel);
;       if (lane == i) myword = sb;
; DI void phaseA1(const Params& p, int vblock, int nvblocks, int ubegin, int uend, char* smem) {
;     ...
;   const int tid = TIDX, lane = tid & 63, wid = tid >> 6, r = lane & 31, hh = lane >> 5;
; #pragma unroll 1
;   for (int u0 = ubegin + vblock; u0 < uend; u0 += nvblocks) {
;     const int u = 4095 - u0;
;     const int b = u >> 8, q0 = (u & 255) * 8;
;     const size_t tokb = (size_t)b * SEQ;
;     const int qa = ((r >> 2) & 1) * 2 + (r >> 4), ha = (r & 3) + 4 * ((r >> 3) & 1);
	v_and_b32_e32 v103, 63, v0
	v_cmp_eq_u32_e64 s[16:17], 13, v103
	v_and_b32_e32 v6, 60, v0
	v_cmp_eq_u32_e32 vcc, 4, v6
	v_writelane_b32 v254, s16, 10
	v_and_b32_e32 v6, 56, v0
	v_ashrrev_i32_e32 v98, 6, v0
	v_writelane_b32 v254, s17, 11
	v_cmp_eq_u32_e64 s[16:17], 14, v103
	v_cmp_eq_u32_e64 s[2:3], 8, v6
	v_and_b32_e32 v6, 48, v0
	v_writelane_b32 v254, s16, 12
	v_lshrrev_b32_e32 v2, 1, v0
	v_bfe_u32 v4, v0, 4, 1
	v_writelane_b32 v254, s17, 13
	v_cmp_eq_u32_e64 s[16:17], 15, v103
	s_or_b64 s[2:3], s[2:3], vcc
	v_cmp_eq_u32_e32 vcc, 16, v6
	v_writelane_b32 v254, s16, 14
	v_lshlrev_b32_e32 v6, 13, v98
	v_and_b32_e32 v3, 31, v0
	v_writelane_b32 v254, s17, 15
	v_cmp_eq_u32_e64 s[16:17], 16, v103
	v_bfe_u32 v5, v0, 5, 1
	v_and_or_b32 v116, v2, 2, v4
	v_writelane_b32 v254, s16, 16
	v_and_b32_e32 v4, 3, v0
	v_lshl_or_b32 v117, v103, 2, v6
	v_writelane_b32 v254, s17, 17
	v_cmp_eq_u32_e64 s[16:17], 17, v103
	v_lshlrev_b64 v[6:7], v0, -1
	v_lshlrev_b32_e32 v0, 4, v0
	v_writelane_b32 v254, s16, 18
	v_and_b32_e32 v0, 0x3f0, v0
	v_ashrrev_i32_e32 v99, 31, v98
	v_writelane_b32 v254, s17, 19
	v_cmp_eq_u32_e64 s[16:17], 18, v103
	s_or_b64 s[58:59], vcc, s[2:3]
	v_cmp_eq_u32_e64 s[2:3], 8, v103
	v_writelane_b32 v254, s16, 20
	v_and_or_b32 v2, v2, 4, v4
	v_not_b32_e32 v101, v7
	v_writelane_b32 v254, s17, 21
	v_cmp_eq_u32_e64 s[16:17], 19, v103
	v_not_b32_e32 v102, v6
	v_lshlrev_b64 v[6:7], 12, v[98:99]
	v_writelane_b32 v254, s16, 22
	v_lshlrev_b32_e32 v2, 6, v2
	v_lshlrev_b32_e32 v4, 3, v5
	v_writelane_b32 v254, s17, 23
	v_cmp_eq_u32_e64 s[16:17], 20, v103
	v_cmp_eq_u32_e64 s[12:13], 9, v103
	v_cmp_eq_u32_e64 s[36:37], 10, v103
	v_writelane_b32 v254, s16, 24
	v_cmp_eq_u32_e64 s[38:39], 11, v103
	v_cmp_eq_u32_e64 s[40:41], 12, v103
	v_writelane_b32 v254, s17, 25
	v_cmp_eq_u32_e64 s[16:17], 21, v103
	v_lshl_or_b32 v6, v103, 4, v6
	v_lshlrev_b32_e32 v100, 1, v5
	v_writelane_b32 v254, s16, 26
	v_cmp_eq_u32_e64 s[0:1], 0, v103
	v_cmp_eq_u32_e64 s[4:5], 1, v103
	v_writelane_b32 v254, s17, 27
	v_cmp_eq_u32_e64 s[16:17], 22, v103
	v_cmp_eq_u32_e64 s[6:7], 2, v103
	v_cmp_eq_u32_e64 s[8:9], 3, v103
	v_writelane_b32 v254, s16, 28
	v_cmp_eq_u32_e64 s[60:61], 4, v103
	v_cmp_eq_u32_e64 s[62:63], 5, v103
	v_writelane_b32 v254, s17, 29
	v_cmp_eq_u32_e64 s[16:17], 23, v103
	v_cmp_eq_u32_e64 s[64:65], 6, v103
	v_cmp_eq_u32_e64 s[66:67], 7, v103
	v_writelane_b32 v254, s16, 30
	v_cmp_eq_u32_e64 s[54:55], 27, v103
	v_cmp_eq_u32_e64 s[56:57], 28, v103
	v_writelane_b32 v254, s17, 31
	v_cmp_eq_u32_e64 s[16:17], 24, v103
	v_cmp_eq_u32_e64 s[90:91], 29, v103
	v_cmp_eq_u32_e64 s[34:35], 30, v103
	v_writelane_b32 v254, s16, 32
	v_cmp_eq_u32_e64 s[92:93], 31, v103
	v_cmp_gt_u32_e64 s[68:69], 32, v103
	v_writelane_b32 v254, s17, 33
	v_cmp_eq_u32_e64 s[16:17], 25, v103
	s_sub_i32 s10, 0xfff, s11
	v_lshlrev_b32_e32 v110, 1, v4
	v_writelane_b32 v254, s16, 34
	s_nop 1
	v_writelane_b32 v254, s17, 35
	v_cmp_eq_u32_e64 s[16:17], 26, v103
	s_nop 1
	v_writelane_b32 v254, s16, 36
	s_nop 1
	v_writelane_b32 v254, s17, 37
	v_readlane_b32 s16, v253, 11
	v_readlane_b32 s18, v253, 13
	v_readlane_b32 s19, v253, 14
	v_readlane_b32 s20, v253, 15
	v_readlane_b32 s21, v253, 16
	v_readlane_b32 s22, v253, 17
	v_readlane_b32 s23, v253, 18
	v_lshl_add_u64 v[104:105], s[18:19], 0, v[0:1]
	v_lshlrev_b32_e32 v0, 3, v103
	s_mov_b64 s[22:23], s[2:3]
	v_lshl_add_u64 v[106:107], s[20:21], 0, v[0:1]
	v_lshlrev_b32_e32 v0, 7, v98
	v_readlane_b32 s2, v253, 27
	v_readlane_b32 s17, v253, 12
	v_readlane_b32 s24, v253, 19
	v_readlane_b32 s25, v253, 20
	v_readlane_b32 s26, v253, 21
	v_readlane_b32 s27, v253, 22
	v_readlane_b32 s28, v253, 23
	v_readlane_b32 s29, v253, 24
	v_readlane_b32 s30, v253, 25
	v_readlane_b32 s31, v253, 26
	v_lshl_add_u32 v0, v5, 14, v0
	v_readlane_b32 s3, v253, 28
	s_mov_b64 s[30:31], s[40:41]
	s_mov_b64 s[28:29], s[38:39]
	s_mov_b64 s[26:27], s[36:37]
	s_mov_b64 s[24:25], s[12:13]
	v_lshl_or_b32 v118, v3, 2, v0
	v_lshl_add_u64 v[108:109], s[2:3], 0, v[6:7]
	v_lshlrev_b32_e32 v0, 1, v2
	v_readlane_b32 s17, v253, 46
	s_branch .LBB0_802

; #define MFMA32(a, b, c) __builtin_amdgcn_mfma_f32_32x32x16_bf16((a), (b), (c), 0, 0, 0)
; #define B2_STORE() do { uint4* l_ = (uint4*)L + tid; \
;     l_[0] = pw0; l_[256] = pw1; l_[512] = pw2; l_[768] = pw3; l_[1024] = pq0; l_[1280] = pq1; l_[1536] = pq2; l_[1792] = pq3; \
;     l_[2048] = pk0; l_[2304] = pk1; l_[2560] = pk2; l_[2816] = pk3; l_[3072] = pa0; l_[3328] = pa1; } while (0)
; DI void phaseB2(const Params& p, int bh, char* smem, int n_begin, int n_end) {
;     ...
;   __syncthreads();
;   B2_LOAD(n_begin);
;   B2_LOADU(n_begin);
;   B2_STORE();
;   __syncthreads();
; #pragma unroll 1
;   for (int n = n_begin; n < n_end; ++n) {
;     B2_LOAD(n + 1 < 32 ? n + 1 : n);
;     f32x16 vn[2], o[2];
; #pragma unroll
;     for (int it = 0; it < 2; ++it) {
;       f32x16 aw;
; #pragma unroll
;       for (int e = 0; e < 16; ++e) aw[e] = 0.f;
; #pragma unroll
;       for (int T = 0; T < 4; ++T)
; #pragma unroll
;         for (int s = 0; s < 2; ++s) aw = MFMA32(ld16(wg + (it * 4096 + (T * 2 + s) * 512) + lo8), pack8(S[T], s), aw);
; #pragma unroll
;       for (int g = 0; g < 4; ++g) {
;         const uint2 uu = it == 0 ? (g == 0 ? pu0 : g == 1 ? pu1 : g == 2 ? pu2 : pu3) : (g == 0 ? pu4 : g == 1 ? pu5 : g == 2 ? pu6 : pu7);
;         vn[it][4 * g + 0] = __uint_as_float(uu.x << 16) - aw[4 * g + 0];
;         vn[it][4 * g + 1] = __uint_as_float(uu.x & 0xffff0000u) - aw[4 * g + 1];
;         vn[it][4 * g + 2] = __uint_as_float(uu.y << 16) - aw[4 * g + 2];
;         vn[it][4 * g + 3] = __uint_as_float(uu.y & 0xffff0000u) - aw[4 * g + 3];
;       }
;     }
.LBB0_1238:
	s_setprio 3
	s_add_i32 s6, s2, 1
	s_cmp_lt_u32 s2, 31
	s_cselect_b32 s2, s6, s2
	s_add_i32 s2, s2, s1
	s_lshl_b32 s2, s2, 2
	s_or_b32 s2, s2, s5
	s_ashr_i32 s3, s2, 31
	s_lshl_b64 s[8:9], s[2:3], 13
	s_lshl_b64 s[2:3], s[2:3], 14
	v_lshl_add_u64 v[66:67], v[210:211], 0, s[2:3]
	v_add_co_u32_e32 v74, vcc, s80, v66
	global_load_dwordx4 v[98:101], v[66:67], off
	s_nop 0
	v_addc_co_u32_e32 v75, vcc, 0, v67, vcc
	v_add_co_u32_e32 v66, vcc, s81, v66
	v_lshl_add_u64 v[68:69], v[212:213], 0, s[2:3]
	s_nop 0
	v_addc_co_u32_e32 v67, vcc, 0, v67, vcc
	global_load_dwordx4 v[102:105], v[74:75], off offset:-4096
	global_load_dwordx4 v[106:109], v[74:75], off
	global_load_dwordx4 v[110:113], v[66:67], off
	global_load_dwordx4 v[114:117], v[68:69], off
	v_add_co_u32_e32 v66, vcc, s80, v68
	v_lshl_add_u64 v[70:71], v[214:215], 0, s[2:3]
	s_nop 0
	v_addc_co_u32_e32 v67, vcc, 0, v69, vcc
	global_load_dwordx4 v[118:121], v[66:67], off offset:-4096
	global_load_dwordx4 v[122:125], v[66:67], off
	v_add_co_u32_e32 v66, vcc, s81, v68
	v_lshl_add_u64 v[72:73], v[216:217], 0, s[8:9]
	s_nop 0
	v_addc_co_u32_e32 v67, vcc, 0, v69, vcc
	global_load_dwordx4 v[126:129], v[66:67], off
	global_load_dwordx4 v[130:133], v[70:71], off
	v_add_co_u32_e32 v66, vcc, s80, v70
	v_cvt_pk_bf16_f32 v198, v2, v3
	s_nop 0
	v_addc_co_u32_e32 v67, vcc, 0, v71, vcc
	global_load_dwordx4 v[134:137], v[66:67], off offset:-4096
	global_load_dwordx4 v[138:141], v[66:67], off
	v_add_co_u32_e32 v66, vcc, s81, v70
	v_cvt_pk_bf16_f32 v199, v4, v5
	s_nop 0
	v_addc_co_u32_e32 v67, vcc, 0, v71, vcc
	global_load_dwordx4 v[142:145], v[66:67], off
	global_load_dwordx4 v[146:149], v[72:73], off
	v_add_co_u32_e32 v66, vcc, s97, v72
	v_cvt_pk_bf16_f32 v200, v6, v7
	s_nop 0
	v_addc_co_u32_e32 v67, vcc, 0, v73, vcc
	global_load_dwordx4 v[150:153], v[66:67], off
	ds_read_b128 v[66:69], v242
	ds_read_b128 v[82:85], v242 offset:1024
	v_cvt_pk_bf16_f32 v201, v8, v9
	v_cvt_pk_bf16_f32 v194, v10, v11
	v_cvt_pk_bf16_f32 v195, v12, v13
	s_waitcnt lgkmcnt(1)
	v_mfma_f32_32x32x16_bf16 v[66:81], v[66:69], v[198:201], 0
	v_cvt_pk_bf16_f32 v196, v14, v15
	v_cvt_pk_bf16_f32 v197, v16, v17
	v_cvt_pk_bf16_f32 v190, v18, v19
	v_cvt_pk_bf16_f32 v191, v20, v21
	v_cvt_pk_bf16_f32 v192, v22, v23
	v_cvt_pk_bf16_f32 v193, v24, v25
	v_cvt_pk_bf16_f32 v186, v26, v27
	s_waitcnt lgkmcnt(0)
	v_mfma_f32_32x32x16_bf16 v[66:81], v[82:85], v[194:197], v[66:81]
	ds_read_b128 v[82:85], v242 offset:2048
	v_cvt_pk_bf16_f32 v187, v28, v29
	v_cvt_pk_bf16_f32 v188, v30, v31
	v_cvt_pk_bf16_f32 v189, v32, v33
	v_cvt_pk_bf16_f32 v182, v34, v35
	v_cvt_pk_bf16_f32 v183, v36, v37
	v_cvt_pk_bf16_f32 v184, v38, v39
	s_waitcnt lgkmcnt(0)
	v_mfma_f32_32x32x16_bf16 v[66:81], v[82:85], v[190:193], v[66:81]
	ds_read_b128 v[82:85], v242 offset:3072
	v_cvt_pk_bf16_f32 v185, v40, v41
	v_cvt_pk_bf16_f32 v178, v42, v43
	v_cvt_pk_bf16_f32 v179, v44, v45
	v_cvt_pk_bf16_f32 v180, v46, v47
	v_cvt_pk_bf16_f32 v181, v48, v49
	v_cvt_pk_bf16_f32 v174, v50, v51
	s_waitcnt lgkmcnt(0)
	v_mfma_f32_32x32x16_bf16 v[66:81], v[82:85], v[186:189], v[66:81]
	ds_read_b128 v[82:85], v242 offset:4096
	v_cvt_pk_bf16_f32 v175, v52, v53
	v_cvt_pk_bf16_f32 v176, v54, v55
	v_cvt_pk_bf16_f32 v177, v56, v57
	v_cvt_pk_bf16_f32 v166, v58, v59
	v_cvt_pk_bf16_f32 v167, v60, v61
	v_cvt_pk_bf16_f32 v168, v62, v63
	s_waitcnt lgkmcnt(0)
	v_mfma_f32_32x32x16_bf16 v[66:81], v[82:85], v[182:185], v[66:81]
	ds_read_b128 v[82:85], v242 offset:5120
	v_cvt_pk_bf16_f32 v169, v64, v65
	s_waitcnt vmcnt(21)
	v_lshlrev_b32_e32 v0, 16, v228
	s_cmp_lg_u32 s6, 32
	s_waitcnt lgkmcnt(0)
	v_mfma_f32_32x32x16_bf16 v[66:81], v[82:85], v[178:181], v[66:81]
	ds_read_b128 v[82:85], v242 offset:6144
	s_waitcnt lgkmcnt(0)
	v_mfma_f32_32x32x16_bf16 v[66:81], v[82:85], v[174:177], v[66:81]
	ds_read_b128 v[82:85], v242 offset:7168
	s_waitcnt lgkmcnt(0)
	v_mfma_f32_32x32x16_bf16 v[66:81], v[82:85], v[166:169], v[66:81]
	ds_read_b128 v[82:85], v242 offset:9216
	s_nop 10
	v_sub_f32_e32 v0, v0, v66
	v_and_b32_e32 v66, 0xffff0000, v228
	v_sub_f32_e32 v86, v66, v67
	v_lshlrev_b32_e32 v66, 16, v229
	v_sub_f32_e32 v87, v66, v68
	v_and_b32_e32 v66, 0xffff0000, v229
	v_sub_f32_e32 v88, v66, v69
	s_waitcnt vmcnt(20)
	v_lshlrev_b32_e32 v66, 16, v226
	v_sub_f32_e32 v89, v66, v70
	v_and_b32_e32 v66, 0xffff0000, v226
	v_sub_f32_e32 v90, v66, v71
	v_lshlrev_b32_e32 v66, 16, v227
	v_sub_f32_e32 v91, v66, v72
	v_and_b32_e32 v66, 0xffff0000, v227
	v_sub_f32_e32 v92, v66, v73
	s_waitcnt vmcnt(19)
	v_lshlrev_b32_e32 v66, 16, v224
	v_sub_f32_e32 v93, v66, v74
	v_and_b32_e32 v66, 0xffff0000, v224
	v_sub_f32_e32 v94, v66, v75
	v_lshlrev_b32_e32 v66, 16, v225
	v_sub_f32_e32 v95, v66, v76
	v_and_b32_e32 v66, 0xffff0000, v225
	v_sub_f32_e32 v96, v66, v77
	s_waitcnt vmcnt(18)
	v_lshlrev_b32_e32 v66, 16, v222
	v_sub_f32_e32 v97, v66, v78
	v_and_b32_e32 v66, 0xffff0000, v222
	v_sub_f32_e32 v154, v66, v79
	v_lshlrev_b32_e32 v66, 16, v223
	v_sub_f32_e32 v155, v66, v80
	v_and_b32_e32 v66, 0xffff0000, v223
	v_sub_f32_e32 v156, v66, v81
	ds_read_b128 v[66:69], v242 offset:8192
	s_waitcnt lgkmcnt(0)
	v_mfma_f32_32x32x16_bf16 v[66:81], v[66:69], v[198:201], 0
	v_cvt_pk_bf16_f32 v170, v0, v86
	v_cvt_pk_bf16_f32 v171, v87, v88
	v_cvt_pk_bf16_f32 v172, v89, v90
	v_cvt_pk_bf16_f32 v173, v91, v92
	v_cvt_pk_bf16_f32 v162, v93, v94
	v_cvt_pk_bf16_f32 v163, v95, v96
	v_cvt_pk_bf16_f32 v164, v97, v154
	v_mfma_f32_32x32x16_bf16 v[66:81], v[82:85], v[194:197], v[66:81]
	ds_read_b128 v[82:85], v242 offset:10240
	v_cvt_pk_bf16_f32 v165, v155, v156
	ds_bpermute_b32 v0, v243, v240
	v_add_u32_e32 v243, 4, v243
	s_waitcnt lgkmcnt(0)
; #define MFMA32(a, b, c) __builtin_amdgcn_mfma_f32_32x32x16_bf16((a), (b), (c), 0, 0, 0)
; DI void phaseB2(const Params& p, int bh, char* smem, int n_begin, int n_end) {
;     ...
;     for (int it = 0; it < 2; ++it) {
;       f32x16 aw;
; #pragma unroll
;       for (int e = 0; e < 16; ++e) aw[e] = 0.f;
; #pragma unroll
;       for (int T = 0; T < 4; ++T)
; #pragma unroll
;         for (int s = 0; s < 2; ++s) aw = MFMA32(ld16(wg + (it * 4096 + (T * 2 + s) * 512) + lo8), pack8(S[T], s), aw);
; #pragma unroll
;       for (int g = 0; g < 4; ++g) {
;         const uint2 uu = it == 0 ? (g == 0 ? pu0 : g == 1 ? pu1 : g == 2 ? pu2 : pu3) : (g == 0 ? pu4 : g == 1 ? pu5 : g == 2 ? pu6 : pu7);
;         vn[it][4 * g + 0] = __uint_as_float(uu.x << 16) - aw[4 * g + 0];
;         vn[it][4 * g + 1] = __uint_as_float(uu.x & 0xffff0000u) - aw[4 * g + 1];
;         vn[it][4 * g + 2] = __uint_as_float(uu.y << 16) - aw[4 * g + 2];
;         vn[it][4 * g + 3] = __uint_as_float(uu.y & 0xffff0000u) - aw[4 * g + 3];
;       }
;     }
;     B2_LOADU(n + 1 < 32 ? n + 1 : n);
;     bf16x8 Vb[2][2];
; #pragma unroll
;     for (int jt = 0; jt < 2; ++jt) { Vb[jt][0] = pack8(vn[jt], 0); Vb[jt][1] = pack8(vn[jt], 1); }
; #pragma unroll
;     for (int it = 0; it < 2; ++it) {
; #pragma unroll
;       for (int e = 0; e < 16; ++e) o[it][e] = 0.f;
; #pragma unroll
;       for (int T = 0; T < 4; ++T)
; #pragma unroll
;         for (int s = 0; s < 2; ++s) o[it] = MFMA32(ld16(qg + (it * 4096 + (T * 2 + s) * 512) + lo8), pack8(S[T], s), o[it]);
; #pragma unroll
;       for (int jt = 0; jt < 2; ++jt)
; #pragma unroll
;         for (int s = 0; s < 2; ++s)
;           o[it] = MFMA32(ld16(ag + (it * 2048 + (jt * 2 + s) * 512) + lo8), Vb[jt][s], o[it]);
;     }
;     const float egl = __shfl(eglv, n);
; #pragma unroll
;     for (int T = 0; T < 4; ++T) {
;       f32x16 acc;
; #pragma unroll
;       for (int e = 0; e < 16; ++e) acc[e] = S[T][e] * egl;
	v_pk_mul_f32 v[16:17], v[16:17], v[0:1] op_sel_hi:[1,0]
	v_mfma_f32_32x32x16_bf16 v[66:81], v[82:85], v[190:193], v[66:81]
	ds_read_b128 v[82:85], v242 offset:11264
	v_mul_f32_e64 v14, v14, v0
	v_mul_f32_e64 v15, v15, v0
	v_mul_f32_e64 v12, v12, v0
	v_mul_f32_e64 v13, v13, v0
	v_pk_mul_f32 v[10:11], v[10:11], v[0:1] op_sel_hi:[1,0]
	v_pk_mul_f32 v[8:9], v[8:9], v[0:1] op_sel_hi:[1,0]
	v_pk_mul_f32 v[6:7], v[6:7], v[0:1] op_sel_hi:[1,0]
	v_pk_mul_f32 v[4:5], v[4:5], v[0:1] op_sel_hi:[1,0]
	s_waitcnt lgkmcnt(0)
	v_mfma_f32_32x32x16_bf16 v[66:81], v[82:85], v[186:189], v[66:81]
	ds_read_b128 v[82:85], v242 offset:12288
	v_mul_f32_e64 v2, v2, v0
	v_mul_f32_e64 v3, v3, v0
	v_mul_f32_e64 v32, v32, v0
	v_mul_f32_e64 v33, v33, v0
	v_pk_mul_f32 v[30:31], v[30:31], v[0:1] op_sel_hi:[1,0]
	v_pk_mul_f32 v[28:29], v[28:29], v[0:1] op_sel_hi:[1,0]
	v_pk_mul_f32 v[26:27], v[26:27], v[0:1] op_sel_hi:[1,0]
	v_pk_mul_f32 v[24:25], v[24:25], v[0:1] op_sel_hi:[1,0]
	s_waitcnt lgkmcnt(0)
	v_mfma_f32_32x32x16_bf16 v[66:81], v[82:85], v[182:185], v[66:81]
	ds_read_b128 v[82:85], v242 offset:13312
	v_mul_f32_e64 v22, v22, v0
	v_mul_f32_e64 v23, v23, v0
	v_mul_f32_e64 v20, v20, v0
	v_mul_f32_e64 v21, v21, v0
	v_pk_mul_f32 v[18:19], v[18:19], v[0:1] op_sel_hi:[1,0]
	v_pk_mul_f32 v[48:49], v[48:49], v[0:1] op_sel_hi:[1,0]
	v_pk_mul_f32 v[46:47], v[46:47], v[0:1] op_sel_hi:[1,0]
	v_pk_mul_f32 v[44:45], v[44:45], v[0:1] op_sel_hi:[1,0]
	s_waitcnt lgkmcnt(0)
	v_mfma_f32_32x32x16_bf16 v[66:81], v[82:85], v[178:181], v[66:81]
	ds_read_b128 v[82:85], v242 offset:14336
	v_mul_f32_e64 v42, v42, v0
	v_mul_f32_e64 v43, v43, v0
	v_mul_f32_e64 v40, v40, v0
	v_mul_f32_e64 v41, v41, v0
	v_pk_mul_f32 v[38:39], v[38:39], v[0:1] op_sel_hi:[1,0]
	v_pk_mul_f32 v[36:37], v[36:37], v[0:1] op_sel_hi:[1,0]
	v_pk_mul_f32 v[34:35], v[34:35], v[0:1] op_sel_hi:[1,0]
	v_pk_mul_f32 v[64:65], v[64:65], v[0:1] op_sel_hi:[1,0]
	s_waitcnt lgkmcnt(0)
	v_mfma_f32_32x32x16_bf16 v[66:81], v[82:85], v[174:177], v[66:81]
	ds_read_b128 v[82:85], v242 offset:15360
	v_mul_f32_e64 v62, v62, v0
	v_mul_f32_e64 v63, v63, v0
	v_mul_f32_e64 v60, v60, v0
	v_mul_f32_e64 v61, v61, v0
	v_pk_mul_f32 v[58:59], v[58:59], v[0:1] op_sel_hi:[1,0]
	v_pk_mul_f32 v[56:57], v[56:57], v[0:1] op_sel_hi:[1,0]
	v_pk_mul_f32 v[54:55], v[54:55], v[0:1] op_sel_hi:[1,0]
	v_pk_mul_f32 v[52:53], v[52:53], v[0:1] op_sel_hi:[1,0]
	s_waitcnt lgkmcnt(0)
	v_mfma_f32_32x32x16_bf16 v[66:81], v[82:85], v[166:169], v[66:81]
	s_waitcnt vmcnt(17)
	v_lshlrev_b32_e32 v82, 16, v208
	v_and_b32_e32 v83, 0xffff0000, v208
	v_mul_f32_e64 v50, v50, v0
	v_mul_f32_e64 v51, v51, v0
	s_nop 6
	v_pk_add_f32 v[66:67], v[82:83], v[66:67] neg_lo:[0,1] neg_hi:[0,1]
	v_lshlrev_b32_e32 v82, 16, v209
	v_and_b32_e32 v83, 0xffff0000, v209
	v_pk_add_f32 v[68:69], v[82:83], v[68:69] neg_lo:[0,1] neg_hi:[0,1]
	s_waitcnt vmcnt(16)
	v_lshlrev_b32_e32 v82, 16, v206
	v_and_b32_e32 v83, 0xffff0000, v206
	v_pk_add_f32 v[70:71], v[82:83], v[70:71] neg_lo:[0,1] neg_hi:[0,1]
	v_lshlrev_b32_e32 v82, 16, v207
	v_and_b32_e32 v83, 0xffff0000, v207
	v_pk_add_f32 v[72:73], v[82:83], v[72:73] neg_lo:[0,1] neg_hi:[0,1]
	s_waitcnt vmcnt(15)
	v_lshlrev_b32_e32 v82, 16, v204
	v_and_b32_e32 v83, 0xffff0000, v204
	v_pk_add_f32 v[74:75], v[82:83], v[74:75] neg_lo:[0,1] neg_hi:[0,1]
	v_lshlrev_b32_e32 v82, 16, v205
	v_and_b32_e32 v83, 0xffff0000, v205
	v_pk_add_f32 v[76:77], v[82:83], v[76:77] neg_lo:[0,1] neg_hi:[0,1]
	s_waitcnt vmcnt(14)
	v_lshlrev_b32_e32 v82, 16, v202
	v_and_b32_e32 v83, 0xffff0000, v202
	v_pk_add_f32 v[78:79], v[82:83], v[78:79] neg_lo:[0,1] neg_hi:[0,1]
	v_lshlrev_b32_e32 v82, 16, v203
	v_and_b32_e32 v83, 0xffff0000, v203
	v_pk_add_f32 v[80:81], v[82:83], v[80:81] neg_lo:[0,1] neg_hi:[0,1]
	v_lshl_add_u64 v[82:83], v[218:219], 0, s[2:3]
	global_load_dwordx2 v[228:229], v[82:83], off
	global_load_dwordx2 v[226:227], v[82:83], off offset:512
	global_load_dwordx2 v[224:225], v[82:83], off offset:1024
	global_load_dwordx2 v[222:223], v[82:83], off offset:1536
	global_load_dwordx2 v[208:209], v[82:83], off offset:2048
	global_load_dwordx2 v[206:207], v[82:83], off offset:2560
	global_load_dwordx2 v[204:205], v[82:83], off offset:3072
	global_load_dwordx2 v[202:203], v[82:83], off offset:3584
	v_cvt_pk_bf16_f32 v158, v66, v67
	v_cvt_pk_bf16_f32 v159, v68, v69
	ds_read_b128 v[66:69], v242 offset:16384
	s_waitcnt lgkmcnt(0)
	v_mfma_f32_32x32x16_bf16 v[82:97], v[66:69], v[198:201], 0
	ds_read_b128 v[66:69], v242 offset:17408
	v_cvt_pk_bf16_f32 v160, v70, v71
	v_cvt_pk_bf16_f32 v161, v72, v73
	v_cvt_pk_bf16_f32 v154, v74, v75
	v_cvt_pk_bf16_f32 v155, v76, v77
	v_cvt_pk_bf16_f32 v156, v78, v79
	v_cvt_pk_bf16_f32 v157, v80, v81
	s_waitcnt lgkmcnt(0)
	v_mfma_f32_32x32x16_bf16 v[82:97], v[66:69], v[194:197], v[82:97]
	ds_read_b128 v[66:69], v242 offset:18432
	s_mov_b32 s2, s6
	s_waitcnt lgkmcnt(0)
	v_mfma_f32_32x32x16_bf16 v[82:97], v[66:69], v[190:193], v[82:97]
	ds_read_b128 v[66:69], v242 offset:19456
	s_waitcnt lgkmcnt(0)
	v_mfma_f32_32x32x16_bf16 v[82:97], v[66:69], v[186:189], v[82:97]
	ds_read_b128 v[66:69], v242 offset:20480
	s_waitcnt lgkmcnt(0)
	v_mfma_f32_32x32x16_bf16 v[82:97], v[66:69], v[182:185], v[82:97]
	ds_read_b128 v[66:69], v242 offset:21504
	s_waitcnt lgkmcnt(0)
	v_mfma_f32_32x32x16_bf16 v[82:97], v[66:69], v[178:181], v[82:97]
	ds_read_b128 v[66:69], v242 offset:22528
	s_waitcnt lgkmcnt(0)
	v_mfma_f32_32x32x16_bf16 v[82:97], v[66:69], v[174:177], v[82:97]
	ds_read_b128 v[66:69], v242 offset:23552
	s_waitcnt lgkmcnt(0)
	v_mfma_f32_32x32x16_bf16 v[82:97], v[66:69], v[166:169], v[82:97]
	ds_read_b128 v[66:69], v242 offset:49152
	s_waitcnt lgkmcnt(0)
; #define MFMA32(a, b, c) __builtin_amdgcn_mfma_f32_32x32x16_bf16((a), (b), (c), 0, 0, 0)
; DI void phaseB2(const Params& p, int bh, char* smem, int n_begin, int n_end) {
;     ...
; #pragma unroll
;     for (int it = 0; it < 2; ++it) {
; #pragma unroll
;       for (int e = 0; e < 16; ++e) o[it][e] = 0.f;
; #pragma unroll
;       for (int T = 0; T < 4; ++T)
; #pragma unroll
;         for (int s = 0; s < 2; ++s) o[it] = MFMA32(ld16(qg + (it * 4096 + (T * 2 + s) * 512) + lo8), pack8(S[T], s), o[it]);
; #pragma unroll
;       for (int jt = 0; jt < 2; ++jt)
; #pragma unroll
;         for (int s = 0; s < 2; ++s)
;           o[it] = MFMA32(ld16(ag + (it * 2048 + (jt * 2 + s) * 512) + lo8), Vb[jt][s], o[it]);
;     }
;     const float egl = __shfl(eglv, n);
; #pragma unroll
;     for (int T = 0; T < 4; ++T) {
;       f32x16 acc;
; #pragma unroll
;       for (int e = 0; e < 16; ++e) acc[e] = S[T][e] * egl;
; #pragma unroll
;       for (int jt = 0; jt < 2; ++jt)
; #pragma unroll
;         for (int s = 0; s < 2; ++s)
;           acc = MFMA32(ld16(kg + (T * 2048 + (jt * 2 + s) * 512) + lo8), Vb[jt][s], acc);
	v_mfma_f32_32x32x16_bf16 v[82:97], v[66:69], v[170:173], v[82:97]
	ds_read_b128 v[66:69], v242 offset:50176
	s_waitcnt lgkmcnt(0)
	v_mfma_f32_32x32x16_bf16 v[82:97], v[66:69], v[162:165], v[82:97]
	ds_read_b128 v[66:69], v242 offset:51200
	s_waitcnt lgkmcnt(0)
	v_mfma_f32_32x32x16_bf16 v[82:97], v[66:69], v[158:161], v[82:97]
	ds_read_b128 v[66:69], v242 offset:52224
	s_waitcnt lgkmcnt(0)
	v_mfma_f32_32x32x16_bf16 v[82:97], v[66:69], v[154:157], v[82:97]
	ds_read_b128 v[66:69], v242 offset:24576
	s_waitcnt lgkmcnt(0)
	v_mfma_f32_32x32x16_bf16 v[66:81], v[66:69], v[198:201], 0
	ds_read_b128 v[198:201], v242 offset:25600
	s_nop 7
	v_cvt_pk_bf16_f32 v0, v82, s0
	v_add_co_u32_e32 v82, vcc, s80, v220
	s_waitcnt lgkmcnt(0)
	v_mfma_f32_32x32x16_bf16 v[66:81], v[198:201], v[194:197], v[66:81]
	ds_read_b128 v[194:197], v242 offset:26624
	s_waitcnt lgkmcnt(0)
	v_mfma_f32_32x32x16_bf16 v[66:81], v[194:197], v[190:193], v[66:81]
	ds_read_b128 v[190:193], v242 offset:27648
	s_waitcnt lgkmcnt(0)
	v_mfma_f32_32x32x16_bf16 v[66:81], v[190:193], v[186:189], v[66:81]
	ds_read_b128 v[186:189], v242 offset:28672
	s_waitcnt lgkmcnt(0)
	v_mfma_f32_32x32x16_bf16 v[66:81], v[186:189], v[182:185], v[66:81]
	ds_read_b128 v[182:185], v242 offset:29696
	s_waitcnt lgkmcnt(0)
	v_mfma_f32_32x32x16_bf16 v[66:81], v[182:185], v[178:181], v[66:81]
	ds_read_b128 v[178:181], v242 offset:30720
	s_waitcnt lgkmcnt(0)
	v_mfma_f32_32x32x16_bf16 v[66:81], v[178:181], v[174:177], v[66:81]
	ds_read_b128 v[174:177], v242 offset:31744
	s_waitcnt lgkmcnt(0)
	v_mfma_f32_32x32x16_bf16 v[66:81], v[174:177], v[166:169], v[66:81]
	ds_read_b128 v[166:169], v242 offset:53248
	s_waitcnt lgkmcnt(0)
	v_mfma_f32_32x32x16_bf16 v[66:81], v[166:169], v[170:173], v[66:81]
	ds_read_b128 v[166:169], v242 offset:54272
	s_waitcnt lgkmcnt(0)
	v_mfma_f32_32x32x16_bf16 v[66:81], v[166:169], v[162:165], v[66:81]
	ds_read_b128 v[166:169], v242 offset:55296
	s_waitcnt lgkmcnt(0)
	v_mfma_f32_32x32x16_bf16 v[66:81], v[166:169], v[158:161], v[66:81]
	ds_read_b128 v[166:169], v242 offset:56320
	s_waitcnt lgkmcnt(0)
	v_mfma_f32_32x32x16_bf16 v[66:81], v[166:169], v[154:157], v[66:81]
	ds_read_b128 v[166:169], v242 offset:32768
	s_waitcnt lgkmcnt(0)
	v_mfma_f32_32x32x16_bf16 v[2:17], v[166:169], v[170:173], v[2:17]
	ds_read_b128 v[166:169], v242 offset:33792
	s_waitcnt lgkmcnt(0)
	v_mfma_f32_32x32x16_bf16 v[2:17], v[166:169], v[162:165], v[2:17]
	ds_read_b128 v[166:169], v242 offset:34816
	s_waitcnt lgkmcnt(0)
	v_mfma_f32_32x32x16_bf16 v[2:17], v[166:169], v[158:161], v[2:17]
	ds_read_b128 v[166:169], v242 offset:35840
	s_waitcnt lgkmcnt(0)
	v_mfma_f32_32x32x16_bf16 v[2:17], v[166:169], v[154:157], v[2:17]
	ds_read_b128 v[166:169], v242 offset:36864
	s_waitcnt lgkmcnt(0)
	v_mfma_f32_32x32x16_bf16 v[18:33], v[166:169], v[170:173], v[18:33]
	ds_read_b128 v[166:169], v242 offset:37888
	s_waitcnt lgkmcnt(0)
	v_mfma_f32_32x32x16_bf16 v[18:33], v[166:169], v[162:165], v[18:33]
	ds_read_b128 v[166:169], v242 offset:38912
	s_waitcnt lgkmcnt(0)
	v_mfma_f32_32x32x16_bf16 v[18:33], v[166:169], v[158:161], v[18:33]
	ds_read_b128 v[166:169], v242 offset:39936
	s_waitcnt lgkmcnt(0)
	v_mfma_f32_32x32x16_bf16 v[18:33], v[166:169], v[154:157], v[18:33]
	ds_read_b128 v[166:169], v242 offset:40960
	s_waitcnt lgkmcnt(0)
	v_mfma_f32_32x32x16_bf16 v[34:49], v[166:169], v[170:173], v[34:49]
	ds_read_b128 v[166:169], v242 offset:41984
	s_waitcnt lgkmcnt(0)
	v_mfma_f32_32x32x16_bf16 v[34:49], v[166:169], v[162:165], v[34:49]
	ds_read_b128 v[166:169], v242 offset:43008
	s_waitcnt lgkmcnt(0)
	v_mfma_f32_32x32x16_bf16 v[34:49], v[166:169], v[158:161], v[34:49]
	ds_read_b128 v[166:169], v242 offset:44032
	s_waitcnt lgkmcnt(0)
	v_mfma_f32_32x32x16_bf16 v[34:49], v[166:169], v[154:157], v[34:49]
	ds_read_b128 v[166:169], v242 offset:45056
	s_waitcnt lgkmcnt(0)
	v_mfma_f32_32x32x16_bf16 v[50:65], v[166:169], v[170:173], v[50:65]
	ds_read_b128 v[166:169], v242 offset:46080
	s_waitcnt lgkmcnt(0)
	v_mfma_f32_32x32x16_bf16 v[50:65], v[166:169], v[162:165], v[50:65]
	ds_read_b128 v[162:165], v242 offset:47104
	s_waitcnt lgkmcnt(0)
	v_mfma_f32_32x32x16_bf16 v[50:65], v[162:165], v[158:161], v[50:65]
	ds_read_b128 v[158:161], v242 offset:48128
	s_waitcnt lgkmcnt(0)
	s_barrier
; DI bf16_t f2bf(float x) { return (bf16_t)(pack2(x, 0.f) & 0xffffu); }
; DI int crow(int reg, int hh) { return (reg & 3) + 8 * (reg >> 2) + 4 * hh; }
; #define B2_STORE() do { uint4* l_ = (uint4*)L + tid; \
;     l_[0] = pw0; l_[256] = pw1; l_[512] = pw2; l_[768] = pw3; l_[1024] = pq0; l_[1280] = pq1; l_[1536] = pq2; l_[1792] = pq3; \
;     l_[2048] = pk0; l_[2304] = pk1; l_[2560] = pk2; l_[2816] = pk3; l_[3072] = pa0; l_[3328] = pa1; } while (0)
; DI void phaseB2(const Params& p, int bh, char* smem, int n_begin, int n_end) {
;     ...
;     asm volatile("s_waitcnt lgkmcnt(0)\n\ts_barrier" ::: "memory");
;     B2_STORE();
;     asm volatile("s_waitcnt lgkmcnt(0)\n\ts_barrier" ::: "memory");
;     {
;       bf16_t* og = p.ob + (size_t)(b * SEQ + n * 64) * 512 + hd * 128 + v0 + r;
; #pragma unroll
;       for (int it = 0; it < 2; ++it)
; #pragma unroll
;         for (int e = 0; e < 16; ++e) og[(size_t)(it * 32 + crow(e, hh)) * 512] = f2bf(o[it][e]);
;     }
;   }
	s_waitcnt vmcnt(21)
	ds_write_b128 v241, v[98:101]
	s_waitcnt vmcnt(20)
	ds_write_b128 v241, v[102:105] offset:4096
	s_waitcnt vmcnt(19)
	ds_write_b128 v241, v[106:109] offset:8192
	s_waitcnt vmcnt(18)
	ds_write_b128 v241, v[110:113] offset:12288
	s_waitcnt vmcnt(17)
	ds_write_b128 v241, v[114:117] offset:16384
	s_waitcnt vmcnt(16)
	ds_write_b128 v241, v[118:121] offset:20480
	s_waitcnt vmcnt(15)
	ds_write_b128 v241, v[122:125] offset:24576
	s_waitcnt vmcnt(14)
	ds_write_b128 v241, v[126:129] offset:28672
	s_waitcnt vmcnt(13)
	ds_write_b128 v241, v[130:133] offset:32768
	s_waitcnt vmcnt(12)
	ds_write_b128 v241, v[134:137] offset:36864
	s_waitcnt vmcnt(11)
	ds_write_b128 v241, v[138:141] offset:40960
	s_waitcnt vmcnt(10)
	ds_write_b128 v241, v[142:145] offset:45056
	s_waitcnt vmcnt(9)
	ds_write_b128 v241, v[146:149] offset:49152
	s_waitcnt vmcnt(8)
	ds_write_b128 v241, v[150:153] offset:53248
	s_waitcnt lgkmcnt(0)
	s_barrier
	global_store_short v[220:221], v0, off
	v_cvt_pk_bf16_f32 v0, v83, s0
	global_store_short v[220:221], v0, off offset:1024
	v_cvt_pk_bf16_f32 v0, v84, s0
	global_store_short v[220:221], v0, off offset:2048
	v_cvt_pk_bf16_f32 v0, v85, s0
	global_store_short v[220:221], v0, off offset:3072
	v_cvt_pk_bf16_f32 v0, v86, s0
	v_addc_co_u32_e32 v83, vcc, 0, v221, vcc
	global_store_short v[82:83], v0, off
	v_cvt_pk_bf16_f32 v0, v87, s0
	global_store_short v[82:83], v0, off offset:1024
	v_cvt_pk_bf16_f32 v0, v88, s0
	global_store_short v[82:83], v0, off offset:2048
	v_cvt_pk_bf16_f32 v0, v89, s0
	global_store_short v[82:83], v0, off offset:3072
	v_add_co_u32_e32 v82, vcc, s95, v220
	v_cvt_pk_bf16_f32 v0, v90, s0
	s_nop 0
	v_addc_co_u32_e32 v83, vcc, 0, v221, vcc
	global_store_short v[82:83], v0, off
	v_cvt_pk_bf16_f32 v0, v91, s0
	global_store_short v[82:83], v0, off offset:1024
	v_cvt_pk_bf16_f32 v0, v92, s0
	global_store_short v[82:83], v0, off offset:2048
	v_cvt_pk_bf16_f32 v0, v93, s0
	global_store_short v[82:83], v0, off offset:3072
	v_add_co_u32_e32 v82, vcc, s7, v220
	v_cvt_pk_bf16_f32 v0, v94, s0
	s_nop 0
	v_addc_co_u32_e32 v83, vcc, 0, v221, vcc
	global_store_short v[82:83], v0, off
	v_cvt_pk_bf16_f32 v0, v95, s0
	global_store_short v[82:83], v0, off offset:1024
	v_cvt_pk_bf16_f32 v0, v96, s0
	global_store_short v[82:83], v0, off offset:2048
	v_cvt_pk_bf16_f32 v0, v97, s0
	global_store_short v[82:83], v0, off offset:3072
	v_add_co_u32_e32 v82, vcc, s51, v220
	v_cvt_pk_bf16_f32 v0, v66, s0
	s_nop 0
	v_addc_co_u32_e32 v83, vcc, 0, v221, vcc
	global_store_short v[82:83], v0, off
	v_cvt_pk_bf16_f32 v0, v67, s0
	global_store_short v[82:83], v0, off offset:1024
	v_cvt_pk_bf16_f32 v0, v68, s0
	global_store_short v[82:83], v0, off offset:2048
	v_cvt_pk_bf16_f32 v0, v69, s0
	v_add_co_u32_e32 v66, vcc, s10, v220
	global_store_short v[82:83], v0, off offset:3072
	v_cvt_pk_bf16_f32 v0, v70, s0
	v_addc_co_u32_e32 v67, vcc, 0, v221, vcc
	global_store_short v[66:67], v0, off
	v_cvt_pk_bf16_f32 v0, v71, s0
	global_store_short v[66:67], v0, off offset:1024
	v_cvt_pk_bf16_f32 v0, v72, s0
	global_store_short v[66:67], v0, off offset:2048
	v_cvt_pk_bf16_f32 v0, v73, s0
	global_store_short v[66:67], v0, off offset:3072
	v_add_co_u32_e32 v66, vcc, s11, v220
	v_cvt_pk_bf16_f32 v0, v74, s0
	s_nop 0
	v_addc_co_u32_e32 v67, vcc, 0, v221, vcc
	s_waitcnt lgkmcnt(14)
	v_mfma_f32_32x32x16_bf16 v[50:65], v[158:161], v[154:157], v[50:65]
	global_store_short v[66:67], v0, off
	v_cvt_pk_bf16_f32 v0, v75, s0
	global_store_short v[66:67], v0, off offset:1024
	v_cvt_pk_bf16_f32 v0, v76, s0
	global_store_short v[66:67], v0, off offset:2048
	v_cvt_pk_bf16_f32 v0, v77, s0
	global_store_short v[66:67], v0, off offset:3072
	v_add_co_u32_e32 v66, vcc, s12, v220
	v_cvt_pk_bf16_f32 v0, v78, s0
	s_nop 0
	v_addc_co_u32_e32 v67, vcc, 0, v221, vcc
	global_store_short v[66:67], v0, off
	v_cvt_pk_bf16_f32 v0, v79, s0
	global_store_short v[66:67], v0, off offset:1024
	v_cvt_pk_bf16_f32 v0, v80, s0
	global_store_short v[66:67], v0, off offset:2048
	v_cvt_pk_bf16_f32 v0, v81, s0
	v_lshl_add_u64 v[220:221], v[220:221], 0, s[40:41]
	global_store_short v[66:67], v0, off offset:3072
	s_cbranch_scc1 .LBB0_1238
	s_setprio 0
	v_readlane_b32 s1, v253, 56
	s_add_i32 s0, s0, s1
	s_add_i32 s4, s4, s1
	s_cmp_gt_i32 s0, 63
	s_waitcnt lgkmcnt(0)
	s_barrier
	s_cbranch_scc0 .LBB0_1237

; #define MFMA32(a, b, c) __builtin_amdgcn_mfma_f32_32x32x16_bf16((a), (b), (c), 0, 0, 0)
; #define B2_STORE() do { uint4* l_ = (uint4*)L + tid; \
;     l_[0] = pw0; l_[256] = pw1; l_[512] = pw2; l_[768] = pw3; l_[1024] = pq0; l_[1280] = pq1; l_[1536] = pq2; l_[1792] = pq3; \
;     l_[2048] = pk0; l_[2304] = pk1; l_[2560] = pk2; l_[2816] = pk3; l_[3072] = pa0; l_[3328] = pa1; } while (0)
; DI void phaseB2(const Params& p, int bh, char* smem, int n_begin, int n_end) {
;     ...
;   __syncthreads();
;   B2_LOAD(n_begin);
;   B2_LOADU(n_begin);
;   B2_STORE();
;   __syncthreads();
; #pragma unroll 1
;   for (int n = n_begin; n < n_end; ++n) {
;     B2_LOAD(n + 1 < 32 ? n + 1 : n);
;     f32x16 vn[2], o[2];
; #pragma unroll
;     for (int it = 0; it < 2; ++it) {
;       f32x16 aw;
; #pragma unroll
;       for (int e = 0; e < 16; ++e) aw[e] = 0.f;
; #pragma unroll
;       for (int T = 0; T < 4; ++T)
; #pragma unroll
;         for (int s = 0; s < 2; ++s) aw = MFMA32(ld16(wg + (it * 4096 + (T * 2 + s) * 512) + lo8), pack8(S[T], s), aw);
; #pragma unroll
;       for (int g = 0; g < 4; ++g) {
;         const uint2 uu = it == 0 ? (g == 0 ? pu0 : g == 1 ? pu1 : g == 2 ? pu2 : pu3) : (g == 0 ? pu4 : g == 1 ? pu5 : g == 2 ? pu6 : pu7);
;         vn[it][4 * g + 0] = __uint_as_float(uu.x << 16) - aw[4 * g + 0];
;         vn[it][4 * g + 1] = __uint_as_float(uu.x & 0xffff0000u) - aw[4 * g + 1];
;         vn[it][4 * g + 2] = __uint_as_float(uu.y << 16) - aw[4 * g + 2];
;         vn[it][4 * g + 3] = __uint_as_float(uu.y & 0xffff0000u) - aw[4 * g + 3];
;       }
;     }
.LBB0_1757:
	s_setprio 3
	s_ashr_i32 s3, s2, 31
	s_lshl_b64 s[4:5], s[2:3], 14
	v_lshl_add_u64 v[66:67], v[208:209], 0, s[4:5]
	v_add_co_u32_e32 v74, vcc, s80, v66
	global_load_dwordx4 v[98:101], v[66:67], off
	s_nop 0
	v_addc_co_u32_e32 v75, vcc, 0, v67, vcc
	v_add_co_u32_e32 v66, vcc, s81, v66
	v_lshl_add_u64 v[68:69], v[210:211], 0, s[4:5]
	s_nop 0
	v_addc_co_u32_e32 v67, vcc, 0, v67, vcc
	global_load_dwordx4 v[102:105], v[74:75], off offset:-4096
	global_load_dwordx4 v[106:109], v[74:75], off
	global_load_dwordx4 v[110:113], v[66:67], off
	global_load_dwordx4 v[114:117], v[68:69], off
	v_add_co_u32_e32 v66, vcc, s80, v68
	v_lshl_add_u64 v[70:71], v[212:213], 0, s[4:5]
	s_nop 0
	v_addc_co_u32_e32 v67, vcc, 0, v69, vcc
	global_load_dwordx4 v[118:121], v[66:67], off offset:-4096
	global_load_dwordx4 v[122:125], v[66:67], off
	v_add_co_u32_e32 v66, vcc, s81, v68
	s_lshl_b64 s[6:7], s[2:3], 13
	s_nop 0
	v_addc_co_u32_e32 v67, vcc, 0, v69, vcc
	global_load_dwordx4 v[126:129], v[66:67], off
	global_load_dwordx4 v[130:133], v[70:71], off
	v_add_co_u32_e32 v66, vcc, s80, v70
	v_lshl_add_u64 v[72:73], v[214:215], 0, s[6:7]
	s_nop 0
	v_addc_co_u32_e32 v67, vcc, 0, v71, vcc
	global_load_dwordx4 v[134:137], v[66:67], off offset:-4096
	global_load_dwordx4 v[138:141], v[66:67], off
	v_add_co_u32_e32 v66, vcc, s81, v70
	v_cvt_pk_bf16_f32 v82, v50, v51
	s_nop 0
	v_addc_co_u32_e32 v67, vcc, 0, v71, vcc
	global_load_dwordx4 v[142:145], v[66:67], off
	global_load_dwordx4 v[146:149], v[72:73], off
	v_add_co_u32_e32 v66, vcc, s97, v72
	v_cvt_pk_bf16_f32 v83, v52, v53
	s_nop 0
	v_addc_co_u32_e32 v67, vcc, 0, v73, vcc
	global_load_dwordx4 v[150:153], v[66:67], off
	ds_read_b128 v[66:69], v240
	ds_read_b128 v[86:89], v240 offset:1024
	v_cvt_pk_bf16_f32 v84, v54, v55
	v_cvt_pk_bf16_f32 v85, v56, v57
	v_cvt_pk_bf16_f32 v194, v58, v59
	v_cvt_pk_bf16_f32 v195, v60, v61
	s_waitcnt lgkmcnt(1)
	v_mfma_f32_32x32x16_bf16 v[66:81], v[66:69], v[82:85], 0
	v_cvt_pk_bf16_f32 v196, v62, v63
	v_cvt_pk_bf16_f32 v197, v64, v65
	v_cvt_pk_bf16_f32 v190, v34, v35
	v_cvt_pk_bf16_f32 v191, v36, v37
	v_cvt_pk_bf16_f32 v192, v38, v39
	v_cvt_pk_bf16_f32 v193, v40, v41
	v_cvt_pk_bf16_f32 v186, v42, v43
	s_waitcnt lgkmcnt(0)
	v_mfma_f32_32x32x16_bf16 v[66:81], v[86:89], v[194:197], v[66:81]
	ds_read_b128 v[86:89], v240 offset:2048
	v_cvt_pk_bf16_f32 v187, v44, v45
	v_cvt_pk_bf16_f32 v188, v46, v47
	v_cvt_pk_bf16_f32 v189, v48, v49
	v_cvt_pk_bf16_f32 v182, v18, v19
	v_cvt_pk_bf16_f32 v183, v20, v21
	v_cvt_pk_bf16_f32 v184, v22, v23
	s_waitcnt lgkmcnt(0)
	v_mfma_f32_32x32x16_bf16 v[66:81], v[86:89], v[190:193], v[66:81]
	ds_read_b128 v[86:89], v240 offset:3072
	v_cvt_pk_bf16_f32 v185, v24, v25
	v_cvt_pk_bf16_f32 v178, v26, v27
	v_cvt_pk_bf16_f32 v179, v28, v29
	v_cvt_pk_bf16_f32 v180, v30, v31
	v_cvt_pk_bf16_f32 v181, v32, v33
	v_cvt_pk_bf16_f32 v174, v2, v3
	s_waitcnt lgkmcnt(0)
	v_mfma_f32_32x32x16_bf16 v[66:81], v[86:89], v[186:189], v[66:81]
	ds_read_b128 v[86:89], v240 offset:4096
	v_cvt_pk_bf16_f32 v175, v4, v5
	v_cvt_pk_bf16_f32 v176, v6, v7
	v_cvt_pk_bf16_f32 v177, v8, v9
	v_cvt_pk_bf16_f32 v170, v10, v11
	v_cvt_pk_bf16_f32 v171, v12, v13
	v_cvt_pk_bf16_f32 v172, v14, v15
	s_waitcnt lgkmcnt(0)
	v_mfma_f32_32x32x16_bf16 v[66:81], v[86:89], v[182:185], v[66:81]
	ds_read_b128 v[86:89], v240 offset:5120
	v_cvt_pk_bf16_f32 v173, v16, v17
	s_waitcnt vmcnt(21)
	v_lshlrev_b32_e32 v0, 16, v226
	s_waitcnt lgkmcnt(0)
	v_mfma_f32_32x32x16_bf16 v[66:81], v[86:89], v[178:181], v[66:81]
	ds_read_b128 v[86:89], v240 offset:6144
	s_waitcnt lgkmcnt(0)
	v_mfma_f32_32x32x16_bf16 v[66:81], v[86:89], v[174:177], v[66:81]
	ds_read_b128 v[86:89], v240 offset:7168
	s_waitcnt lgkmcnt(0)
	v_mfma_f32_32x32x16_bf16 v[66:81], v[86:89], v[170:173], v[66:81]
	ds_read_b128 v[86:89], v240 offset:9216
	s_nop 10
	v_sub_f32_e32 v0, v0, v66
	v_and_b32_e32 v66, 0xffff0000, v226
	v_sub_f32_e32 v90, v66, v67
	v_lshlrev_b32_e32 v66, 16, v227
	v_sub_f32_e32 v91, v66, v68
	v_and_b32_e32 v66, 0xffff0000, v227
	v_sub_f32_e32 v92, v66, v69
	s_waitcnt vmcnt(20)
	v_lshlrev_b32_e32 v66, 16, v224
	v_sub_f32_e32 v93, v66, v70
	v_and_b32_e32 v66, 0xffff0000, v224
	v_sub_f32_e32 v94, v66, v71
	v_lshlrev_b32_e32 v66, 16, v225
	v_sub_f32_e32 v95, v66, v72
	v_and_b32_e32 v66, 0xffff0000, v225
	v_sub_f32_e32 v96, v66, v73
	s_waitcnt vmcnt(19)
	v_lshlrev_b32_e32 v66, 16, v222
	v_sub_f32_e32 v97, v66, v74
	v_and_b32_e32 v66, 0xffff0000, v222
	v_sub_f32_e32 v154, v66, v75
	v_lshlrev_b32_e32 v66, 16, v223
	v_sub_f32_e32 v155, v66, v76
	v_and_b32_e32 v66, 0xffff0000, v223
	v_sub_f32_e32 v156, v66, v77
	s_waitcnt vmcnt(18)
	v_lshlrev_b32_e32 v66, 16, v220
	v_sub_f32_e32 v157, v66, v78
	v_and_b32_e32 v66, 0xffff0000, v220
	v_sub_f32_e32 v158, v66, v79
	v_lshlrev_b32_e32 v66, 16, v221
	v_sub_f32_e32 v159, v66, v80
	v_and_b32_e32 v66, 0xffff0000, v221
	v_sub_f32_e32 v160, v66, v81
	ds_read_b128 v[66:69], v240 offset:8192
	s_waitcnt lgkmcnt(0)
	v_mfma_f32_32x32x16_bf16 v[66:81], v[66:69], v[82:85], 0
	v_cvt_pk_bf16_f32 v164, v157, v158
	v_cvt_pk_bf16_f32 v165, v159, v160
	v_cvt_pk_bf16_f32 v162, v97, v154
	v_cvt_pk_bf16_f32 v163, v155, v156
	v_cvt_pk_bf16_f32 v166, v0, v90
	v_cvt_pk_bf16_f32 v167, v91, v92
	v_cvt_pk_bf16_f32 v168, v93, v94
	v_mfma_f32_32x32x16_bf16 v[66:81], v[86:89], v[194:197], v[66:81]
	ds_read_b128 v[86:89], v240 offset:10240
	v_cvt_pk_bf16_f32 v169, v95, v96
	ds_bpermute_b32 v0, v241, v228
	v_add_u32_e32 v241, 4, v241
	s_waitcnt lgkmcnt(0)
; #define MFMA32(a, b, c) __builtin_amdgcn_mfma_f32_32x32x16_bf16((a), (b), (c), 0, 0, 0)
; DI void phaseB2(const Params& p, int bh, char* smem, int n_begin, int n_end) {
;     ...
;         for (int s = 0; s < 2; ++s) aw = MFMA32(ld16(wg + (it * 4096 + (T * 2 + s) * 512) + lo8), pack8(S[T], s), aw);
; #pragma unroll
;       for (int g = 0; g < 4; ++g) {
;         const uint2 uu = it == 0 ? (g == 0 ? pu0 : g == 1 ? pu1 : g == 2 ? pu2 : pu3) : (g == 0 ? pu4 : g == 1 ? pu5 : g == 2 ? pu6 : pu7);
;         vn[it][4 * g + 0] = __uint_as_float(uu.x << 16) - aw[4 * g + 0];
;         vn[it][4 * g + 1] = __uint_as_float(uu.x & 0xffff0000u) - aw[4 * g + 1];
;         vn[it][4 * g + 2] = __uint_as_float(uu.y << 16) - aw[4 * g + 2];
;         vn[it][4 * g + 3] = __uint_as_float(uu.y & 0xffff0000u) - aw[4 * g + 3];
;       }
;     }
;     B2_LOADU(n + 1 < 32 ? n + 1 : n);
;     bf16x8 Vb[2][2];
; #pragma unroll
;     for (int jt = 0; jt < 2; ++jt) { Vb[jt][0] = pack8(vn[jt], 0); Vb[jt][1] = pack8(vn[jt], 1); }
; #pragma unroll
;     for (int it = 0; it < 2; ++it) {
; #pragma unroll
;       for (int e = 0; e < 16; ++e) o[it][e] = 0.f;
; #pragma unroll
;       for (int T = 0; T < 4; ++T)
; #pragma unroll
;         for (int s = 0; s < 2; ++s) o[it] = MFMA32(ld16(qg + (it * 4096 + (T * 2 + s) * 512) + lo8), pack8(S[T], s), o[it]);
; #pragma unroll
;       for (int jt = 0; jt < 2; ++jt)
; #pragma unroll
;         for (int s = 0; s < 2; ++s)
;           o[it] = MFMA32(ld16(ag + (it * 2048 + (jt * 2 + s) * 512) + lo8), Vb[jt][s], o[it]);
;     }
;     const float egl = __shfl(eglv, n);
; #pragma unroll
;     for (int T = 0; T < 4; ++T) {
;       f32x16 acc;
; #pragma unroll
;       for (int e = 0; e < 16; ++e) acc[e] = S[T][e] * egl;
	v_pk_mul_f32 v[64:65], v[64:65], v[0:1] op_sel_hi:[1,0]
	v_mfma_f32_32x32x16_bf16 v[66:81], v[86:89], v[190:193], v[66:81]
	ds_read_b128 v[86:89], v240 offset:11264
	v_mul_f32_e64 v62, v62, v0
	v_mul_f32_e64 v63, v63, v0
	v_mul_f32_e64 v60, v60, v0
	v_mul_f32_e64 v61, v61, v0
	v_pk_mul_f32 v[58:59], v[58:59], v[0:1] op_sel_hi:[1,0]
	v_pk_mul_f32 v[56:57], v[56:57], v[0:1] op_sel_hi:[1,0]
	v_pk_mul_f32 v[54:55], v[54:55], v[0:1] op_sel_hi:[1,0]
	v_pk_mul_f32 v[52:53], v[52:53], v[0:1] op_sel_hi:[1,0]
	s_waitcnt lgkmcnt(0)
	v_mfma_f32_32x32x16_bf16 v[66:81], v[86:89], v[186:189], v[66:81]
	ds_read_b128 v[86:89], v240 offset:12288
	v_mul_f32_e64 v50, v50, v0
	v_mul_f32_e64 v51, v51, v0
	v_mul_f32_e64 v48, v48, v0
	v_mul_f32_e64 v49, v49, v0
	v_pk_mul_f32 v[46:47], v[46:47], v[0:1] op_sel_hi:[1,0]
	v_pk_mul_f32 v[44:45], v[44:45], v[0:1] op_sel_hi:[1,0]
	v_pk_mul_f32 v[42:43], v[42:43], v[0:1] op_sel_hi:[1,0]
	v_pk_mul_f32 v[40:41], v[40:41], v[0:1] op_sel_hi:[1,0]
	s_waitcnt lgkmcnt(0)
	v_mfma_f32_32x32x16_bf16 v[66:81], v[86:89], v[182:185], v[66:81]
	ds_read_b128 v[86:89], v240 offset:13312
	v_mul_f32_e64 v38, v38, v0
	v_mul_f32_e64 v39, v39, v0
	v_mul_f32_e64 v36, v36, v0
	v_mul_f32_e64 v37, v37, v0
	v_pk_mul_f32 v[34:35], v[34:35], v[0:1] op_sel_hi:[1,0]
	v_pk_mul_f32 v[32:33], v[32:33], v[0:1] op_sel_hi:[1,0]
	v_pk_mul_f32 v[30:31], v[30:31], v[0:1] op_sel_hi:[1,0]
	v_pk_mul_f32 v[28:29], v[28:29], v[0:1] op_sel_hi:[1,0]
	s_waitcnt lgkmcnt(0)
	v_mfma_f32_32x32x16_bf16 v[66:81], v[86:89], v[178:181], v[66:81]
	ds_read_b128 v[86:89], v240 offset:14336
	v_mul_f32_e64 v26, v26, v0
	v_mul_f32_e64 v27, v27, v0
	v_mul_f32_e64 v24, v24, v0
	v_mul_f32_e64 v25, v25, v0
	v_pk_mul_f32 v[22:23], v[22:23], v[0:1] op_sel_hi:[1,0]
	v_pk_mul_f32 v[20:21], v[20:21], v[0:1] op_sel_hi:[1,0]
	v_pk_mul_f32 v[18:19], v[18:19], v[0:1] op_sel_hi:[1,0]
	v_pk_mul_f32 v[16:17], v[16:17], v[0:1] op_sel_hi:[1,0]
	s_waitcnt lgkmcnt(0)
	v_mfma_f32_32x32x16_bf16 v[66:81], v[86:89], v[174:177], v[66:81]
	ds_read_b128 v[86:89], v240 offset:15360
	v_mul_f32_e64 v14, v14, v0
	v_mul_f32_e64 v15, v15, v0
	v_mul_f32_e64 v12, v12, v0
	v_mul_f32_e64 v13, v13, v0
	v_pk_mul_f32 v[10:11], v[10:11], v[0:1] op_sel_hi:[1,0]
	v_pk_mul_f32 v[8:9], v[8:9], v[0:1] op_sel_hi:[1,0]
	v_pk_mul_f32 v[6:7], v[6:7], v[0:1] op_sel_hi:[1,0]
	v_pk_mul_f32 v[4:5], v[4:5], v[0:1] op_sel_hi:[1,0]
	s_waitcnt lgkmcnt(0)
	v_mfma_f32_32x32x16_bf16 v[66:81], v[86:89], v[170:173], v[66:81]
	s_waitcnt vmcnt(17)
	v_lshlrev_b32_e32 v86, 16, v206
	v_and_b32_e32 v87, 0xffff0000, v206
	v_mul_f32_e64 v2, v2, v0
	v_mul_f32_e64 v3, v3, v0
	s_nop 6
	v_pk_add_f32 v[66:67], v[86:87], v[66:67] neg_lo:[0,1] neg_hi:[0,1]
	v_lshlrev_b32_e32 v86, 16, v207
	v_and_b32_e32 v87, 0xffff0000, v207
	v_pk_add_f32 v[68:69], v[86:87], v[68:69] neg_lo:[0,1] neg_hi:[0,1]
	s_waitcnt vmcnt(16)
	v_lshlrev_b32_e32 v86, 16, v204
	v_and_b32_e32 v87, 0xffff0000, v204
	v_pk_add_f32 v[70:71], v[86:87], v[70:71] neg_lo:[0,1] neg_hi:[0,1]
	v_lshlrev_b32_e32 v86, 16, v205
	v_and_b32_e32 v87, 0xffff0000, v205
	v_pk_add_f32 v[72:73], v[86:87], v[72:73] neg_lo:[0,1] neg_hi:[0,1]
	s_waitcnt vmcnt(15)
	v_lshlrev_b32_e32 v86, 16, v202
	v_and_b32_e32 v87, 0xffff0000, v202
	v_pk_add_f32 v[74:75], v[86:87], v[74:75] neg_lo:[0,1] neg_hi:[0,1]
	v_lshlrev_b32_e32 v86, 16, v203
	v_and_b32_e32 v87, 0xffff0000, v203
	v_pk_add_f32 v[76:77], v[86:87], v[76:77] neg_lo:[0,1] neg_hi:[0,1]
	s_waitcnt vmcnt(14)
	v_lshlrev_b32_e32 v86, 16, v200
	v_and_b32_e32 v87, 0xffff0000, v200
	v_pk_add_f32 v[78:79], v[86:87], v[78:79] neg_lo:[0,1] neg_hi:[0,1]
	v_lshlrev_b32_e32 v86, 16, v201
	v_and_b32_e32 v87, 0xffff0000, v201
	v_pk_add_f32 v[80:81], v[86:87], v[80:81] neg_lo:[0,1] neg_hi:[0,1]
	v_lshl_add_u64 v[86:87], v[216:217], 0, s[4:5]
	global_load_dwordx2 v[226:227], v[86:87], off
	global_load_dwordx2 v[224:225], v[86:87], off offset:512
	global_load_dwordx2 v[222:223], v[86:87], off offset:1024
	global_load_dwordx2 v[220:221], v[86:87], off offset:1536
	global_load_dwordx2 v[206:207], v[86:87], off offset:2048
	global_load_dwordx2 v[204:205], v[86:87], off offset:2560
	global_load_dwordx2 v[202:203], v[86:87], off offset:3072
	global_load_dwordx2 v[200:201], v[86:87], off offset:3584
	v_cvt_pk_bf16_f32 v158, v66, v67
	v_cvt_pk_bf16_f32 v159, v68, v69
	ds_read_b128 v[66:69], v240 offset:16384
	ds_read_b128 v[86:89], v240 offset:17408
	v_cvt_pk_bf16_f32 v160, v70, v71
	v_cvt_pk_bf16_f32 v161, v72, v73
	v_cvt_pk_bf16_f32 v154, v74, v75
	v_cvt_pk_bf16_f32 v155, v76, v77
	v_cvt_pk_bf16_f32 v156, v78, v79
	v_cvt_pk_bf16_f32 v157, v80, v81
	s_waitcnt lgkmcnt(1)
	v_mfma_f32_32x32x16_bf16 v[66:81], v[66:69], v[82:85], 0
	ds_read_b128 v[242:245], v240 offset:25600
	s_waitcnt lgkmcnt(1)
	v_mfma_f32_32x32x16_bf16 v[66:81], v[86:89], v[194:197], v[66:81]
	ds_read_b128 v[86:89], v240 offset:18432
	s_waitcnt lgkmcnt(0)
	v_mfma_f32_32x32x16_bf16 v[66:81], v[86:89], v[190:193], v[66:81]
	ds_read_b128 v[86:89], v240 offset:19456
	s_waitcnt lgkmcnt(0)
	v_mfma_f32_32x32x16_bf16 v[66:81], v[86:89], v[186:189], v[66:81]
	ds_read_b128 v[86:89], v240 offset:20480
	s_waitcnt lgkmcnt(0)
	v_mfma_f32_32x32x16_bf16 v[66:81], v[86:89], v[182:185], v[66:81]
	ds_read_b128 v[86:89], v240 offset:21504
	s_waitcnt lgkmcnt(0)
	v_mfma_f32_32x32x16_bf16 v[66:81], v[86:89], v[178:181], v[66:81]
	ds_read_b128 v[86:89], v240 offset:22528
	s_waitcnt lgkmcnt(0)
	v_mfma_f32_32x32x16_bf16 v[66:81], v[86:89], v[174:177], v[66:81]
	ds_read_b128 v[86:89], v240 offset:23552
	s_waitcnt lgkmcnt(0)
	v_mfma_f32_32x32x16_bf16 v[66:81], v[86:89], v[170:173], v[66:81]
	ds_read_b128 v[86:89], v240 offset:49152
	s_waitcnt lgkmcnt(0)
; #define MFMA32(a, b, c) __builtin_amdgcn_mfma_f32_32x32x16_bf16((a), (b), (c), 0, 0, 0)
; #define B2_STORE() do { uint4* l_ = (uint4*)L + tid; \
;     l_[0] = pw0; l_[256] = pw1; l_[512] = pw2; l_[768] = pw3; l_[1024] = pq0; l_[1280] = pq1; l_[1536] = pq2; l_[1792] = pq3; \
;     l_[2048] = pk0; l_[2304] = pk1; l_[2560] = pk2; l_[2816] = pk3; l_[3072] = pa0; l_[3328] = pa1; } while (0)
; DI void phaseB2(const Params& p, int bh, char* smem, int n_begin, int n_end) {
;     ...
;         for (int s = 0; s < 2; ++s) o[it] = MFMA32(ld16(qg + (it * 4096 + (T * 2 + s) * 512) + lo8), pack8(S[T], s), o[it]);
; #pragma unroll
;       for (int jt = 0; jt < 2; ++jt)
; #pragma unroll
;         for (int s = 0; s < 2; ++s)
;           o[it] = MFMA32(ld16(ag + (it * 2048 + (jt * 2 + s) * 512) + lo8), Vb[jt][s], o[it]);
;     }
;     const float egl = __shfl(eglv, n);
; #pragma unroll
;     for (int T = 0; T < 4; ++T) {
;       f32x16 acc;
; #pragma unroll
;       for (int e = 0; e < 16; ++e) acc[e] = S[T][e] * egl;
; #pragma unroll
;       for (int jt = 0; jt < 2; ++jt)
; #pragma unroll
;         for (int s = 0; s < 2; ++s)
;           acc = MFMA32(ld16(kg + (T * 2048 + (jt * 2 + s) * 512) + lo8), Vb[jt][s], acc);
;       S[T] = acc;
;     }
;     asm volatile("s_waitcnt lgkmcnt(0)\n\ts_barrier" ::: "memory");
;     B2_STORE();
	v_mfma_f32_32x32x16_bf16 v[66:81], v[86:89], v[166:169], v[66:81]
	ds_read_b128 v[86:89], v240 offset:50176
	s_waitcnt lgkmcnt(0)
	v_mfma_f32_32x32x16_bf16 v[66:81], v[86:89], v[162:165], v[66:81]
	ds_read_b128 v[86:89], v240 offset:51200
	s_waitcnt lgkmcnt(0)
	v_mfma_f32_32x32x16_bf16 v[66:81], v[86:89], v[158:161], v[66:81]
	ds_read_b128 v[86:89], v240 offset:52224
	s_waitcnt lgkmcnt(0)
	v_mfma_f32_32x32x16_bf16 v[66:81], v[86:89], v[154:157], v[66:81]
	ds_read_b128 v[86:89], v240 offset:24576
	s_waitcnt lgkmcnt(0)
	v_mfma_f32_32x32x16_bf16 v[82:97], v[86:89], v[82:85], 0
	s_nop 8
	v_cvt_pk_bf16_f32 v0, v66, s0
	v_mfma_f32_32x32x16_bf16 v[82:97], v[242:245], v[194:197], v[82:97]
	ds_read_b128 v[194:197], v240 offset:26624
	s_waitcnt lgkmcnt(0)
	v_mfma_f32_32x32x16_bf16 v[82:97], v[194:197], v[190:193], v[82:97]
	ds_read_b128 v[190:193], v240 offset:27648
	s_waitcnt lgkmcnt(0)
	v_mfma_f32_32x32x16_bf16 v[82:97], v[190:193], v[186:189], v[82:97]
	ds_read_b128 v[186:189], v240 offset:28672
	s_waitcnt lgkmcnt(0)
	v_mfma_f32_32x32x16_bf16 v[82:97], v[186:189], v[182:185], v[82:97]
	ds_read_b128 v[182:185], v240 offset:29696
	s_waitcnt lgkmcnt(0)
	v_mfma_f32_32x32x16_bf16 v[82:97], v[182:185], v[178:181], v[82:97]
	ds_read_b128 v[178:181], v240 offset:30720
	s_waitcnt lgkmcnt(0)
	v_mfma_f32_32x32x16_bf16 v[82:97], v[178:181], v[174:177], v[82:97]
	ds_read_b128 v[174:177], v240 offset:31744
	s_waitcnt lgkmcnt(0)
	v_mfma_f32_32x32x16_bf16 v[82:97], v[174:177], v[170:173], v[82:97]
	ds_read_b128 v[170:173], v240 offset:53248
	s_waitcnt lgkmcnt(0)
	v_mfma_f32_32x32x16_bf16 v[82:97], v[170:173], v[166:169], v[82:97]
	ds_read_b128 v[170:173], v240 offset:54272
	s_waitcnt lgkmcnt(0)
	v_mfma_f32_32x32x16_bf16 v[82:97], v[170:173], v[162:165], v[82:97]
	ds_read_b128 v[170:173], v240 offset:55296
	s_waitcnt lgkmcnt(0)
	v_mfma_f32_32x32x16_bf16 v[82:97], v[170:173], v[158:161], v[82:97]
	ds_read_b128 v[170:173], v240 offset:56320
	s_waitcnt lgkmcnt(0)
	v_mfma_f32_32x32x16_bf16 v[82:97], v[170:173], v[154:157], v[82:97]
	ds_read_b128 v[170:173], v240 offset:32768
	s_waitcnt lgkmcnt(0)
	v_mfma_f32_32x32x16_bf16 v[50:65], v[170:173], v[166:169], v[50:65]
	ds_read_b128 v[170:173], v240 offset:33792
	s_waitcnt lgkmcnt(0)
	v_mfma_f32_32x32x16_bf16 v[50:65], v[170:173], v[162:165], v[50:65]
	ds_read_b128 v[170:173], v240 offset:34816
	s_waitcnt lgkmcnt(0)
	v_mfma_f32_32x32x16_bf16 v[50:65], v[170:173], v[158:161], v[50:65]
	ds_read_b128 v[170:173], v240 offset:35840
	s_waitcnt lgkmcnt(0)
	v_mfma_f32_32x32x16_bf16 v[50:65], v[170:173], v[154:157], v[50:65]
	ds_read_b128 v[170:173], v240 offset:36864
	s_waitcnt lgkmcnt(0)
	v_mfma_f32_32x32x16_bf16 v[34:49], v[170:173], v[166:169], v[34:49]
	ds_read_b128 v[170:173], v240 offset:37888
	s_waitcnt lgkmcnt(0)
	v_mfma_f32_32x32x16_bf16 v[34:49], v[170:173], v[162:165], v[34:49]
	ds_read_b128 v[170:173], v240 offset:38912
	s_waitcnt lgkmcnt(0)
	v_mfma_f32_32x32x16_bf16 v[34:49], v[170:173], v[158:161], v[34:49]
	ds_read_b128 v[170:173], v240 offset:39936
	s_waitcnt lgkmcnt(0)
	v_mfma_f32_32x32x16_bf16 v[34:49], v[170:173], v[154:157], v[34:49]
	ds_read_b128 v[170:173], v240 offset:40960
	s_waitcnt lgkmcnt(0)
	v_mfma_f32_32x32x16_bf16 v[18:33], v[170:173], v[166:169], v[18:33]
	ds_read_b128 v[170:173], v240 offset:41984
	s_waitcnt lgkmcnt(0)
	v_mfma_f32_32x32x16_bf16 v[18:33], v[170:173], v[162:165], v[18:33]
	ds_read_b128 v[170:173], v240 offset:43008
	s_waitcnt lgkmcnt(0)
	v_mfma_f32_32x32x16_bf16 v[18:33], v[170:173], v[158:161], v[18:33]
	ds_read_b128 v[170:173], v240 offset:44032
	s_waitcnt lgkmcnt(0)
	v_mfma_f32_32x32x16_bf16 v[18:33], v[170:173], v[154:157], v[18:33]
	ds_read_b128 v[170:173], v240 offset:45056
	s_waitcnt lgkmcnt(0)
	v_mfma_f32_32x32x16_bf16 v[2:17], v[170:173], v[166:169], v[2:17]
	ds_read_b128 v[166:169], v240 offset:46080
	s_waitcnt lgkmcnt(0)
	v_mfma_f32_32x32x16_bf16 v[2:17], v[166:169], v[162:165], v[2:17]
	ds_read_b128 v[162:165], v240 offset:47104
	s_waitcnt lgkmcnt(0)
	v_mfma_f32_32x32x16_bf16 v[2:17], v[162:165], v[158:161], v[2:17]
	ds_read_b128 v[158:161], v240 offset:48128
	s_waitcnt lgkmcnt(0)
	s_barrier
	s_waitcnt vmcnt(21)
	ds_write_b128 v229, v[98:101]
	s_waitcnt vmcnt(20)
	ds_write_b128 v229, v[102:105] offset:4096
	s_waitcnt vmcnt(19)
	ds_write_b128 v229, v[106:109] offset:8192
	s_waitcnt vmcnt(18)
	ds_write_b128 v229, v[110:113] offset:12288
	s_waitcnt vmcnt(17)
	ds_write_b128 v229, v[114:117] offset:16384
	s_waitcnt vmcnt(16)
	ds_write_b128 v229, v[118:121] offset:20480
	s_waitcnt vmcnt(15)
	ds_write_b128 v229, v[122:125] offset:24576
	s_waitcnt vmcnt(14)
	ds_write_b128 v229, v[126:129] offset:28672
	s_waitcnt vmcnt(13)
	ds_write_b128 v229, v[130:133] offset:32768
	s_waitcnt vmcnt(12)
	ds_write_b128 v229, v[134:137] offset:36864
	s_waitcnt vmcnt(11)
	ds_write_b128 v229, v[138:141] offset:40960
	s_waitcnt vmcnt(10)
	ds_write_b128 v229, v[142:145] offset:45056
	s_waitcnt vmcnt(9)
	ds_write_b128 v229, v[146:149] offset:49152
	s_waitcnt vmcnt(8)
	ds_write_b128 v229, v[150:153] offset:53248
	v_lshl_add_u64 v[98:99], v[218:219], 0, s[0:1]
	v_add_co_u32_e32 v100, vcc, s8, v98
	s_waitcnt lgkmcnt(0)
	s_barrier
; #define MFMA32(a, b, c) __builtin_amdgcn_mfma_f32_32x32x16_bf16((a), (b), (c), 0, 0, 0)
; DI bf16_t f2bf(float x) { return (bf16_t)(pack2(x, 0.f) & 0xffffu); }
; DI int crow(int reg, int hh) { return (reg & 3) + 8 * (reg >> 2) + 4 * hh; }
; #define B2_STORE() do { uint4* l_ = (uint4*)L + tid; \
;     l_[0] = pw0; l_[256] = pw1; l_[512] = pw2; l_[768] = pw3; l_[1024] = pq0; l_[1280] = pq1; l_[1536] = pq2; l_[1792] = pq3; \
;     l_[2048] = pk0; l_[2304] = pk1; l_[2560] = pk2; l_[2816] = pk3; l_[3072] = pa0; l_[3328] = pa1; } while (0)
; DI void phaseB2(const Params& p, int bh, char* smem, int n_begin, int n_end) {
;     ...
;           acc = MFMA32(ld16(kg + (T * 2048 + (jt * 2 + s) * 512) + lo8), Vb[jt][s], acc);
;       S[T] = acc;
;     }
;     asm volatile("s_waitcnt lgkmcnt(0)\n\ts_barrier" ::: "memory");
;     B2_STORE();
;     asm volatile("s_waitcnt lgkmcnt(0)\n\ts_barrier" ::: "memory");
;     {
;       bf16_t* og = p.ob + (size_t)(b * SEQ + n * 64) * 512 + hd * 128 + v0 + r;
; #pragma unroll
;       for (int it = 0; it < 2; ++it)
; #pragma unroll
;         for (int e = 0; e < 16; ++e) og[(size_t)(it * 32 + crow(e, hh)) * 512] = f2bf(o[it][e]);
;     }
;   }
;   if (n_end < 32) {
; #pragma unroll
;     for (int T = 0; T < 4; ++T)
; #pragma unroll
;       for (int q4 = 0; q4 < 4; ++q4)
;         *(float4*)(sst + T * 16 + q4 * 4) = make_float4(S[T][q4 * 4], S[T][q4 * 4 + 1], S[T][q4 * 4 + 2], S[T][q4 * 4 + 3]);
;   }
;   __syncthreads();
	s_waitcnt lgkmcnt(14)
	v_mfma_f32_32x32x16_bf16 v[2:17], v[158:161], v[154:157], v[2:17]
	v_addc_co_u32_e32 v101, vcc, 0, v99, vcc
	global_store_short v[100:101], v0, off
	v_cvt_pk_bf16_f32 v0, v67, s0
	global_store_short v[100:101], v0, off offset:1024
	v_cvt_pk_bf16_f32 v0, v68, s0
	global_store_short v[100:101], v0, off offset:2048
	v_cvt_pk_bf16_f32 v0, v69, s0
	v_add_co_u32_e32 v66, vcc, s9, v98
	global_store_short v[100:101], v0, off offset:3072
	v_cvt_pk_bf16_f32 v0, v70, s0
	v_addc_co_u32_e32 v67, vcc, 0, v99, vcc
	global_store_short v[66:67], v0, off
	v_cvt_pk_bf16_f32 v0, v71, s0
	global_store_short v[66:67], v0, off offset:1024
	v_cvt_pk_bf16_f32 v0, v72, s0
	global_store_short v[66:67], v0, off offset:2048
	v_cvt_pk_bf16_f32 v0, v73, s0
	global_store_short v[66:67], v0, off offset:3072
	v_add_co_u32_e32 v66, vcc, s10, v98
	v_cvt_pk_bf16_f32 v0, v74, s0
	s_nop 0
	v_addc_co_u32_e32 v67, vcc, 0, v99, vcc
	global_store_short v[66:67], v0, off
	v_cvt_pk_bf16_f32 v0, v75, s0
	global_store_short v[66:67], v0, off offset:1024
	v_cvt_pk_bf16_f32 v0, v76, s0
	global_store_short v[66:67], v0, off offset:2048
	v_cvt_pk_bf16_f32 v0, v77, s0
	global_store_short v[66:67], v0, off offset:3072
	v_add_co_u32_e32 v66, vcc, s11, v98
	v_cvt_pk_bf16_f32 v0, v78, s0
	s_nop 0
	v_addc_co_u32_e32 v67, vcc, 0, v99, vcc
	global_store_short v[66:67], v0, off
	v_cvt_pk_bf16_f32 v0, v79, s0
	global_store_short v[66:67], v0, off offset:1024
	v_cvt_pk_bf16_f32 v0, v80, s0
	global_store_short v[66:67], v0, off offset:2048
	v_cvt_pk_bf16_f32 v0, v81, s0
	global_store_short v[66:67], v0, off offset:3072
	v_add_co_u32_e32 v66, vcc, s12, v98
	v_cvt_pk_bf16_f32 v0, v82, s0
	s_nop 0
	v_addc_co_u32_e32 v67, vcc, 0, v99, vcc
	global_store_short v[66:67], v0, off
	v_cvt_pk_bf16_f32 v0, v83, s0
	global_store_short v[66:67], v0, off offset:1024
	v_cvt_pk_bf16_f32 v0, v84, s0
	global_store_short v[66:67], v0, off offset:2048
	v_cvt_pk_bf16_f32 v0, v85, s0
	global_store_short v[66:67], v0, off offset:3072
	v_add_co_u32_e32 v66, vcc, s13, v98
	v_cvt_pk_bf16_f32 v0, v86, s0
	s_nop 0
	v_addc_co_u32_e32 v67, vcc, 0, v99, vcc
	global_store_short v[66:67], v0, off
	v_cvt_pk_bf16_f32 v0, v87, s0
	global_store_short v[66:67], v0, off offset:1024
	v_cvt_pk_bf16_f32 v0, v88, s0
	global_store_short v[66:67], v0, off offset:2048
	v_cvt_pk_bf16_f32 v0, v89, s0
	global_store_short v[66:67], v0, off offset:3072
	v_add_co_u32_e32 v66, vcc, s14, v98
	v_cvt_pk_bf16_f32 v0, v90, s0
	s_nop 0
	v_addc_co_u32_e32 v67, vcc, 0, v99, vcc
	global_store_short v[66:67], v0, off
	v_cvt_pk_bf16_f32 v0, v91, s0
	global_store_short v[66:67], v0, off offset:1024
	v_cvt_pk_bf16_f32 v0, v92, s0
	global_store_short v[66:67], v0, off offset:2048
	v_cvt_pk_bf16_f32 v0, v93, s0
	global_store_short v[66:67], v0, off offset:3072
	v_add_co_u32_e32 v66, vcc, s16, v98
	v_cvt_pk_bf16_f32 v0, v94, s0
	s_nop 0
	v_addc_co_u32_e32 v67, vcc, 0, v99, vcc
	global_store_short v[66:67], v0, off
	v_cvt_pk_bf16_f32 v0, v95, s0
	global_store_short v[66:67], v0, off offset:1024
	v_cvt_pk_bf16_f32 v0, v96, s0
	global_store_short v[66:67], v0, off offset:2048
	v_cvt_pk_bf16_f32 v0, v97, s0
	s_add_u32 s0, s0, 0x10000
	s_addc_u32 s1, s1, 0
	s_add_i32 s2, s2, 4
	s_cmp_lg_u32 s0, 0x50000
	global_store_short v[66:67], v0, off offset:3072
	s_cbranch_scc1 .LBB0_1757
	s_setprio 0
	v_add_co_u32_e32 v66, vcc, 0x400000, v198
	s_nop 1
	v_addc_co_u32_e32 v67, vcc, 0, v199, vcc
	global_store_dwordx4 v[66:67], v[50:53], off
	global_store_dwordx4 v[66:67], v[54:57], off offset:16
	global_store_dwordx4 v[66:67], v[58:61], off offset:32
	global_store_dwordx4 v[66:67], v[62:65], off offset:48
	global_store_dwordx4 v[66:67], v[34:37], off offset:64
	global_store_dwordx4 v[66:67], v[38:41], off offset:80
	global_store_dwordx4 v[66:67], v[42:45], off offset:96
	global_store_dwordx4 v[66:67], v[46:49], off offset:112
	global_store_dwordx4 v[66:67], v[18:21], off offset:128
	global_store_dwordx4 v[66:67], v[22:25], off offset:144
	global_store_dwordx4 v[66:67], v[26:29], off offset:160
	global_store_dwordx4 v[66:67], v[30:33], off offset:176
	global_store_dwordx4 v[66:67], v[2:5], off offset:192
	global_store_dwordx4 v[66:67], v[6:9], off offset:208
	global_store_dwordx4 v[66:67], v[10:13], off offset:224
	global_store_dwordx4 v[66:67], v[14:17], off offset:240
	s_waitcnt lgkmcnt(0)
	s_barrier

; #define MFMA32(a, b, c) __builtin_amdgcn_mfma_f32_32x32x16_bf16((a), (b), (c), 0, 0, 0)
; #define B2_STORE() do { uint4* l_ = (uint4*)L + tid; \
;     l_[0] = pw0; l_[256] = pw1; l_[512] = pw2; l_[768] = pw3; l_[1024] = pq0; l_[1280] = pq1; l_[1536] = pq2; l_[1792] = pq3; \
;     l_[2048] = pk0; l_[2304] = pk1; l_[2560] = pk2; l_[2816] = pk3; l_[3072] = pa0; l_[3328] = pa1; } while (0)
; DI void phaseB2(const Params& p, int bh, char* smem, int n_begin, int n_end) {
;     ...
;   __syncthreads();
;   B2_LOAD(n_begin);
;   B2_LOADU(n_begin);
;   B2_STORE();
;   __syncthreads();
; #pragma unroll 1
;   for (int n = n_begin; n < n_end; ++n) {
;     B2_LOAD(n + 1 < 32 ? n + 1 : n);
;     f32x16 vn[2], o[2];
; #pragma unroll
;     for (int it = 0; it < 2; ++it) {
;       f32x16 aw;
; #pragma unroll
;       for (int e = 0; e < 16; ++e) aw[e] = 0.f;
; #pragma unroll
;       for (int T = 0; T < 4; ++T)
; #pragma unroll
;         for (int s = 0; s < 2; ++s) aw = MFMA32(ld16(wg + (it * 4096 + (T * 2 + s) * 512) + lo8), pack8(S[T], s), aw);
; #pragma unroll
;       for (int g = 0; g < 4; ++g) {
;         const uint2 uu = it == 0 ? (g == 0 ? pu0 : g == 1 ? pu1 : g == 2 ? pu2 : pu3) : (g == 0 ? pu4 : g == 1 ? pu5 : g == 2 ? pu6 : pu7);
;         vn[it][4 * g + 0] = __uint_as_float(uu.x << 16) - aw[4 * g + 0];
;         vn[it][4 * g + 1] = __uint_as_float(uu.x & 0xffff0000u) - aw[4 * g + 1];
;         vn[it][4 * g + 2] = __uint_as_float(uu.y << 16) - aw[4 * g + 2];
;         vn[it][4 * g + 3] = __uint_as_float(uu.y & 0xffff0000u) - aw[4 * g + 3];
;       }
;     }
;     B2_LOADU(n + 1 < 32 ? n + 1 : n);
;     bf16x8 Vb[2][2];
; #pragma unroll
;     for (int jt = 0; jt < 2; ++jt) { Vb[jt][0] = pack8(vn[jt], 0); Vb[jt][1] = pack8(vn[jt], 1); }
; #pragma unroll
;     for (int it = 0; it < 2; ++it) {
; #pragma unroll
;       for (int e = 0; e < 16; ++e) o[it][e] = 0.f;
; #pragma unroll
;       for (int T = 0; T < 4; ++T)
; #pragma unroll
;         for (int s = 0; s < 2; ++s) o[it] = MFMA32(ld16(qg + (it * 4096 + (T * 2 + s) * 512) + lo8), pack8(S[T], s), o[it]);
; #pragma unroll
;       for (int jt = 0; jt < 2; ++jt)
; #pragma unroll
;         for (int s = 0; s < 2; ++s)
;           o[it] = MFMA32(ld16(ag + (it * 2048 + (jt * 2 + s) * 512) + lo8), Vb[jt][s], o[it]);
;     }
;     const float egl = __shfl(eglv, n);
.LBB0_1761:
	s_setprio 3
	s_ashr_i32 s3, s2, 31
	s_lshl_b64 s[6:7], s[2:3], 14
	v_lshl_add_u64 v[66:67], v[208:209], 0, s[6:7]
	v_add_co_u32_e32 v74, vcc, s80, v66
	global_load_dwordx4 v[98:101], v[66:67], off
	s_nop 0
	v_addc_co_u32_e32 v75, vcc, 0, v67, vcc
	v_add_co_u32_e32 v66, vcc, s81, v66
	v_lshl_add_u64 v[68:69], v[210:211], 0, s[6:7]
	s_nop 0
	v_addc_co_u32_e32 v67, vcc, 0, v67, vcc
	global_load_dwordx4 v[102:105], v[74:75], off offset:-4096
	global_load_dwordx4 v[106:109], v[74:75], off
	global_load_dwordx4 v[110:113], v[66:67], off
	global_load_dwordx4 v[114:117], v[68:69], off
	v_add_co_u32_e32 v66, vcc, s80, v68
	v_lshl_add_u64 v[70:71], v[212:213], 0, s[6:7]
	s_nop 0
	v_addc_co_u32_e32 v67, vcc, 0, v69, vcc
	global_load_dwordx4 v[118:121], v[66:67], off offset:-4096
	global_load_dwordx4 v[122:125], v[66:67], off
	v_add_co_u32_e32 v66, vcc, s81, v68
	s_lshl_b64 s[10:11], s[2:3], 13
	s_nop 0
	v_addc_co_u32_e32 v67, vcc, 0, v69, vcc
	global_load_dwordx4 v[126:129], v[66:67], off
	global_load_dwordx4 v[130:133], v[70:71], off
	v_add_co_u32_e32 v66, vcc, s80, v70
	v_lshl_add_u64 v[72:73], v[214:215], 0, s[10:11]
	s_nop 0
	v_addc_co_u32_e32 v67, vcc, 0, v71, vcc
	global_load_dwordx4 v[134:137], v[66:67], off offset:-4096
	global_load_dwordx4 v[138:141], v[66:67], off
	v_add_co_u32_e32 v66, vcc, s81, v70
	v_cvt_pk_bf16_f32 v82, v50, v51
	s_nop 0
	v_addc_co_u32_e32 v67, vcc, 0, v71, vcc
	global_load_dwordx4 v[142:145], v[66:67], off
	global_load_dwordx4 v[146:149], v[72:73], off
	v_add_co_u32_e32 v66, vcc, s97, v72
	v_cvt_pk_bf16_f32 v83, v52, v53
	s_nop 0
	v_addc_co_u32_e32 v67, vcc, 0, v73, vcc
	global_load_dwordx4 v[150:153], v[66:67], off
	ds_read_b128 v[66:69], v240
	ds_read_b128 v[86:89], v240 offset:1024
	v_cvt_pk_bf16_f32 v84, v54, v55
	v_cvt_pk_bf16_f32 v85, v56, v57
	v_cvt_pk_bf16_f32 v194, v58, v59
	v_cvt_pk_bf16_f32 v195, v60, v61
	s_waitcnt lgkmcnt(1)
	v_mfma_f32_32x32x16_bf16 v[66:81], v[66:69], v[82:85], 0
	v_cvt_pk_bf16_f32 v196, v62, v63
	v_cvt_pk_bf16_f32 v197, v64, v65
	v_cvt_pk_bf16_f32 v190, v34, v35
	v_cvt_pk_bf16_f32 v191, v36, v37
	v_cvt_pk_bf16_f32 v192, v38, v39
	v_cvt_pk_bf16_f32 v193, v40, v41
	v_cvt_pk_bf16_f32 v186, v42, v43
	s_waitcnt lgkmcnt(0)
	v_mfma_f32_32x32x16_bf16 v[66:81], v[86:89], v[194:197], v[66:81]
	ds_read_b128 v[86:89], v240 offset:2048
	v_cvt_pk_bf16_f32 v187, v44, v45
	v_cvt_pk_bf16_f32 v188, v46, v47
	v_cvt_pk_bf16_f32 v189, v48, v49
	v_cvt_pk_bf16_f32 v182, v18, v19
	v_cvt_pk_bf16_f32 v183, v20, v21
	v_cvt_pk_bf16_f32 v184, v22, v23
	s_waitcnt lgkmcnt(0)
	v_mfma_f32_32x32x16_bf16 v[66:81], v[86:89], v[190:193], v[66:81]
	ds_read_b128 v[86:89], v240 offset:3072
	v_cvt_pk_bf16_f32 v185, v24, v25
	v_cvt_pk_bf16_f32 v178, v26, v27
	v_cvt_pk_bf16_f32 v179, v28, v29
	v_cvt_pk_bf16_f32 v180, v30, v31
	v_cvt_pk_bf16_f32 v181, v32, v33
	v_cvt_pk_bf16_f32 v174, v2, v3
	s_waitcnt lgkmcnt(0)
	v_mfma_f32_32x32x16_bf16 v[66:81], v[86:89], v[186:189], v[66:81]
	ds_read_b128 v[86:89], v240 offset:4096
	v_cvt_pk_bf16_f32 v175, v4, v5
	v_cvt_pk_bf16_f32 v176, v6, v7
	v_cvt_pk_bf16_f32 v177, v8, v9
	v_cvt_pk_bf16_f32 v170, v10, v11
	v_cvt_pk_bf16_f32 v171, v12, v13
	v_cvt_pk_bf16_f32 v172, v14, v15
	s_waitcnt lgkmcnt(0)
	v_mfma_f32_32x32x16_bf16 v[66:81], v[86:89], v[182:185], v[66:81]
	ds_read_b128 v[86:89], v240 offset:5120
	v_cvt_pk_bf16_f32 v173, v16, v17
	s_waitcnt vmcnt(21)
	v_lshlrev_b32_e32 v0, 16, v226
	s_waitcnt lgkmcnt(0)
	v_mfma_f32_32x32x16_bf16 v[66:81], v[86:89], v[178:181], v[66:81]
	ds_read_b128 v[86:89], v240 offset:6144
	s_waitcnt lgkmcnt(0)
	v_mfma_f32_32x32x16_bf16 v[66:81], v[86:89], v[174:177], v[66:81]
	ds_read_b128 v[86:89], v240 offset:7168
	s_waitcnt lgkmcnt(0)
	v_mfma_f32_32x32x16_bf16 v[66:81], v[86:89], v[170:173], v[66:81]
	ds_read_b128 v[86:89], v240 offset:9216
	s_nop 10
	v_sub_f32_e32 v0, v0, v66
	v_and_b32_e32 v66, 0xffff0000, v226
	v_sub_f32_e32 v90, v66, v67
	v_lshlrev_b32_e32 v66, 16, v227
	v_sub_f32_e32 v91, v66, v68
	v_and_b32_e32 v66, 0xffff0000, v227
	v_sub_f32_e32 v92, v66, v69
	s_waitcnt vmcnt(20)
	v_lshlrev_b32_e32 v66, 16, v224
	v_sub_f32_e32 v93, v66, v70
	v_and_b32_e32 v66, 0xffff0000, v224
	v_sub_f32_e32 v94, v66, v71
	v_lshlrev_b32_e32 v66, 16, v225
	v_sub_f32_e32 v95, v66, v72
	v_and_b32_e32 v66, 0xffff0000, v225
	v_sub_f32_e32 v96, v66, v73
	s_waitcnt vmcnt(19)
	v_lshlrev_b32_e32 v66, 16, v222
	v_sub_f32_e32 v97, v66, v74
	v_and_b32_e32 v66, 0xffff0000, v222
	v_sub_f32_e32 v154, v66, v75
	v_lshlrev_b32_e32 v66, 16, v223
	v_sub_f32_e32 v155, v66, v76
	v_and_b32_e32 v66, 0xffff0000, v223
	v_sub_f32_e32 v156, v66, v77
	s_waitcnt vmcnt(18)
	v_lshlrev_b32_e32 v66, 16, v220
	v_sub_f32_e32 v157, v66, v78
	v_and_b32_e32 v66, 0xffff0000, v220
	v_sub_f32_e32 v158, v66, v79
	v_lshlrev_b32_e32 v66, 16, v221
	v_sub_f32_e32 v159, v66, v80
	v_and_b32_e32 v66, 0xffff0000, v221
	v_sub_f32_e32 v160, v66, v81
	ds_read_b128 v[66:69], v240 offset:8192
	s_waitcnt lgkmcnt(0)
	v_mfma_f32_32x32x16_bf16 v[66:81], v[66:69], v[82:85], 0
	v_cvt_pk_bf16_f32 v164, v157, v158
	v_cvt_pk_bf16_f32 v165, v159, v160
	v_cvt_pk_bf16_f32 v162, v97, v154
	v_cvt_pk_bf16_f32 v163, v155, v156
	v_cvt_pk_bf16_f32 v166, v0, v90
	v_cvt_pk_bf16_f32 v167, v91, v92
	v_cvt_pk_bf16_f32 v168, v93, v94
	v_mfma_f32_32x32x16_bf16 v[66:81], v[86:89], v[194:197], v[66:81]
	ds_read_b128 v[86:89], v240 offset:10240
	v_cvt_pk_bf16_f32 v169, v95, v96
	ds_bpermute_b32 v0, v241, v228
	v_add_u32_e32 v241, 4, v241
	s_waitcnt lgkmcnt(0)
; #define MFMA32(a, b, c) __builtin_amdgcn_mfma_f32_32x32x16_bf16((a), (b), (c), 0, 0, 0)
; DI void phaseB2(const Params& p, int bh, char* smem, int n_begin, int n_end) {
;     ...
;         for (int s = 0; s < 2; ++s) aw = MFMA32(ld16(wg + (it * 4096 + (T * 2 + s) * 512) + lo8), pack8(S[T], s), aw);
; #pragma unroll
;       for (int g = 0; g < 4; ++g) {
;         const uint2 uu = it == 0 ? (g == 0 ? pu0 : g == 1 ? pu1 : g == 2 ? pu2 : pu3) : (g == 0 ? pu4 : g == 1 ? pu5 : g == 2 ? pu6 : pu7);
;         vn[it][4 * g + 0] = __uint_as_float(uu.x << 16) - aw[4 * g + 0];
;         vn[it][4 * g + 1] = __uint_as_float(uu.x & 0xffff0000u) - aw[4 * g + 1];
;         vn[it][4 * g + 2] = __uint_as_float(uu.y << 16) - aw[4 * g + 2];
;         vn[it][4 * g + 3] = __uint_as_float(uu.y & 0xffff0000u) - aw[4 * g + 3];
;       }
;     }
;     B2_LOADU(n + 1 < 32 ? n + 1 : n);
;     bf16x8 Vb[2][2];
; #pragma unroll
;     for (int jt = 0; jt < 2; ++jt) { Vb[jt][0] = pack8(vn[jt], 0); Vb[jt][1] = pack8(vn[jt], 1); }
; #pragma unroll
;     for (int it = 0; it < 2; ++it) {
; #pragma unroll
;       for (int e = 0; e < 16; ++e) o[it][e] = 0.f;
; #pragma unroll
;       for (int T = 0; T < 4; ++T)
; #pragma unroll
;         for (int s = 0; s < 2; ++s) o[it] = MFMA32(ld16(qg + (it * 4096 + (T * 2 + s) * 512) + lo8), pack8(S[T], s), o[it]);
; #pragma unroll
;       for (int jt = 0; jt < 2; ++jt)
; #pragma unroll
;         for (int s = 0; s < 2; ++s)
;           o[it] = MFMA32(ld16(ag + (it * 2048 + (jt * 2 + s) * 512) + lo8), Vb[jt][s], o[it]);
;     }
;     const float egl = __shfl(eglv, n);
; #pragma unroll
;     for (int T = 0; T < 4; ++T) {
;       f32x16 acc;
; #pragma unroll
;       for (int e = 0; e < 16; ++e) acc[e] = S[T][e] * egl;
	v_pk_mul_f32 v[64:65], v[64:65], v[0:1] op_sel_hi:[1,0]
	v_mfma_f32_32x32x16_bf16 v[66:81], v[86:89], v[190:193], v[66:81]
	ds_read_b128 v[86:89], v240 offset:11264
	v_mul_f32_e64 v62, v62, v0
	v_mul_f32_e64 v63, v63, v0
	v_mul_f32_e64 v60, v60, v0
	v_mul_f32_e64 v61, v61, v0
	v_pk_mul_f32 v[58:59], v[58:59], v[0:1] op_sel_hi:[1,0]
	v_pk_mul_f32 v[56:57], v[56:57], v[0:1] op_sel_hi:[1,0]
	v_pk_mul_f32 v[54:55], v[54:55], v[0:1] op_sel_hi:[1,0]
	v_pk_mul_f32 v[52:53], v[52:53], v[0:1] op_sel_hi:[1,0]
	s_waitcnt lgkmcnt(0)
	v_mfma_f32_32x32x16_bf16 v[66:81], v[86:89], v[186:189], v[66:81]
	ds_read_b128 v[86:89], v240 offset:12288
	v_mul_f32_e64 v50, v50, v0
	v_mul_f32_e64 v51, v51, v0
	v_mul_f32_e64 v48, v48, v0
	v_mul_f32_e64 v49, v49, v0
	v_pk_mul_f32 v[46:47], v[46:47], v[0:1] op_sel_hi:[1,0]
	v_pk_mul_f32 v[44:45], v[44:45], v[0:1] op_sel_hi:[1,0]
	v_pk_mul_f32 v[42:43], v[42:43], v[0:1] op_sel_hi:[1,0]
	v_pk_mul_f32 v[40:41], v[40:41], v[0:1] op_sel_hi:[1,0]
	s_waitcnt lgkmcnt(0)
	v_mfma_f32_32x32x16_bf16 v[66:81], v[86:89], v[182:185], v[66:81]
	ds_read_b128 v[86:89], v240 offset:13312
	v_mul_f32_e64 v38, v38, v0
	v_mul_f32_e64 v39, v39, v0
	v_mul_f32_e64 v36, v36, v0
	v_mul_f32_e64 v37, v37, v0
	v_pk_mul_f32 v[34:35], v[34:35], v[0:1] op_sel_hi:[1,0]
	v_pk_mul_f32 v[32:33], v[32:33], v[0:1] op_sel_hi:[1,0]
	v_pk_mul_f32 v[30:31], v[30:31], v[0:1] op_sel_hi:[1,0]
	v_pk_mul_f32 v[28:29], v[28:29], v[0:1] op_sel_hi:[1,0]
	s_waitcnt lgkmcnt(0)
	v_mfma_f32_32x32x16_bf16 v[66:81], v[86:89], v[178:181], v[66:81]
	ds_read_b128 v[86:89], v240 offset:14336
	v_mul_f32_e64 v26, v26, v0
	v_mul_f32_e64 v27, v27, v0
	v_mul_f32_e64 v24, v24, v0
	v_mul_f32_e64 v25, v25, v0
	v_pk_mul_f32 v[22:23], v[22:23], v[0:1] op_sel_hi:[1,0]
	v_pk_mul_f32 v[20:21], v[20:21], v[0:1] op_sel_hi:[1,0]
	v_pk_mul_f32 v[18:19], v[18:19], v[0:1] op_sel_hi:[1,0]
	v_pk_mul_f32 v[16:17], v[16:17], v[0:1] op_sel_hi:[1,0]
	s_waitcnt lgkmcnt(0)
	v_mfma_f32_32x32x16_bf16 v[66:81], v[86:89], v[174:177], v[66:81]
	ds_read_b128 v[86:89], v240 offset:15360
	v_mul_f32_e64 v14, v14, v0
	v_mul_f32_e64 v15, v15, v0
	v_mul_f32_e64 v12, v12, v0
	v_mul_f32_e64 v13, v13, v0
	v_pk_mul_f32 v[10:11], v[10:11], v[0:1] op_sel_hi:[1,0]
	v_pk_mul_f32 v[8:9], v[8:9], v[0:1] op_sel_hi:[1,0]
	v_pk_mul_f32 v[6:7], v[6:7], v[0:1] op_sel_hi:[1,0]
	v_pk_mul_f32 v[4:5], v[4:5], v[0:1] op_sel_hi:[1,0]
	s_waitcnt lgkmcnt(0)
	v_mfma_f32_32x32x16_bf16 v[66:81], v[86:89], v[170:173], v[66:81]
	s_waitcnt vmcnt(17)
	v_lshlrev_b32_e32 v86, 16, v206
	v_and_b32_e32 v87, 0xffff0000, v206
	v_mul_f32_e64 v2, v2, v0
	v_mul_f32_e64 v3, v3, v0
	s_nop 6
	v_pk_add_f32 v[66:67], v[86:87], v[66:67] neg_lo:[0,1] neg_hi:[0,1]
	v_lshlrev_b32_e32 v86, 16, v207
	v_and_b32_e32 v87, 0xffff0000, v207
	v_pk_add_f32 v[68:69], v[86:87], v[68:69] neg_lo:[0,1] neg_hi:[0,1]
	s_waitcnt vmcnt(16)
	v_lshlrev_b32_e32 v86, 16, v204
	v_and_b32_e32 v87, 0xffff0000, v204
	v_pk_add_f32 v[70:71], v[86:87], v[70:71] neg_lo:[0,1] neg_hi:[0,1]
	v_lshlrev_b32_e32 v86, 16, v205
	v_and_b32_e32 v87, 0xffff0000, v205
	v_pk_add_f32 v[72:73], v[86:87], v[72:73] neg_lo:[0,1] neg_hi:[0,1]
	s_waitcnt vmcnt(15)
	v_lshlrev_b32_e32 v86, 16, v202
	v_and_b32_e32 v87, 0xffff0000, v202
	v_pk_add_f32 v[74:75], v[86:87], v[74:75] neg_lo:[0,1] neg_hi:[0,1]
	v_lshlrev_b32_e32 v86, 16, v203
	v_and_b32_e32 v87, 0xffff0000, v203
	v_pk_add_f32 v[76:77], v[86:87], v[76:77] neg_lo:[0,1] neg_hi:[0,1]
	s_waitcnt vmcnt(14)
	v_lshlrev_b32_e32 v86, 16, v200
	v_and_b32_e32 v87, 0xffff0000, v200
	v_pk_add_f32 v[78:79], v[86:87], v[78:79] neg_lo:[0,1] neg_hi:[0,1]
	v_lshlrev_b32_e32 v86, 16, v201
	v_and_b32_e32 v87, 0xffff0000, v201
	v_pk_add_f32 v[80:81], v[86:87], v[80:81] neg_lo:[0,1] neg_hi:[0,1]
	v_lshl_add_u64 v[86:87], v[216:217], 0, s[6:7]
	global_load_dwordx2 v[226:227], v[86:87], off
	global_load_dwordx2 v[224:225], v[86:87], off offset:512
	global_load_dwordx2 v[222:223], v[86:87], off offset:1024
	global_load_dwordx2 v[220:221], v[86:87], off offset:1536
	global_load_dwordx2 v[206:207], v[86:87], off offset:2048
	global_load_dwordx2 v[204:205], v[86:87], off offset:2560
	global_load_dwordx2 v[202:203], v[86:87], off offset:3072
	global_load_dwordx2 v[200:201], v[86:87], off offset:3584
	v_cvt_pk_bf16_f32 v158, v66, v67
	v_cvt_pk_bf16_f32 v159, v68, v69
	ds_read_b128 v[66:69], v240 offset:16384
	ds_read_b128 v[86:89], v240 offset:17408
	v_cvt_pk_bf16_f32 v160, v70, v71
	v_cvt_pk_bf16_f32 v161, v72, v73
	v_cvt_pk_bf16_f32 v154, v74, v75
	v_cvt_pk_bf16_f32 v155, v76, v77
	v_cvt_pk_bf16_f32 v156, v78, v79
	v_cvt_pk_bf16_f32 v157, v80, v81
	s_waitcnt lgkmcnt(1)
	v_mfma_f32_32x32x16_bf16 v[66:81], v[66:69], v[82:85], 0
	ds_read_b128 v[242:245], v240 offset:25600
	s_waitcnt lgkmcnt(1)
	v_mfma_f32_32x32x16_bf16 v[66:81], v[86:89], v[194:197], v[66:81]
	ds_read_b128 v[86:89], v240 offset:18432
	s_waitcnt lgkmcnt(0)
	v_mfma_f32_32x32x16_bf16 v[66:81], v[86:89], v[190:193], v[66:81]
	ds_read_b128 v[86:89], v240 offset:19456
	s_waitcnt lgkmcnt(0)
	v_mfma_f32_32x32x16_bf16 v[66:81], v[86:89], v[186:189], v[66:81]
	ds_read_b128 v[86:89], v240 offset:20480
	s_waitcnt lgkmcnt(0)
	v_mfma_f32_32x32x16_bf16 v[66:81], v[86:89], v[182:185], v[66:81]
	ds_read_b128 v[86:89], v240 offset:21504
	s_waitcnt lgkmcnt(0)
	v_mfma_f32_32x32x16_bf16 v[66:81], v[86:89], v[178:181], v[66:81]
	ds_read_b128 v[86:89], v240 offset:22528
	s_waitcnt lgkmcnt(0)
	v_mfma_f32_32x32x16_bf16 v[66:81], v[86:89], v[174:177], v[66:81]
	ds_read_b128 v[86:89], v240 offset:23552
	s_waitcnt lgkmcnt(0)
	v_mfma_f32_32x32x16_bf16 v[66:81], v[86:89], v[170:173], v[66:81]
	ds_read_b128 v[86:89], v240 offset:49152
	s_waitcnt lgkmcnt(0)
; #define MFMA32(a, b, c) __builtin_amdgcn_mfma_f32_32x32x16_bf16((a), (b), (c), 0, 0, 0)
; #define B2_STORE() do { uint4* l_ = (uint4*)L + tid; \
;     l_[0] = pw0; l_[256] = pw1; l_[512] = pw2; l_[768] = pw3; l_[1024] = pq0; l_[1280] = pq1; l_[1536] = pq2; l_[1792] = pq3; \
;     l_[2048] = pk0; l_[2304] = pk1; l_[2560] = pk2; l_[2816] = pk3; l_[3072] = pa0; l_[3328] = pa1; } while (0)
; DI void phaseB2(const Params& p, int bh, char* smem, int n_begin, int n_end) {
;     ...
;         for (int s = 0; s < 2; ++s) o[it] = MFMA32(ld16(qg + (it * 4096 + (T * 2 + s) * 512) + lo8), pack8(S[T], s), o[it]);
; #pragma unroll
;       for (int jt = 0; jt < 2; ++jt)
; #pragma unroll
;         for (int s = 0; s < 2; ++s)
;           o[it] = MFMA32(ld16(ag + (it * 2048 + (jt * 2 + s) * 512) + lo8), Vb[jt][s], o[it]);
;     }
;     const float egl = __shfl(eglv, n);
; #pragma unroll
;     for (int T = 0; T < 4; ++T) {
;       f32x16 acc;
; #pragma unroll
;       for (int e = 0; e < 16; ++e) acc[e] = S[T][e] * egl;
; #pragma unroll
;       for (int jt = 0; jt < 2; ++jt)
; #pragma unroll
;         for (int s = 0; s < 2; ++s)
;           acc = MFMA32(ld16(kg + (T * 2048 + (jt * 2 + s) * 512) + lo8), Vb[jt][s], acc);
;       S[T] = acc;
;     }
;     asm volatile("s_waitcnt lgkmcnt(0)\n\ts_barrier" ::: "memory");
;     B2_STORE();
	v_mfma_f32_32x32x16_bf16 v[66:81], v[86:89], v[166:169], v[66:81]
	ds_read_b128 v[86:89], v240 offset:50176
	s_waitcnt lgkmcnt(0)
	v_mfma_f32_32x32x16_bf16 v[66:81], v[86:89], v[162:165], v[66:81]
	ds_read_b128 v[86:89], v240 offset:51200
	s_waitcnt lgkmcnt(0)
	v_mfma_f32_32x32x16_bf16 v[66:81], v[86:89], v[158:161], v[66:81]
	ds_read_b128 v[86:89], v240 offset:52224
	s_waitcnt lgkmcnt(0)
	v_mfma_f32_32x32x16_bf16 v[66:81], v[86:89], v[154:157], v[66:81]
	ds_read_b128 v[86:89], v240 offset:24576
	s_waitcnt lgkmcnt(0)
	v_mfma_f32_32x32x16_bf16 v[82:97], v[86:89], v[82:85], 0
	s_nop 8
	v_cvt_pk_bf16_f32 v0, v66, s0
	v_mfma_f32_32x32x16_bf16 v[82:97], v[242:245], v[194:197], v[82:97]
	ds_read_b128 v[194:197], v240 offset:26624
	s_waitcnt lgkmcnt(0)
	v_mfma_f32_32x32x16_bf16 v[82:97], v[194:197], v[190:193], v[82:97]
	ds_read_b128 v[190:193], v240 offset:27648
	s_waitcnt lgkmcnt(0)
	v_mfma_f32_32x32x16_bf16 v[82:97], v[190:193], v[186:189], v[82:97]
	ds_read_b128 v[186:189], v240 offset:28672
	s_waitcnt lgkmcnt(0)
	v_mfma_f32_32x32x16_bf16 v[82:97], v[186:189], v[182:185], v[82:97]
	ds_read_b128 v[182:185], v240 offset:29696
	s_waitcnt lgkmcnt(0)
	v_mfma_f32_32x32x16_bf16 v[82:97], v[182:185], v[178:181], v[82:97]
	ds_read_b128 v[178:181], v240 offset:30720
	s_waitcnt lgkmcnt(0)
	v_mfma_f32_32x32x16_bf16 v[82:97], v[178:181], v[174:177], v[82:97]
	ds_read_b128 v[174:177], v240 offset:31744
	s_waitcnt lgkmcnt(0)
	v_mfma_f32_32x32x16_bf16 v[82:97], v[174:177], v[170:173], v[82:97]
	ds_read_b128 v[170:173], v240 offset:53248
	s_waitcnt lgkmcnt(0)
	v_mfma_f32_32x32x16_bf16 v[82:97], v[170:173], v[166:169], v[82:97]
	ds_read_b128 v[170:173], v240 offset:54272
	s_waitcnt lgkmcnt(0)
	v_mfma_f32_32x32x16_bf16 v[82:97], v[170:173], v[162:165], v[82:97]
	ds_read_b128 v[170:173], v240 offset:55296
	s_waitcnt lgkmcnt(0)
	v_mfma_f32_32x32x16_bf16 v[82:97], v[170:173], v[158:161], v[82:97]
	ds_read_b128 v[170:173], v240 offset:56320
	s_waitcnt lgkmcnt(0)
	v_mfma_f32_32x32x16_bf16 v[82:97], v[170:173], v[154:157], v[82:97]
	ds_read_b128 v[170:173], v240 offset:32768
	s_waitcnt lgkmcnt(0)
	v_mfma_f32_32x32x16_bf16 v[50:65], v[170:173], v[166:169], v[50:65]
	ds_read_b128 v[170:173], v240 offset:33792
	s_waitcnt lgkmcnt(0)
	v_mfma_f32_32x32x16_bf16 v[50:65], v[170:173], v[162:165], v[50:65]
	ds_read_b128 v[170:173], v240 offset:34816
	s_waitcnt lgkmcnt(0)
	v_mfma_f32_32x32x16_bf16 v[50:65], v[170:173], v[158:161], v[50:65]
	ds_read_b128 v[170:173], v240 offset:35840
	s_waitcnt lgkmcnt(0)
	v_mfma_f32_32x32x16_bf16 v[50:65], v[170:173], v[154:157], v[50:65]
	ds_read_b128 v[170:173], v240 offset:36864
	s_waitcnt lgkmcnt(0)
	v_mfma_f32_32x32x16_bf16 v[34:49], v[170:173], v[166:169], v[34:49]
	ds_read_b128 v[170:173], v240 offset:37888
	s_waitcnt lgkmcnt(0)
	v_mfma_f32_32x32x16_bf16 v[34:49], v[170:173], v[162:165], v[34:49]
	ds_read_b128 v[170:173], v240 offset:38912
	s_waitcnt lgkmcnt(0)
	v_mfma_f32_32x32x16_bf16 v[34:49], v[170:173], v[158:161], v[34:49]
	ds_read_b128 v[170:173], v240 offset:39936
	s_waitcnt lgkmcnt(0)
	v_mfma_f32_32x32x16_bf16 v[34:49], v[170:173], v[154:157], v[34:49]
	ds_read_b128 v[170:173], v240 offset:40960
	s_waitcnt lgkmcnt(0)
	v_mfma_f32_32x32x16_bf16 v[18:33], v[170:173], v[166:169], v[18:33]
	ds_read_b128 v[170:173], v240 offset:41984
	s_waitcnt lgkmcnt(0)
	v_mfma_f32_32x32x16_bf16 v[18:33], v[170:173], v[162:165], v[18:33]
	ds_read_b128 v[170:173], v240 offset:43008
	s_waitcnt lgkmcnt(0)
	v_mfma_f32_32x32x16_bf16 v[18:33], v[170:173], v[158:161], v[18:33]
	ds_read_b128 v[170:173], v240 offset:44032
	s_waitcnt lgkmcnt(0)
	v_mfma_f32_32x32x16_bf16 v[18:33], v[170:173], v[154:157], v[18:33]
	ds_read_b128 v[170:173], v240 offset:45056
	s_waitcnt lgkmcnt(0)
	v_mfma_f32_32x32x16_bf16 v[2:17], v[170:173], v[166:169], v[2:17]
	ds_read_b128 v[166:169], v240 offset:46080
	s_waitcnt lgkmcnt(0)
	v_mfma_f32_32x32x16_bf16 v[2:17], v[166:169], v[162:165], v[2:17]
	ds_read_b128 v[162:165], v240 offset:47104
	s_waitcnt lgkmcnt(0)
	v_mfma_f32_32x32x16_bf16 v[2:17], v[162:165], v[158:161], v[2:17]
	ds_read_b128 v[158:161], v240 offset:48128
	s_waitcnt lgkmcnt(0)
	s_barrier
	s_waitcnt vmcnt(21)
	ds_write_b128 v229, v[98:101]
	s_waitcnt vmcnt(20)
	ds_write_b128 v229, v[102:105] offset:4096
	s_waitcnt vmcnt(19)
	ds_write_b128 v229, v[106:109] offset:8192
	s_waitcnt vmcnt(18)
	ds_write_b128 v229, v[110:113] offset:12288
	s_waitcnt vmcnt(17)
	ds_write_b128 v229, v[114:117] offset:16384
	s_waitcnt vmcnt(16)
	ds_write_b128 v229, v[118:121] offset:20480
	s_waitcnt vmcnt(15)
	ds_write_b128 v229, v[122:125] offset:24576
	s_waitcnt vmcnt(14)
	ds_write_b128 v229, v[126:129] offset:28672
	s_waitcnt vmcnt(13)
	ds_write_b128 v229, v[130:133] offset:32768
	s_waitcnt vmcnt(12)
	ds_write_b128 v229, v[134:137] offset:36864
	s_waitcnt vmcnt(11)
	ds_write_b128 v229, v[138:141] offset:40960
	s_waitcnt vmcnt(10)
	ds_write_b128 v229, v[142:145] offset:45056
	s_waitcnt vmcnt(9)
	ds_write_b128 v229, v[146:149] offset:49152
	s_waitcnt vmcnt(8)
	ds_write_b128 v229, v[150:153] offset:53248
	v_lshl_add_u64 v[98:99], v[218:219], 0, s[4:5]
	v_add_co_u32_e32 v100, vcc, s1, v98
	s_waitcnt lgkmcnt(0)
	s_barrier
; #define MFMA32(a, b, c) __builtin_amdgcn_mfma_f32_32x32x16_bf16((a), (b), (c), 0, 0, 0)
; DI bf16_t f2bf(float x) { return (bf16_t)(pack2(x, 0.f) & 0xffffu); }
; DI int crow(int reg, int hh) { return (reg & 3) + 8 * (reg >> 2) + 4 * hh; }
; #define B2_STORE() do { uint4* l_ = (uint4*)L + tid; \
;     l_[0] = pw0; l_[256] = pw1; l_[512] = pw2; l_[768] = pw3; l_[1024] = pq0; l_[1280] = pq1; l_[1536] = pq2; l_[1792] = pq3; \
;     l_[2048] = pk0; l_[2304] = pk1; l_[2560] = pk2; l_[2816] = pk3; l_[3072] = pa0; l_[3328] = pa1; } while (0)
; DI void phaseB2(const Params& p, int bh, char* smem, int n_begin, int n_end) {
;     ...
;           acc = MFMA32(ld16(kg + (T * 2048 + (jt * 2 + s) * 512) + lo8), Vb[jt][s], acc);
;       S[T] = acc;
;     }
;     asm volatile("s_waitcnt lgkmcnt(0)\n\ts_barrier" ::: "memory");
;     B2_STORE();
;     asm volatile("s_waitcnt lgkmcnt(0)\n\ts_barrier" ::: "memory");
;     {
;       bf16_t* og = p.ob + (size_t)(b * SEQ + n * 64) * 512 + hd * 128 + v0 + r;
; #pragma unroll
;       for (int it = 0; it < 2; ++it)
; #pragma unroll
;         for (int e = 0; e < 16; ++e) og[(size_t)(it * 32 + crow(e, hh)) * 512] = f2bf(o[it][e]);
;     }
;   }
;   if (n_end < 32) {
; #pragma unroll
;     for (int T = 0; T < 4; ++T)
; #pragma unroll
;       for (int q4 = 0; q4 < 4; ++q4)
;         *(float4*)(sst + T * 16 + q4 * 4) = make_float4(S[T][q4 * 4], S[T][q4 * 4 + 1], S[T][q4 * 4 + 2], S[T][q4 * 4 + 3]);
;   }
;   __syncthreads();
; __global__ void __launch_bounds__(256, 2) mega(Params p, int ph_lo, int ph_hi) {
;     ...
;         if (nb2 == 0) for (int u = blockIdx.x; u < 64; u += gridDim.x) phaseB2(p, u, smem, B2_S1, B2_S2);
	s_waitcnt lgkmcnt(14)
	v_mfma_f32_32x32x16_bf16 v[2:17], v[158:161], v[154:157], v[2:17]
	v_addc_co_u32_e32 v101, vcc, 0, v99, vcc
	global_store_short v[100:101], v0, off
	v_cvt_pk_bf16_f32 v0, v67, s0
	global_store_short v[100:101], v0, off offset:1024
	v_cvt_pk_bf16_f32 v0, v68, s0
	global_store_short v[100:101], v0, off offset:2048
	v_cvt_pk_bf16_f32 v0, v69, s0
	v_add_co_u32_e32 v66, vcc, s9, v98
	global_store_short v[100:101], v0, off offset:3072
	v_cvt_pk_bf16_f32 v0, v70, s0
	v_addc_co_u32_e32 v67, vcc, 0, v99, vcc
	global_store_short v[66:67], v0, off
	v_cvt_pk_bf16_f32 v0, v71, s0
	global_store_short v[66:67], v0, off offset:1024
	v_cvt_pk_bf16_f32 v0, v72, s0
	global_store_short v[66:67], v0, off offset:2048
	v_cvt_pk_bf16_f32 v0, v73, s0
	global_store_short v[66:67], v0, off offset:3072
	v_add_co_u32_e32 v66, vcc, s12, v98
	v_cvt_pk_bf16_f32 v0, v74, s0
	s_nop 0
	v_addc_co_u32_e32 v67, vcc, 0, v99, vcc
	global_store_short v[66:67], v0, off
	v_cvt_pk_bf16_f32 v0, v75, s0
	global_store_short v[66:67], v0, off offset:1024
	v_cvt_pk_bf16_f32 v0, v76, s0
	global_store_short v[66:67], v0, off offset:2048
	v_cvt_pk_bf16_f32 v0, v77, s0
	global_store_short v[66:67], v0, off offset:3072
	v_add_co_u32_e32 v66, vcc, s13, v98
	v_cvt_pk_bf16_f32 v0, v78, s0
	s_nop 0
	v_addc_co_u32_e32 v67, vcc, 0, v99, vcc
	global_store_short v[66:67], v0, off
	v_cvt_pk_bf16_f32 v0, v79, s0
	global_store_short v[66:67], v0, off offset:1024
	v_cvt_pk_bf16_f32 v0, v80, s0
	global_store_short v[66:67], v0, off offset:2048
	v_cvt_pk_bf16_f32 v0, v81, s0
	global_store_short v[66:67], v0, off offset:3072
	v_add_co_u32_e32 v66, vcc, s14, v98
	v_cvt_pk_bf16_f32 v0, v82, s0
	s_nop 0
	v_addc_co_u32_e32 v67, vcc, 0, v99, vcc
	global_store_short v[66:67], v0, off
	v_cvt_pk_bf16_f32 v0, v83, s0
	global_store_short v[66:67], v0, off offset:1024
	v_cvt_pk_bf16_f32 v0, v84, s0
	global_store_short v[66:67], v0, off offset:2048
	v_cvt_pk_bf16_f32 v0, v85, s0
	global_store_short v[66:67], v0, off offset:3072
	v_add_co_u32_e32 v66, vcc, s16, v98
	v_cvt_pk_bf16_f32 v0, v86, s0
	s_nop 0
	v_addc_co_u32_e32 v67, vcc, 0, v99, vcc
	global_store_short v[66:67], v0, off
	v_cvt_pk_bf16_f32 v0, v87, s0
	global_store_short v[66:67], v0, off offset:1024
	v_cvt_pk_bf16_f32 v0, v88, s0
	global_store_short v[66:67], v0, off offset:2048
	v_cvt_pk_bf16_f32 v0, v89, s0
	global_store_short v[66:67], v0, off offset:3072
	v_add_co_u32_e32 v66, vcc, s17, v98
	v_cvt_pk_bf16_f32 v0, v90, s0
	s_nop 0
	v_addc_co_u32_e32 v67, vcc, 0, v99, vcc
	global_store_short v[66:67], v0, off
	v_cvt_pk_bf16_f32 v0, v91, s0
	global_store_short v[66:67], v0, off offset:1024
	v_cvt_pk_bf16_f32 v0, v92, s0
	global_store_short v[66:67], v0, off offset:2048
	v_cvt_pk_bf16_f32 v0, v93, s0
	global_store_short v[66:67], v0, off offset:3072
	v_add_co_u32_e32 v66, vcc, s18, v98
	v_cvt_pk_bf16_f32 v0, v94, s0
	s_nop 0
	v_addc_co_u32_e32 v67, vcc, 0, v99, vcc
	global_store_short v[66:67], v0, off
	v_cvt_pk_bf16_f32 v0, v95, s0
	s_add_u32 s4, s4, 0x10000
	global_store_short v[66:67], v0, off offset:1024
	v_cvt_pk_bf16_f32 v0, v96, s0
	s_addc_u32 s5, s5, 0
	s_add_i32 s2, s2, 4
	global_store_short v[66:67], v0, off offset:2048
	v_cvt_pk_bf16_f32 v0, v97, s0
	s_cmp_lg_u32 s4, 0x50000
	global_store_short v[66:67], v0, off offset:3072
	s_cbranch_scc1 .LBB0_1761
	s_setprio 0
	v_readlane_b32 s1, v253, 56
	v_add_co_u32_e32 v66, vcc, 0x400000, v198
	s_add_i32 s0, s0, s1
	s_add_i32 s8, s8, s1
	v_addc_co_u32_e32 v67, vcc, 0, v199, vcc
	s_cmp_gt_i32 s0, 63
	global_store_dwordx4 v[66:67], v[50:53], off
	global_store_dwordx4 v[66:67], v[54:57], off offset:16
	global_store_dwordx4 v[66:67], v[58:61], off offset:32
	global_store_dwordx4 v[66:67], v[62:65], off offset:48
	global_store_dwordx4 v[66:67], v[34:37], off offset:64
	global_store_dwordx4 v[66:67], v[38:41], off offset:80
	global_store_dwordx4 v[66:67], v[42:45], off offset:96
	global_store_dwordx4 v[66:67], v[46:49], off offset:112
	global_store_dwordx4 v[66:67], v[18:21], off offset:128
	global_store_dwordx4 v[66:67], v[22:25], off offset:144
	global_store_dwordx4 v[66:67], v[26:29], off offset:160
	global_store_dwordx4 v[66:67], v[30:33], off offset:176
	global_store_dwordx4 v[66:67], v[2:5], off offset:192
	global_store_dwordx4 v[66:67], v[6:9], off offset:208
	global_store_dwordx4 v[66:67], v[10:13], off offset:224
	global_store_dwordx4 v[66:67], v[14:17], off offset:240
	s_waitcnt lgkmcnt(0)
	s_barrier
	s_cbranch_scc0 .LBB0_1760

; #define MFMA32(a, b, c) __builtin_amdgcn_mfma_f32_32x32x16_bf16((a), (b), (c), 0, 0, 0)
; #define B2_STORE() do { uint4* l_ = (uint4*)L + tid; \
;     l_[0] = pw0; l_[256] = pw1; l_[512] = pw2; l_[768] = pw3; l_[1024] = pq0; l_[1280] = pq1; l_[1536] = pq2; l_[1792] = pq3; \
;     l_[2048] = pk0; l_[2304] = pk1; l_[2560] = pk2; l_[2816] = pk3; l_[3072] = pa0; l_[3328] = pa1; } while (0)
; DI void phaseB2(const Params& p, int bh, char* smem, int n_begin, int n_end) {
;     ...
;   __syncthreads();
;   B2_LOAD(n_begin);
;   B2_LOADU(n_begin);
;   B2_STORE();
;   __syncthreads();
; #pragma unroll 1
;   for (int n = n_begin; n < n_end; ++n) {
;     B2_LOAD(n + 1 < 32 ? n + 1 : n);
;     f32x16 vn[2], o[2];
; #pragma unroll
;     for (int it = 0; it < 2; ++it) {
;       f32x16 aw;
; #pragma unroll
;       for (int e = 0; e < 16; ++e) aw[e] = 0.f;
; #pragma unroll
;       for (int T = 0; T < 4; ++T)
; #pragma unroll
;         for (int s = 0; s < 2; ++s) aw = MFMA32(ld16(wg + (it * 4096 + (T * 2 + s) * 512) + lo8), pack8(S[T], s), aw);
; #pragma unroll
;       for (int g = 0; g < 4; ++g) {
;         const uint2 uu = it == 0 ? (g == 0 ? pu0 : g == 1 ? pu1 : g == 2 ? pu2 : pu3) : (g == 0 ? pu4 : g == 1 ? pu5 : g == 2 ? pu6 : pu7);
;         vn[it][4 * g + 0] = __uint_as_float(uu.x << 16) - aw[4 * g + 0];
;         vn[it][4 * g + 1] = __uint_as_float(uu.x & 0xffff0000u) - aw[4 * g + 1];
;         vn[it][4 * g + 2] = __uint_as_float(uu.y << 16) - aw[4 * g + 2];
;         vn[it][4 * g + 3] = __uint_as_float(uu.y & 0xffff0000u) - aw[4 * g + 3];
;       }
;     }
;     B2_LOADU(n + 1 < 32 ? n + 1 : n);
;     bf16x8 Vb[2][2];
; #pragma unroll
;     for (int jt = 0; jt < 2; ++jt) { Vb[jt][0] = pack8(vn[jt], 0); Vb[jt][1] = pack8(vn[jt], 1); }
; #pragma unroll
;     for (int it = 0; it < 2; ++it) {
; #pragma unroll
;       for (int e = 0; e < 16; ++e) o[it][e] = 0.f;
; #pragma unroll
;       for (int T = 0; T < 4; ++T)
; #pragma unroll
;         for (int s = 0; s < 2; ++s) o[it] = MFMA32(ld16(qg + (it * 4096 + (T * 2 + s) * 512) + lo8), pack8(S[T], s), o[it]);
; #pragma unroll
;       for (int jt = 0; jt < 2; ++jt)
; #pragma unroll
;         for (int s = 0; s < 2; ++s)
;           o[it] = MFMA32(ld16(ag + (it * 2048 + (jt * 2 + s) * 512) + lo8), Vb[jt][s], o[it]);
;     }
;     const float egl = __shfl(eglv, n);
.LBB0_1770:
	s_setprio 3
	s_ashr_i32 s3, s2, 31
	s_lshl_b64 s[4:5], s[2:3], 14
	v_lshl_add_u64 v[66:67], v[208:209], 0, s[4:5]
	v_add_co_u32_e32 v74, vcc, s80, v66
	global_load_dwordx4 v[98:101], v[66:67], off
	s_nop 0
	v_addc_co_u32_e32 v75, vcc, 0, v67, vcc
	v_add_co_u32_e32 v66, vcc, s81, v66
	v_lshl_add_u64 v[68:69], v[210:211], 0, s[4:5]
	s_nop 0
	v_addc_co_u32_e32 v67, vcc, 0, v67, vcc
	global_load_dwordx4 v[102:105], v[74:75], off offset:-4096
	global_load_dwordx4 v[106:109], v[74:75], off
	global_load_dwordx4 v[110:113], v[66:67], off
	global_load_dwordx4 v[114:117], v[68:69], off
	v_add_co_u32_e32 v66, vcc, s80, v68
	v_lshl_add_u64 v[70:71], v[212:213], 0, s[4:5]
	s_nop 0
	v_addc_co_u32_e32 v67, vcc, 0, v69, vcc
	global_load_dwordx4 v[118:121], v[66:67], off offset:-4096
	global_load_dwordx4 v[122:125], v[66:67], off
	v_add_co_u32_e32 v66, vcc, s81, v68
	s_lshl_b64 s[6:7], s[2:3], 13
	s_nop 0
	v_addc_co_u32_e32 v67, vcc, 0, v69, vcc
	global_load_dwordx4 v[126:129], v[66:67], off
	global_load_dwordx4 v[130:133], v[70:71], off
	v_add_co_u32_e32 v66, vcc, s80, v70
	v_lshl_add_u64 v[72:73], v[214:215], 0, s[6:7]
	s_nop 0
	v_addc_co_u32_e32 v67, vcc, 0, v71, vcc
	global_load_dwordx4 v[134:137], v[66:67], off offset:-4096
	global_load_dwordx4 v[138:141], v[66:67], off
	v_add_co_u32_e32 v66, vcc, s81, v70
	v_cvt_pk_bf16_f32 v82, v2, v3
	s_nop 0
	v_addc_co_u32_e32 v67, vcc, 0, v71, vcc
	global_load_dwordx4 v[142:145], v[66:67], off
	global_load_dwordx4 v[146:149], v[72:73], off
	v_add_co_u32_e32 v66, vcc, s97, v72
	v_cvt_pk_bf16_f32 v83, v4, v5
	s_nop 0
	v_addc_co_u32_e32 v67, vcc, 0, v73, vcc
	global_load_dwordx4 v[150:153], v[66:67], off
	ds_read_b128 v[66:69], v240
	ds_read_b128 v[86:89], v240 offset:1024
	v_cvt_pk_bf16_f32 v84, v6, v7
	v_cvt_pk_bf16_f32 v85, v8, v9
	v_cvt_pk_bf16_f32 v194, v10, v11
	v_cvt_pk_bf16_f32 v195, v12, v13
	s_waitcnt lgkmcnt(1)
	v_mfma_f32_32x32x16_bf16 v[66:81], v[66:69], v[82:85], 0
	v_cvt_pk_bf16_f32 v196, v14, v15
	v_cvt_pk_bf16_f32 v197, v16, v17
	v_cvt_pk_bf16_f32 v190, v50, v51
	v_cvt_pk_bf16_f32 v191, v52, v53
	v_cvt_pk_bf16_f32 v192, v54, v55
	v_cvt_pk_bf16_f32 v193, v56, v57
	v_cvt_pk_bf16_f32 v186, v58, v59
	s_waitcnt lgkmcnt(0)
	v_mfma_f32_32x32x16_bf16 v[66:81], v[86:89], v[194:197], v[66:81]
	ds_read_b128 v[86:89], v240 offset:2048
	v_cvt_pk_bf16_f32 v187, v60, v61
	v_cvt_pk_bf16_f32 v188, v62, v63
	v_cvt_pk_bf16_f32 v189, v64, v65
	v_cvt_pk_bf16_f32 v182, v34, v35
	v_cvt_pk_bf16_f32 v183, v36, v37
	v_cvt_pk_bf16_f32 v184, v38, v39
	s_waitcnt lgkmcnt(0)
	v_mfma_f32_32x32x16_bf16 v[66:81], v[86:89], v[190:193], v[66:81]
	ds_read_b128 v[86:89], v240 offset:3072
	v_cvt_pk_bf16_f32 v185, v40, v41
	v_cvt_pk_bf16_f32 v178, v42, v43
	v_cvt_pk_bf16_f32 v179, v44, v45
	v_cvt_pk_bf16_f32 v180, v46, v47
	v_cvt_pk_bf16_f32 v181, v48, v49
	v_cvt_pk_bf16_f32 v174, v18, v19
	s_waitcnt lgkmcnt(0)
	v_mfma_f32_32x32x16_bf16 v[66:81], v[86:89], v[186:189], v[66:81]
	ds_read_b128 v[86:89], v240 offset:4096
	v_cvt_pk_bf16_f32 v175, v20, v21
	v_cvt_pk_bf16_f32 v176, v22, v23
	v_cvt_pk_bf16_f32 v177, v24, v25
	v_cvt_pk_bf16_f32 v170, v26, v27
	v_cvt_pk_bf16_f32 v171, v28, v29
	v_cvt_pk_bf16_f32 v172, v30, v31
	s_waitcnt lgkmcnt(0)
	v_mfma_f32_32x32x16_bf16 v[66:81], v[86:89], v[182:185], v[66:81]
	ds_read_b128 v[86:89], v240 offset:5120
	v_cvt_pk_bf16_f32 v173, v32, v33
	s_waitcnt vmcnt(21)
	v_lshlrev_b32_e32 v0, 16, v226
	s_waitcnt lgkmcnt(0)
	v_mfma_f32_32x32x16_bf16 v[66:81], v[86:89], v[178:181], v[66:81]
	ds_read_b128 v[86:89], v240 offset:6144
	s_waitcnt lgkmcnt(0)
	v_mfma_f32_32x32x16_bf16 v[66:81], v[86:89], v[174:177], v[66:81]
	ds_read_b128 v[86:89], v240 offset:7168
	s_waitcnt lgkmcnt(0)
	v_mfma_f32_32x32x16_bf16 v[66:81], v[86:89], v[170:173], v[66:81]
	ds_read_b128 v[86:89], v240 offset:9216
	s_nop 10
	v_sub_f32_e32 v0, v0, v66
	v_and_b32_e32 v66, 0xffff0000, v226
	v_sub_f32_e32 v90, v66, v67
	v_lshlrev_b32_e32 v66, 16, v227
	v_sub_f32_e32 v91, v66, v68
	v_and_b32_e32 v66, 0xffff0000, v227
	v_sub_f32_e32 v92, v66, v69
	s_waitcnt vmcnt(20)
	v_lshlrev_b32_e32 v66, 16, v224
	v_sub_f32_e32 v93, v66, v70
	v_and_b32_e32 v66, 0xffff0000, v224
	v_sub_f32_e32 v94, v66, v71
	v_lshlrev_b32_e32 v66, 16, v225
	v_sub_f32_e32 v95, v66, v72
	v_and_b32_e32 v66, 0xffff0000, v225
	v_sub_f32_e32 v96, v66, v73
	s_waitcnt vmcnt(19)
	v_lshlrev_b32_e32 v66, 16, v222
	v_sub_f32_e32 v97, v66, v74
	v_and_b32_e32 v66, 0xffff0000, v222
	v_sub_f32_e32 v154, v66, v75
	v_lshlrev_b32_e32 v66, 16, v223
	v_sub_f32_e32 v155, v66, v76
	v_and_b32_e32 v66, 0xffff0000, v223
	v_sub_f32_e32 v156, v66, v77
	s_waitcnt vmcnt(18)
	v_lshlrev_b32_e32 v66, 16, v220
	v_sub_f32_e32 v157, v66, v78
	v_and_b32_e32 v66, 0xffff0000, v220
	v_sub_f32_e32 v158, v66, v79
	v_lshlrev_b32_e32 v66, 16, v221
	v_sub_f32_e32 v159, v66, v80
	v_and_b32_e32 v66, 0xffff0000, v221
	v_sub_f32_e32 v160, v66, v81
	ds_read_b128 v[66:69], v240 offset:8192
	s_waitcnt lgkmcnt(0)
	v_mfma_f32_32x32x16_bf16 v[66:81], v[66:69], v[82:85], 0
	v_cvt_pk_bf16_f32 v164, v157, v158
	v_cvt_pk_bf16_f32 v165, v159, v160
	v_cvt_pk_bf16_f32 v162, v97, v154
	v_cvt_pk_bf16_f32 v163, v155, v156
	v_cvt_pk_bf16_f32 v166, v0, v90
	v_cvt_pk_bf16_f32 v167, v91, v92
	v_cvt_pk_bf16_f32 v168, v93, v94
	v_mfma_f32_32x32x16_bf16 v[66:81], v[86:89], v[194:197], v[66:81]
	ds_read_b128 v[86:89], v240 offset:10240
	v_cvt_pk_bf16_f32 v169, v95, v96
	ds_bpermute_b32 v0, v241, v228
	v_add_u32_e32 v241, 4, v241
	s_waitcnt lgkmcnt(0)
; #define MFMA32(a, b, c) __builtin_amdgcn_mfma_f32_32x32x16_bf16((a), (b), (c), 0, 0, 0)
; DI void phaseB2(const Params& p, int bh, char* smem, int n_begin, int n_end) {
;     ...
;         for (int s = 0; s < 2; ++s) aw = MFMA32(ld16(wg + (it * 4096 + (T * 2 + s) * 512) + lo8), pack8(S[T], s), aw);
; #pragma unroll
;       for (int g = 0; g < 4; ++g) {
;         const uint2 uu = it == 0 ? (g == 0 ? pu0 : g == 1 ? pu1 : g == 2 ? pu2 : pu3) : (g == 0 ? pu4 : g == 1 ? pu5 : g == 2 ? pu6 : pu7);
;         vn[it][4 * g + 0] = __uint_as_float(uu.x << 16) - aw[4 * g + 0];
;         vn[it][4 * g + 1] = __uint_as_float(uu.x & 0xffff0000u) - aw[4 * g + 1];
;         vn[it][4 * g + 2] = __uint_as_float(uu.y << 16) - aw[4 * g + 2];
;         vn[it][4 * g + 3] = __uint_as_float(uu.y & 0xffff0000u) - aw[4 * g + 3];
;       }
;     }
;     B2_LOADU(n + 1 < 32 ? n + 1 : n);
;     bf16x8 Vb[2][2];
; #pragma unroll
;     for (int jt = 0; jt < 2; ++jt) { Vb[jt][0] = pack8(vn[jt], 0); Vb[jt][1] = pack8(vn[jt], 1); }
; #pragma unroll
;     for (int it = 0; it < 2; ++it) {
; #pragma unroll
;       for (int e = 0; e < 16; ++e) o[it][e] = 0.f;
; #pragma unroll
;       for (int T = 0; T < 4; ++T)
; #pragma unroll
;         for (int s = 0; s < 2; ++s) o[it] = MFMA32(ld16(qg + (it * 4096 + (T * 2 + s) * 512) + lo8), pack8(S[T], s), o[it]);
; #pragma unroll
;       for (int jt = 0; jt < 2; ++jt)
; #pragma unroll
;         for (int s = 0; s < 2; ++s)
;           o[it] = MFMA32(ld16(ag + (it * 2048 + (jt * 2 + s) * 512) + lo8), Vb[jt][s], o[it]);
;     }
;     const float egl = __shfl(eglv, n);
; #pragma unroll
;     for (int T = 0; T < 4; ++T) {
;       f32x16 acc;
; #pragma unroll
;       for (int e = 0; e < 16; ++e) acc[e] = S[T][e] * egl;
	v_pk_mul_f32 v[16:17], v[16:17], v[0:1] op_sel_hi:[1,0]
	v_mfma_f32_32x32x16_bf16 v[66:81], v[86:89], v[190:193], v[66:81]
	ds_read_b128 v[86:89], v240 offset:11264
	v_mul_f32_e64 v14, v14, v0
	v_mul_f32_e64 v15, v15, v0
	v_mul_f32_e64 v12, v12, v0
	v_mul_f32_e64 v13, v13, v0
	v_pk_mul_f32 v[10:11], v[10:11], v[0:1] op_sel_hi:[1,0]
	v_pk_mul_f32 v[8:9], v[8:9], v[0:1] op_sel_hi:[1,0]
	v_pk_mul_f32 v[6:7], v[6:7], v[0:1] op_sel_hi:[1,0]
	v_pk_mul_f32 v[4:5], v[4:5], v[0:1] op_sel_hi:[1,0]
	s_waitcnt lgkmcnt(0)
	v_mfma_f32_32x32x16_bf16 v[66:81], v[86:89], v[186:189], v[66:81]
	ds_read_b128 v[86:89], v240 offset:12288
	v_mul_f32_e64 v2, v2, v0
	v_mul_f32_e64 v3, v3, v0
	v_mul_f32_e64 v64, v64, v0
	v_mul_f32_e64 v65, v65, v0
	v_pk_mul_f32 v[62:63], v[62:63], v[0:1] op_sel_hi:[1,0]
	v_pk_mul_f32 v[60:61], v[60:61], v[0:1] op_sel_hi:[1,0]
	v_pk_mul_f32 v[58:59], v[58:59], v[0:1] op_sel_hi:[1,0]
	v_pk_mul_f32 v[56:57], v[56:57], v[0:1] op_sel_hi:[1,0]
	s_waitcnt lgkmcnt(0)
	v_mfma_f32_32x32x16_bf16 v[66:81], v[86:89], v[182:185], v[66:81]
	ds_read_b128 v[86:89], v240 offset:13312
	v_mul_f32_e64 v54, v54, v0
	v_mul_f32_e64 v55, v55, v0
	v_mul_f32_e64 v52, v52, v0
	v_mul_f32_e64 v53, v53, v0
	v_pk_mul_f32 v[50:51], v[50:51], v[0:1] op_sel_hi:[1,0]
	v_pk_mul_f32 v[48:49], v[48:49], v[0:1] op_sel_hi:[1,0]
	v_pk_mul_f32 v[46:47], v[46:47], v[0:1] op_sel_hi:[1,0]
	v_pk_mul_f32 v[44:45], v[44:45], v[0:1] op_sel_hi:[1,0]
	s_waitcnt lgkmcnt(0)
	v_mfma_f32_32x32x16_bf16 v[66:81], v[86:89], v[178:181], v[66:81]
	ds_read_b128 v[86:89], v240 offset:14336
	v_mul_f32_e64 v42, v42, v0
	v_mul_f32_e64 v43, v43, v0
	v_mul_f32_e64 v40, v40, v0
	v_mul_f32_e64 v41, v41, v0
	v_pk_mul_f32 v[38:39], v[38:39], v[0:1] op_sel_hi:[1,0]
	v_pk_mul_f32 v[36:37], v[36:37], v[0:1] op_sel_hi:[1,0]
	v_pk_mul_f32 v[34:35], v[34:35], v[0:1] op_sel_hi:[1,0]
	v_pk_mul_f32 v[32:33], v[32:33], v[0:1] op_sel_hi:[1,0]
	s_waitcnt lgkmcnt(0)
	v_mfma_f32_32x32x16_bf16 v[66:81], v[86:89], v[174:177], v[66:81]
	ds_read_b128 v[86:89], v240 offset:15360
	v_mul_f32_e64 v30, v30, v0
	v_mul_f32_e64 v31, v31, v0
	v_mul_f32_e64 v28, v28, v0
	v_mul_f32_e64 v29, v29, v0
	v_pk_mul_f32 v[26:27], v[26:27], v[0:1] op_sel_hi:[1,0]
	v_pk_mul_f32 v[24:25], v[24:25], v[0:1] op_sel_hi:[1,0]
	v_pk_mul_f32 v[22:23], v[22:23], v[0:1] op_sel_hi:[1,0]
	v_pk_mul_f32 v[20:21], v[20:21], v[0:1] op_sel_hi:[1,0]
	s_waitcnt lgkmcnt(0)
	v_mfma_f32_32x32x16_bf16 v[66:81], v[86:89], v[170:173], v[66:81]
	s_waitcnt vmcnt(17)
	v_lshlrev_b32_e32 v86, 16, v206
	v_and_b32_e32 v87, 0xffff0000, v206
	v_mul_f32_e64 v18, v18, v0
	v_mul_f32_e64 v19, v19, v0
	s_nop 6
	v_pk_add_f32 v[66:67], v[86:87], v[66:67] neg_lo:[0,1] neg_hi:[0,1]
	v_lshlrev_b32_e32 v86, 16, v207
	v_and_b32_e32 v87, 0xffff0000, v207
	v_pk_add_f32 v[68:69], v[86:87], v[68:69] neg_lo:[0,1] neg_hi:[0,1]
	s_waitcnt vmcnt(16)
	v_lshlrev_b32_e32 v86, 16, v204
	v_and_b32_e32 v87, 0xffff0000, v204
	v_pk_add_f32 v[70:71], v[86:87], v[70:71] neg_lo:[0,1] neg_hi:[0,1]
	v_lshlrev_b32_e32 v86, 16, v205
	v_and_b32_e32 v87, 0xffff0000, v205
	v_pk_add_f32 v[72:73], v[86:87], v[72:73] neg_lo:[0,1] neg_hi:[0,1]
	s_waitcnt vmcnt(15)
	v_lshlrev_b32_e32 v86, 16, v202
	v_and_b32_e32 v87, 0xffff0000, v202
	v_pk_add_f32 v[74:75], v[86:87], v[74:75] neg_lo:[0,1] neg_hi:[0,1]
	v_lshlrev_b32_e32 v86, 16, v203
	v_and_b32_e32 v87, 0xffff0000, v203
	v_pk_add_f32 v[76:77], v[86:87], v[76:77] neg_lo:[0,1] neg_hi:[0,1]
	s_waitcnt vmcnt(14)
	v_lshlrev_b32_e32 v86, 16, v200
	v_and_b32_e32 v87, 0xffff0000, v200
	v_pk_add_f32 v[78:79], v[86:87], v[78:79] neg_lo:[0,1] neg_hi:[0,1]
	v_lshlrev_b32_e32 v86, 16, v201
	v_and_b32_e32 v87, 0xffff0000, v201
	v_pk_add_f32 v[80:81], v[86:87], v[80:81] neg_lo:[0,1] neg_hi:[0,1]
	v_lshl_add_u64 v[86:87], v[216:217], 0, s[4:5]
	global_load_dwordx2 v[226:227], v[86:87], off
	global_load_dwordx2 v[224:225], v[86:87], off offset:512
	global_load_dwordx2 v[222:223], v[86:87], off offset:1024
	global_load_dwordx2 v[220:221], v[86:87], off offset:1536
	global_load_dwordx2 v[206:207], v[86:87], off offset:2048
	global_load_dwordx2 v[204:205], v[86:87], off offset:2560
	global_load_dwordx2 v[202:203], v[86:87], off offset:3072
	global_load_dwordx2 v[200:201], v[86:87], off offset:3584
	v_cvt_pk_bf16_f32 v158, v66, v67
	v_cvt_pk_bf16_f32 v159, v68, v69
	ds_read_b128 v[66:69], v240 offset:16384
	ds_read_b128 v[86:89], v240 offset:17408
	v_cvt_pk_bf16_f32 v160, v70, v71
	v_cvt_pk_bf16_f32 v161, v72, v73
	v_cvt_pk_bf16_f32 v154, v74, v75
	v_cvt_pk_bf16_f32 v155, v76, v77
	v_cvt_pk_bf16_f32 v156, v78, v79
	v_cvt_pk_bf16_f32 v157, v80, v81
	s_waitcnt lgkmcnt(1)
	v_mfma_f32_32x32x16_bf16 v[66:81], v[66:69], v[82:85], 0
	ds_read_b128 v[242:245], v240 offset:25600
	s_waitcnt lgkmcnt(1)
	v_mfma_f32_32x32x16_bf16 v[66:81], v[86:89], v[194:197], v[66:81]
	ds_read_b128 v[86:89], v240 offset:18432
	s_waitcnt lgkmcnt(0)
	v_mfma_f32_32x32x16_bf16 v[66:81], v[86:89], v[190:193], v[66:81]
	ds_read_b128 v[86:89], v240 offset:19456
	s_waitcnt lgkmcnt(0)
	v_mfma_f32_32x32x16_bf16 v[66:81], v[86:89], v[186:189], v[66:81]
	ds_read_b128 v[86:89], v240 offset:20480
	s_waitcnt lgkmcnt(0)
	v_mfma_f32_32x32x16_bf16 v[66:81], v[86:89], v[182:185], v[66:81]
	ds_read_b128 v[86:89], v240 offset:21504
	s_waitcnt lgkmcnt(0)
	v_mfma_f32_32x32x16_bf16 v[66:81], v[86:89], v[178:181], v[66:81]
	ds_read_b128 v[86:89], v240 offset:22528
	s_waitcnt lgkmcnt(0)
	v_mfma_f32_32x32x16_bf16 v[66:81], v[86:89], v[174:177], v[66:81]
	ds_read_b128 v[86:89], v240 offset:23552
	s_waitcnt lgkmcnt(0)
	v_mfma_f32_32x32x16_bf16 v[66:81], v[86:89], v[170:173], v[66:81]
	ds_read_b128 v[86:89], v240 offset:49152
	s_waitcnt lgkmcnt(0)
; #define MFMA32(a, b, c) __builtin_amdgcn_mfma_f32_32x32x16_bf16((a), (b), (c), 0, 0, 0)
; #define B2_STORE() do { uint4* l_ = (uint4*)L + tid; \
;     l_[0] = pw0; l_[256] = pw1; l_[512] = pw2; l_[768] = pw3; l_[1024] = pq0; l_[1280] = pq1; l_[1536] = pq2; l_[1792] = pq3; \
;     l_[2048] = pk0; l_[2304] = pk1; l_[2560] = pk2; l_[2816] = pk3; l_[3072] = pa0; l_[3328] = pa1; } while (0)
; DI void phaseB2(const Params& p, int bh, char* smem, int n_begin, int n_end) {
;     ...
;         for (int s = 0; s < 2; ++s) o[it] = MFMA32(ld16(qg + (it * 4096 + (T * 2 + s) * 512) + lo8), pack8(S[T], s), o[it]);
; #pragma unroll
;       for (int jt = 0; jt < 2; ++jt)
; #pragma unroll
;         for (int s = 0; s < 2; ++s)
;           o[it] = MFMA32(ld16(ag + (it * 2048 + (jt * 2 + s) * 512) + lo8), Vb[jt][s], o[it]);
;     }
;     const float egl = __shfl(eglv, n);
; #pragma unroll
;     for (int T = 0; T < 4; ++T) {
;       f32x16 acc;
; #pragma unroll
;       for (int e = 0; e < 16; ++e) acc[e] = S[T][e] * egl;
; #pragma unroll
;       for (int jt = 0; jt < 2; ++jt)
; #pragma unroll
;         for (int s = 0; s < 2; ++s)
;           acc = MFMA32(ld16(kg + (T * 2048 + (jt * 2 + s) * 512) + lo8), Vb[jt][s], acc);
;       S[T] = acc;
;     }
;     asm volatile("s_waitcnt lgkmcnt(0)\n\ts_barrier" ::: "memory");
;     B2_STORE();
	v_mfma_f32_32x32x16_bf16 v[66:81], v[86:89], v[166:169], v[66:81]
	ds_read_b128 v[86:89], v240 offset:50176
	s_waitcnt lgkmcnt(0)
	v_mfma_f32_32x32x16_bf16 v[66:81], v[86:89], v[162:165], v[66:81]
	ds_read_b128 v[86:89], v240 offset:51200
	s_waitcnt lgkmcnt(0)
	v_mfma_f32_32x32x16_bf16 v[66:81], v[86:89], v[158:161], v[66:81]
	ds_read_b128 v[86:89], v240 offset:52224
	s_waitcnt lgkmcnt(0)
	v_mfma_f32_32x32x16_bf16 v[66:81], v[86:89], v[154:157], v[66:81]
	ds_read_b128 v[86:89], v240 offset:24576
	s_waitcnt lgkmcnt(0)
	v_mfma_f32_32x32x16_bf16 v[82:97], v[86:89], v[82:85], 0
	s_nop 8
	v_cvt_pk_bf16_f32 v0, v66, s0
	v_mfma_f32_32x32x16_bf16 v[82:97], v[242:245], v[194:197], v[82:97]
	ds_read_b128 v[194:197], v240 offset:26624
	s_waitcnt lgkmcnt(0)
	v_mfma_f32_32x32x16_bf16 v[82:97], v[194:197], v[190:193], v[82:97]
	ds_read_b128 v[190:193], v240 offset:27648
	s_waitcnt lgkmcnt(0)
	v_mfma_f32_32x32x16_bf16 v[82:97], v[190:193], v[186:189], v[82:97]
	ds_read_b128 v[186:189], v240 offset:28672
	s_waitcnt lgkmcnt(0)
	v_mfma_f32_32x32x16_bf16 v[82:97], v[186:189], v[182:185], v[82:97]
	ds_read_b128 v[182:185], v240 offset:29696
	s_waitcnt lgkmcnt(0)
	v_mfma_f32_32x32x16_bf16 v[82:97], v[182:185], v[178:181], v[82:97]
	ds_read_b128 v[178:181], v240 offset:30720
	s_waitcnt lgkmcnt(0)
	v_mfma_f32_32x32x16_bf16 v[82:97], v[178:181], v[174:177], v[82:97]
	ds_read_b128 v[174:177], v240 offset:31744
	s_waitcnt lgkmcnt(0)
	v_mfma_f32_32x32x16_bf16 v[82:97], v[174:177], v[170:173], v[82:97]
	ds_read_b128 v[170:173], v240 offset:53248
	s_waitcnt lgkmcnt(0)
	v_mfma_f32_32x32x16_bf16 v[82:97], v[170:173], v[166:169], v[82:97]
	ds_read_b128 v[170:173], v240 offset:54272
	s_waitcnt lgkmcnt(0)
	v_mfma_f32_32x32x16_bf16 v[82:97], v[170:173], v[162:165], v[82:97]
	ds_read_b128 v[170:173], v240 offset:55296
	s_waitcnt lgkmcnt(0)
	v_mfma_f32_32x32x16_bf16 v[82:97], v[170:173], v[158:161], v[82:97]
	ds_read_b128 v[170:173], v240 offset:56320
	s_waitcnt lgkmcnt(0)
	v_mfma_f32_32x32x16_bf16 v[82:97], v[170:173], v[154:157], v[82:97]
	ds_read_b128 v[170:173], v240 offset:32768
	s_waitcnt lgkmcnt(0)
	v_mfma_f32_32x32x16_bf16 v[2:17], v[170:173], v[166:169], v[2:17]
	ds_read_b128 v[170:173], v240 offset:33792
	s_waitcnt lgkmcnt(0)
	v_mfma_f32_32x32x16_bf16 v[2:17], v[170:173], v[162:165], v[2:17]
	ds_read_b128 v[170:173], v240 offset:34816
	s_waitcnt lgkmcnt(0)
	v_mfma_f32_32x32x16_bf16 v[2:17], v[170:173], v[158:161], v[2:17]
	ds_read_b128 v[170:173], v240 offset:35840
	s_waitcnt lgkmcnt(0)
	v_mfma_f32_32x32x16_bf16 v[2:17], v[170:173], v[154:157], v[2:17]
	ds_read_b128 v[170:173], v240 offset:36864
	s_waitcnt lgkmcnt(0)
	v_mfma_f32_32x32x16_bf16 v[50:65], v[170:173], v[166:169], v[50:65]
	ds_read_b128 v[170:173], v240 offset:37888
	s_waitcnt lgkmcnt(0)
	v_mfma_f32_32x32x16_bf16 v[50:65], v[170:173], v[162:165], v[50:65]
	ds_read_b128 v[170:173], v240 offset:38912
	s_waitcnt lgkmcnt(0)
	v_mfma_f32_32x32x16_bf16 v[50:65], v[170:173], v[158:161], v[50:65]
	ds_read_b128 v[170:173], v240 offset:39936
	s_waitcnt lgkmcnt(0)
	v_mfma_f32_32x32x16_bf16 v[50:65], v[170:173], v[154:157], v[50:65]
	ds_read_b128 v[170:173], v240 offset:40960
	s_waitcnt lgkmcnt(0)
	v_mfma_f32_32x32x16_bf16 v[34:49], v[170:173], v[166:169], v[34:49]
	ds_read_b128 v[170:173], v240 offset:41984
	s_waitcnt lgkmcnt(0)
	v_mfma_f32_32x32x16_bf16 v[34:49], v[170:173], v[162:165], v[34:49]
	ds_read_b128 v[170:173], v240 offset:43008
	s_waitcnt lgkmcnt(0)
	v_mfma_f32_32x32x16_bf16 v[34:49], v[170:173], v[158:161], v[34:49]
	ds_read_b128 v[170:173], v240 offset:44032
	s_waitcnt lgkmcnt(0)
	v_mfma_f32_32x32x16_bf16 v[34:49], v[170:173], v[154:157], v[34:49]
	ds_read_b128 v[170:173], v240 offset:45056
	s_waitcnt lgkmcnt(0)
	v_mfma_f32_32x32x16_bf16 v[18:33], v[170:173], v[166:169], v[18:33]
	ds_read_b128 v[166:169], v240 offset:46080
	s_waitcnt lgkmcnt(0)
	v_mfma_f32_32x32x16_bf16 v[18:33], v[166:169], v[162:165], v[18:33]
	ds_read_b128 v[162:165], v240 offset:47104
	s_waitcnt lgkmcnt(0)
	v_mfma_f32_32x32x16_bf16 v[18:33], v[162:165], v[158:161], v[18:33]
	ds_read_b128 v[158:161], v240 offset:48128
	s_waitcnt lgkmcnt(0)
	s_barrier
	s_waitcnt vmcnt(21)
	ds_write_b128 v229, v[98:101]
	s_waitcnt vmcnt(20)
	ds_write_b128 v229, v[102:105] offset:4096
	s_waitcnt vmcnt(19)
	ds_write_b128 v229, v[106:109] offset:8192
	s_waitcnt vmcnt(18)
	ds_write_b128 v229, v[110:113] offset:12288
	s_waitcnt vmcnt(17)
	ds_write_b128 v229, v[114:117] offset:16384
	s_waitcnt vmcnt(16)
	ds_write_b128 v229, v[118:121] offset:20480
	s_waitcnt vmcnt(15)
	ds_write_b128 v229, v[122:125] offset:24576
	s_waitcnt vmcnt(14)
	ds_write_b128 v229, v[126:129] offset:28672
	s_waitcnt vmcnt(13)
	ds_write_b128 v229, v[130:133] offset:32768
	s_waitcnt vmcnt(12)
	ds_write_b128 v229, v[134:137] offset:36864
	s_waitcnt vmcnt(11)
	ds_write_b128 v229, v[138:141] offset:40960
	s_waitcnt vmcnt(10)
	ds_write_b128 v229, v[142:145] offset:45056
	s_waitcnt vmcnt(9)
	ds_write_b128 v229, v[146:149] offset:49152
	s_waitcnt vmcnt(8)
	ds_write_b128 v229, v[150:153] offset:53248
	v_lshl_add_u64 v[98:99], v[218:219], 0, s[0:1]
	s_waitcnt lgkmcnt(0)
	s_barrier
; #define MFMA32(a, b, c) __builtin_amdgcn_mfma_f32_32x32x16_bf16((a), (b), (c), 0, 0, 0)
; DI bf16_t f2bf(float x) { return (bf16_t)(pack2(x, 0.f) & 0xffffu); }
; DI int crow(int reg, int hh) { return (reg & 3) + 8 * (reg >> 2) + 4 * hh; }
; #define B2_STORE() do { uint4* l_ = (uint4*)L + tid; \
;     l_[0] = pw0; l_[256] = pw1; l_[512] = pw2; l_[768] = pw3; l_[1024] = pq0; l_[1280] = pq1; l_[1536] = pq2; l_[1792] = pq3; \
;     l_[2048] = pk0; l_[2304] = pk1; l_[2560] = pk2; l_[2816] = pk3; l_[3072] = pa0; l_[3328] = pa1; } while (0)
; DI void phaseB2(const Params& p, int bh, char* smem, int n_begin, int n_end) {
;     ...
;           acc = MFMA32(ld16(kg + (T * 2048 + (jt * 2 + s) * 512) + lo8), Vb[jt][s], acc);
;       S[T] = acc;
;     }
;     asm volatile("s_waitcnt lgkmcnt(0)\n\ts_barrier" ::: "memory");
;     B2_STORE();
;     asm volatile("s_waitcnt lgkmcnt(0)\n\ts_barrier" ::: "memory");
;     {
;       bf16_t* og = p.ob + (size_t)(b * SEQ + n * 64) * 512 + hd * 128 + v0 + r;
; #pragma unroll
;       for (int it = 0; it < 2; ++it)
; #pragma unroll
;         for (int e = 0; e < 16; ++e) og[(size_t)(it * 32 + crow(e, hh)) * 512] = f2bf(o[it][e]);
;     }
;   }
;   if (n_end < 32) {
; #pragma unroll
;     for (int T = 0; T < 4; ++T)
; #pragma unroll
;       for (int q4 = 0; q4 < 4; ++q4)
;         *(float4*)(sst + T * 16 + q4 * 4) = make_float4(S[T][q4 * 4], S[T][q4 * 4 + 1], S[T][q4 * 4 + 2], S[T][q4 * 4 + 3]);
;   }
;   __syncthreads();
	global_store_short v[98:99], v0, off
	v_cvt_pk_bf16_f32 v0, v67, s0
	global_store_short v[98:99], v0, off offset:1024
	v_cvt_pk_bf16_f32 v0, v68, s0
	global_store_short v[98:99], v0, off offset:2048
	v_cvt_pk_bf16_f32 v0, v69, s0
	v_add_co_u32_e32 v66, vcc, s80, v98
	global_store_short v[98:99], v0, off offset:3072
	v_cvt_pk_bf16_f32 v0, v70, s0
	v_addc_co_u32_e32 v67, vcc, 0, v99, vcc
	global_store_short v[66:67], v0, off
	v_cvt_pk_bf16_f32 v0, v71, s0
	global_store_short v[66:67], v0, off offset:1024
	v_cvt_pk_bf16_f32 v0, v72, s0
	global_store_short v[66:67], v0, off offset:2048
	v_cvt_pk_bf16_f32 v0, v73, s0
	global_store_short v[66:67], v0, off offset:3072
	v_add_co_u32_e32 v66, vcc, s95, v98
	v_cvt_pk_bf16_f32 v0, v74, s0
	s_nop 0
	v_addc_co_u32_e32 v67, vcc, 0, v99, vcc
	global_store_short v[66:67], v0, off
	v_cvt_pk_bf16_f32 v0, v75, s0
	global_store_short v[66:67], v0, off offset:1024
	v_cvt_pk_bf16_f32 v0, v76, s0
	global_store_short v[66:67], v0, off offset:2048
	v_cvt_pk_bf16_f32 v0, v77, s0
	global_store_short v[66:67], v0, off offset:3072
	v_add_co_u32_e32 v66, vcc, s8, v98
	v_cvt_pk_bf16_f32 v0, v78, s0
	s_nop 0
	v_addc_co_u32_e32 v67, vcc, 0, v99, vcc
	global_store_short v[66:67], v0, off
	v_cvt_pk_bf16_f32 v0, v79, s0
	global_store_short v[66:67], v0, off offset:1024
	v_cvt_pk_bf16_f32 v0, v80, s0
	global_store_short v[66:67], v0, off offset:2048
	v_cvt_pk_bf16_f32 v0, v81, s0
	global_store_short v[66:67], v0, off offset:3072
	v_add_co_u32_e32 v66, vcc, s51, v98
	v_cvt_pk_bf16_f32 v0, v82, s0
	s_nop 0
	v_addc_co_u32_e32 v67, vcc, 0, v99, vcc
	global_store_short v[66:67], v0, off
	v_cvt_pk_bf16_f32 v0, v83, s0
	global_store_short v[66:67], v0, off offset:1024
	v_cvt_pk_bf16_f32 v0, v84, s0
	global_store_short v[66:67], v0, off offset:2048
	v_cvt_pk_bf16_f32 v0, v85, s0
	global_store_short v[66:67], v0, off offset:3072
	v_add_co_u32_e32 v66, vcc, s9, v98
	v_cvt_pk_bf16_f32 v0, v86, s0
	s_nop 0
	v_addc_co_u32_e32 v67, vcc, 0, v99, vcc
	global_store_short v[66:67], v0, off
	v_cvt_pk_bf16_f32 v0, v87, s0
	global_store_short v[66:67], v0, off offset:1024
	v_cvt_pk_bf16_f32 v0, v88, s0
	global_store_short v[66:67], v0, off offset:2048
	v_cvt_pk_bf16_f32 v0, v89, s0
	global_store_short v[66:67], v0, off offset:3072
	v_add_co_u32_e32 v66, vcc, s10, v98
	v_cvt_pk_bf16_f32 v0, v90, s0
	s_nop 0
	v_addc_co_u32_e32 v67, vcc, 0, v99, vcc
	global_store_short v[66:67], v0, off
	v_cvt_pk_bf16_f32 v0, v91, s0
	global_store_short v[66:67], v0, off offset:1024
	v_cvt_pk_bf16_f32 v0, v92, s0
	s_waitcnt lgkmcnt(14)
	v_mfma_f32_32x32x16_bf16 v[18:33], v[158:161], v[154:157], v[18:33]
	global_store_short v[66:67], v0, off offset:2048
	v_cvt_pk_bf16_f32 v0, v93, s0
	global_store_short v[66:67], v0, off offset:3072
	v_add_co_u32_e32 v66, vcc, s11, v98
	v_cvt_pk_bf16_f32 v0, v94, s0
	s_nop 0
	v_addc_co_u32_e32 v67, vcc, 0, v99, vcc
	global_store_short v[66:67], v0, off
	v_cvt_pk_bf16_f32 v0, v95, s0
	global_store_short v[66:67], v0, off offset:1024
	v_cvt_pk_bf16_f32 v0, v96, s0
	global_store_short v[66:67], v0, off offset:2048
	v_cvt_pk_bf16_f32 v0, v97, s0
	s_add_u32 s0, s0, 0x10000
	s_addc_u32 s1, s1, 0
	s_add_i32 s2, s2, 4
	s_cmp_lg_u32 s0, 0x130000
	global_store_short v[66:67], v0, off offset:3072
	s_cbranch_scc1 .LBB0_1770
	s_setprio 0
	v_readlane_b32 s0, v251, 12
	v_lshlrev_b64 v[66:67], 8, v[198:199]
	v_readlane_b32 s1, v251, 13
	s_nop 1
	v_lshl_add_u64 v[66:67], s[0:1], 0, v[66:67]
	global_store_dwordx4 v[66:67], v[2:5], off
	global_store_dwordx4 v[66:67], v[6:9], off offset:16
	global_store_dwordx4 v[66:67], v[10:13], off offset:32
	global_store_dwordx4 v[66:67], v[14:17], off offset:48
	global_store_dwordx4 v[66:67], v[50:53], off offset:64
	global_store_dwordx4 v[66:67], v[54:57], off offset:80
	global_store_dwordx4 v[66:67], v[58:61], off offset:96
	global_store_dwordx4 v[66:67], v[62:65], off offset:112
	global_store_dwordx4 v[66:67], v[34:37], off offset:128
	global_store_dwordx4 v[66:67], v[38:41], off offset:144
	global_store_dwordx4 v[66:67], v[42:45], off offset:160
	global_store_dwordx4 v[66:67], v[46:49], off offset:176
	global_store_dwordx4 v[66:67], v[18:21], off offset:192
	global_store_dwordx4 v[66:67], v[22:25], off offset:208
	global_store_dwordx4 v[66:67], v[26:29], off offset:224
	global_store_dwordx4 v[66:67], v[30:33], off offset:240
	s_waitcnt lgkmcnt(0)
	s_barrier

; #define MFMA32(a, b, c) __builtin_amdgcn_mfma_f32_32x32x16_bf16((a), (b), (c), 0, 0, 0)
; #define B2_STORE() do { uint4* l_ = (uint4*)L + tid; \
;     l_[0] = pw0; l_[256] = pw1; l_[512] = pw2; l_[768] = pw3; l_[1024] = pq0; l_[1280] = pq1; l_[1536] = pq2; l_[1792] = pq3; \
;     l_[2048] = pk0; l_[2304] = pk1; l_[2560] = pk2; l_[2816] = pk3; l_[3072] = pa0; l_[3328] = pa1; } while (0)
; DI void phaseB2(const Params& p, int bh, char* smem, int n_begin, int n_end) {
;     ...
;   __syncthreads();
;   B2_LOAD(n_begin);
;   B2_LOADU(n_begin);
;   B2_STORE();
;   __syncthreads();
; #pragma unroll 1
;   for (int n = n_begin; n < n_end; ++n) {
;     B2_LOAD(n + 1 < 32 ? n + 1 : n);
;     f32x16 vn[2], o[2];
; #pragma unroll
;     for (int it = 0; it < 2; ++it) {
;       f32x16 aw;
; #pragma unroll
;       for (int e = 0; e < 16; ++e) aw[e] = 0.f;
; #pragma unroll
;       for (int T = 0; T < 4; ++T)
; #pragma unroll
;         for (int s = 0; s < 2; ++s) aw = MFMA32(ld16(wg + (it * 4096 + (T * 2 + s) * 512) + lo8), pack8(S[T], s), aw);
; #pragma unroll
;       for (int g = 0; g < 4; ++g) {
;         const uint2 uu = it == 0 ? (g == 0 ? pu0 : g == 1 ? pu1 : g == 2 ? pu2 : pu3) : (g == 0 ? pu4 : g == 1 ? pu5 : g == 2 ? pu6 : pu7);
;         vn[it][4 * g + 0] = __uint_as_float(uu.x << 16) - aw[4 * g + 0];
;         vn[it][4 * g + 1] = __uint_as_float(uu.x & 0xffff0000u) - aw[4 * g + 1];
;         vn[it][4 * g + 2] = __uint_as_float(uu.y << 16) - aw[4 * g + 2];
;         vn[it][4 * g + 3] = __uint_as_float(uu.y & 0xffff0000u) - aw[4 * g + 3];
;       }
;     }
;     B2_LOADU(n + 1 < 32 ? n + 1 : n);
;     bf16x8 Vb[2][2];
; #pragma unroll
;     for (int jt = 0; jt < 2; ++jt) { Vb[jt][0] = pack8(vn[jt], 0); Vb[jt][1] = pack8(vn[jt], 1); }
; #pragma unroll
;     for (int it = 0; it < 2; ++it) {
; #pragma unroll
;       for (int e = 0; e < 16; ++e) o[it][e] = 0.f;
; #pragma unroll
;       for (int T = 0; T < 4; ++T)
; #pragma unroll
;         for (int s = 0; s < 2; ++s) o[it] = MFMA32(ld16(qg + (it * 4096 + (T * 2 + s) * 512) + lo8), pack8(S[T], s), o[it]);
; #pragma unroll
;       for (int jt = 0; jt < 2; ++jt)
; #pragma unroll
;         for (int s = 0; s < 2; ++s)
;           o[it] = MFMA32(ld16(ag + (it * 2048 + (jt * 2 + s) * 512) + lo8), Vb[jt][s], o[it]);
;     }
;     const float egl = __shfl(eglv, n);
.LBB0_1774:
	s_setprio 3
	s_ashr_i32 s3, s2, 31
	s_lshl_b64 s[6:7], s[2:3], 14
	v_lshl_add_u64 v[66:67], v[208:209], 0, s[6:7]
	v_add_co_u32_e32 v74, vcc, s80, v66
	global_load_dwordx4 v[98:101], v[66:67], off
	s_nop 0
	v_addc_co_u32_e32 v75, vcc, 0, v67, vcc
	v_add_co_u32_e32 v66, vcc, s81, v66
	v_lshl_add_u64 v[68:69], v[210:211], 0, s[6:7]
	s_nop 0
	v_addc_co_u32_e32 v67, vcc, 0, v67, vcc
	global_load_dwordx4 v[102:105], v[74:75], off offset:-4096
	global_load_dwordx4 v[106:109], v[74:75], off
	global_load_dwordx4 v[110:113], v[66:67], off
	global_load_dwordx4 v[114:117], v[68:69], off
	v_add_co_u32_e32 v66, vcc, s80, v68
	v_lshl_add_u64 v[70:71], v[212:213], 0, s[6:7]
	s_nop 0
	v_addc_co_u32_e32 v67, vcc, 0, v69, vcc
	global_load_dwordx4 v[118:121], v[66:67], off offset:-4096
	global_load_dwordx4 v[122:125], v[66:67], off
	v_add_co_u32_e32 v66, vcc, s81, v68
	s_lshl_b64 s[10:11], s[2:3], 13
	s_nop 0
	v_addc_co_u32_e32 v67, vcc, 0, v69, vcc
	global_load_dwordx4 v[126:129], v[66:67], off
	global_load_dwordx4 v[130:133], v[70:71], off
	v_add_co_u32_e32 v66, vcc, s80, v70
	v_lshl_add_u64 v[72:73], v[214:215], 0, s[10:11]
	s_nop 0
	v_addc_co_u32_e32 v67, vcc, 0, v71, vcc
	global_load_dwordx4 v[134:137], v[66:67], off offset:-4096
	global_load_dwordx4 v[138:141], v[66:67], off
	v_add_co_u32_e32 v66, vcc, s81, v70
	v_cvt_pk_bf16_f32 v82, v2, v3
	s_nop 0
	v_addc_co_u32_e32 v67, vcc, 0, v71, vcc
	global_load_dwordx4 v[142:145], v[66:67], off
	global_load_dwordx4 v[146:149], v[72:73], off
	v_add_co_u32_e32 v66, vcc, s97, v72
	v_cvt_pk_bf16_f32 v83, v4, v5
	s_nop 0
	v_addc_co_u32_e32 v67, vcc, 0, v73, vcc
	global_load_dwordx4 v[150:153], v[66:67], off
	ds_read_b128 v[66:69], v240
	ds_read_b128 v[86:89], v240 offset:1024
	v_cvt_pk_bf16_f32 v84, v6, v7
	v_cvt_pk_bf16_f32 v85, v8, v9
	v_cvt_pk_bf16_f32 v194, v10, v11
	v_cvt_pk_bf16_f32 v195, v12, v13
	s_waitcnt lgkmcnt(1)
	v_mfma_f32_32x32x16_bf16 v[66:81], v[66:69], v[82:85], 0
	v_cvt_pk_bf16_f32 v196, v14, v15
	v_cvt_pk_bf16_f32 v197, v16, v17
	v_cvt_pk_bf16_f32 v190, v50, v51
	v_cvt_pk_bf16_f32 v191, v52, v53
	v_cvt_pk_bf16_f32 v192, v54, v55
	v_cvt_pk_bf16_f32 v193, v56, v57
	v_cvt_pk_bf16_f32 v186, v58, v59
	s_waitcnt lgkmcnt(0)
	v_mfma_f32_32x32x16_bf16 v[66:81], v[86:89], v[194:197], v[66:81]
	ds_read_b128 v[86:89], v240 offset:2048
	v_cvt_pk_bf16_f32 v187, v60, v61
	v_cvt_pk_bf16_f32 v188, v62, v63
	v_cvt_pk_bf16_f32 v189, v64, v65
	v_cvt_pk_bf16_f32 v182, v34, v35
	v_cvt_pk_bf16_f32 v183, v36, v37
	v_cvt_pk_bf16_f32 v184, v38, v39
	s_waitcnt lgkmcnt(0)
	v_mfma_f32_32x32x16_bf16 v[66:81], v[86:89], v[190:193], v[66:81]
	ds_read_b128 v[86:89], v240 offset:3072
	v_cvt_pk_bf16_f32 v185, v40, v41
	v_cvt_pk_bf16_f32 v178, v42, v43
	v_cvt_pk_bf16_f32 v179, v44, v45
	v_cvt_pk_bf16_f32 v180, v46, v47
	v_cvt_pk_bf16_f32 v181, v48, v49
	v_cvt_pk_bf16_f32 v174, v18, v19
	s_waitcnt lgkmcnt(0)
	v_mfma_f32_32x32x16_bf16 v[66:81], v[86:89], v[186:189], v[66:81]
	ds_read_b128 v[86:89], v240 offset:4096
	v_cvt_pk_bf16_f32 v175, v20, v21
	v_cvt_pk_bf16_f32 v176, v22, v23
	v_cvt_pk_bf16_f32 v177, v24, v25
	v_cvt_pk_bf16_f32 v170, v26, v27
	v_cvt_pk_bf16_f32 v171, v28, v29
	v_cvt_pk_bf16_f32 v172, v30, v31
	s_waitcnt lgkmcnt(0)
	v_mfma_f32_32x32x16_bf16 v[66:81], v[86:89], v[182:185], v[66:81]
	ds_read_b128 v[86:89], v240 offset:5120
	v_cvt_pk_bf16_f32 v173, v32, v33
	s_waitcnt vmcnt(21)
	v_lshlrev_b32_e32 v0, 16, v226
	s_waitcnt lgkmcnt(0)
	v_mfma_f32_32x32x16_bf16 v[66:81], v[86:89], v[178:181], v[66:81]
	ds_read_b128 v[86:89], v240 offset:6144
	s_waitcnt lgkmcnt(0)
	v_mfma_f32_32x32x16_bf16 v[66:81], v[86:89], v[174:177], v[66:81]
	ds_read_b128 v[86:89], v240 offset:7168
	s_waitcnt lgkmcnt(0)
	v_mfma_f32_32x32x16_bf16 v[66:81], v[86:89], v[170:173], v[66:81]
	ds_read_b128 v[86:89], v240 offset:9216
	s_nop 10
	v_sub_f32_e32 v0, v0, v66
	v_and_b32_e32 v66, 0xffff0000, v226
	v_sub_f32_e32 v90, v66, v67
	v_lshlrev_b32_e32 v66, 16, v227
	v_sub_f32_e32 v91, v66, v68
	v_and_b32_e32 v66, 0xffff0000, v227
	v_sub_f32_e32 v92, v66, v69
	s_waitcnt vmcnt(20)
	v_lshlrev_b32_e32 v66, 16, v224
	v_sub_f32_e32 v93, v66, v70
	v_and_b32_e32 v66, 0xffff0000, v224
	v_sub_f32_e32 v94, v66, v71
	v_lshlrev_b32_e32 v66, 16, v225
	v_sub_f32_e32 v95, v66, v72
	v_and_b32_e32 v66, 0xffff0000, v225
	v_sub_f32_e32 v96, v66, v73
	s_waitcnt vmcnt(19)
	v_lshlrev_b32_e32 v66, 16, v222
	v_sub_f32_e32 v97, v66, v74
	v_and_b32_e32 v66, 0xffff0000, v222
	v_sub_f32_e32 v154, v66, v75
	v_lshlrev_b32_e32 v66, 16, v223
	v_sub_f32_e32 v155, v66, v76
	v_and_b32_e32 v66, 0xffff0000, v223
	v_sub_f32_e32 v156, v66, v77
	s_waitcnt vmcnt(18)
	v_lshlrev_b32_e32 v66, 16, v220
	v_sub_f32_e32 v157, v66, v78
	v_and_b32_e32 v66, 0xffff0000, v220
	v_sub_f32_e32 v158, v66, v79
	v_lshlrev_b32_e32 v66, 16, v221
	v_sub_f32_e32 v159, v66, v80
	v_and_b32_e32 v66, 0xffff0000, v221
	v_sub_f32_e32 v160, v66, v81
	ds_read_b128 v[66:69], v240 offset:8192
	s_waitcnt lgkmcnt(0)
	v_mfma_f32_32x32x16_bf16 v[66:81], v[66:69], v[82:85], 0
	v_cvt_pk_bf16_f32 v164, v157, v158
	v_cvt_pk_bf16_f32 v165, v159, v160
	v_cvt_pk_bf16_f32 v162, v97, v154
	v_cvt_pk_bf16_f32 v163, v155, v156
	v_cvt_pk_bf16_f32 v166, v0, v90
	v_cvt_pk_bf16_f32 v167, v91, v92
	v_cvt_pk_bf16_f32 v168, v93, v94
	v_mfma_f32_32x32x16_bf16 v[66:81], v[86:89], v[194:197], v[66:81]
	ds_read_b128 v[86:89], v240 offset:10240
	v_cvt_pk_bf16_f32 v169, v95, v96
	ds_bpermute_b32 v0, v241, v228
	v_add_u32_e32 v241, 4, v241
	s_waitcnt lgkmcnt(0)
; #define MFMA32(a, b, c) __builtin_amdgcn_mfma_f32_32x32x16_bf16((a), (b), (c), 0, 0, 0)
; DI void phaseB2(const Params& p, int bh, char* smem, int n_begin, int n_end) {
;     ...
;         for (int s = 0; s < 2; ++s) aw = MFMA32(ld16(wg + (it * 4096 + (T * 2 + s) * 512) + lo8), pack8(S[T], s), aw);
; #pragma unroll
;       for (int g = 0; g < 4; ++g) {
;         const uint2 uu = it == 0 ? (g == 0 ? pu0 : g == 1 ? pu1 : g == 2 ? pu2 : pu3) : (g == 0 ? pu4 : g == 1 ? pu5 : g == 2 ? pu6 : pu7);
;         vn[it][4 * g + 0] = __uint_as_float(uu.x << 16) - aw[4 * g + 0];
;         vn[it][4 * g + 1] = __uint_as_float(uu.x & 0xffff0000u) - aw[4 * g + 1];
;         vn[it][4 * g + 2] = __uint_as_float(uu.y << 16) - aw[4 * g + 2];
;         vn[it][4 * g + 3] = __uint_as_float(uu.y & 0xffff0000u) - aw[4 * g + 3];
;       }
;     }
;     B2_LOADU(n + 1 < 32 ? n + 1 : n);
;     bf16x8 Vb[2][2];
; #pragma unroll
;     for (int jt = 0; jt < 2; ++jt) { Vb[jt][0] = pack8(vn[jt], 0); Vb[jt][1] = pack8(vn[jt], 1); }
; #pragma unroll
;     for (int it = 0; it < 2; ++it) {
; #pragma unroll
;       for (int e = 0; e < 16; ++e) o[it][e] = 0.f;
; #pragma unroll
;       for (int T = 0; T < 4; ++T)
; #pragma unroll
;         for (int s = 0; s < 2; ++s) o[it] = MFMA32(ld16(qg + (it * 4096 + (T * 2 + s) * 512) + lo8), pack8(S[T], s), o[it]);
; #pragma unroll
;       for (int jt = 0; jt < 2; ++jt)
; #pragma unroll
;         for (int s = 0; s < 2; ++s)
;           o[it] = MFMA32(ld16(ag + (it * 2048 + (jt * 2 + s) * 512) + lo8), Vb[jt][s], o[it]);
;     }
;     const float egl = __shfl(eglv, n);
; #pragma unroll
;     for (int T = 0; T < 4; ++T) {
;       f32x16 acc;
; #pragma unroll
;       for (int e = 0; e < 16; ++e) acc[e] = S[T][e] * egl;
	v_pk_mul_f32 v[16:17], v[16:17], v[0:1] op_sel_hi:[1,0]
	v_mfma_f32_32x32x16_bf16 v[66:81], v[86:89], v[190:193], v[66:81]
	ds_read_b128 v[86:89], v240 offset:11264
	v_mul_f32_e64 v14, v14, v0
	v_mul_f32_e64 v15, v15, v0
	v_mul_f32_e64 v12, v12, v0
	v_mul_f32_e64 v13, v13, v0
	v_pk_mul_f32 v[10:11], v[10:11], v[0:1] op_sel_hi:[1,0]
	v_pk_mul_f32 v[8:9], v[8:9], v[0:1] op_sel_hi:[1,0]
	v_pk_mul_f32 v[6:7], v[6:7], v[0:1] op_sel_hi:[1,0]
	v_pk_mul_f32 v[4:5], v[4:5], v[0:1] op_sel_hi:[1,0]
	s_waitcnt lgkmcnt(0)
	v_mfma_f32_32x32x16_bf16 v[66:81], v[86:89], v[186:189], v[66:81]
	ds_read_b128 v[86:89], v240 offset:12288
	v_mul_f32_e64 v2, v2, v0
	v_mul_f32_e64 v3, v3, v0
	v_mul_f32_e64 v64, v64, v0
	v_mul_f32_e64 v65, v65, v0
	v_pk_mul_f32 v[62:63], v[62:63], v[0:1] op_sel_hi:[1,0]
	v_pk_mul_f32 v[60:61], v[60:61], v[0:1] op_sel_hi:[1,0]
	v_pk_mul_f32 v[58:59], v[58:59], v[0:1] op_sel_hi:[1,0]
	v_pk_mul_f32 v[56:57], v[56:57], v[0:1] op_sel_hi:[1,0]
	s_waitcnt lgkmcnt(0)
	v_mfma_f32_32x32x16_bf16 v[66:81], v[86:89], v[182:185], v[66:81]
	ds_read_b128 v[86:89], v240 offset:13312
	v_mul_f32_e64 v54, v54, v0
	v_mul_f32_e64 v55, v55, v0
	v_mul_f32_e64 v52, v52, v0
	v_mul_f32_e64 v53, v53, v0
	v_pk_mul_f32 v[50:51], v[50:51], v[0:1] op_sel_hi:[1,0]
	v_pk_mul_f32 v[48:49], v[48:49], v[0:1] op_sel_hi:[1,0]
	v_pk_mul_f32 v[46:47], v[46:47], v[0:1] op_sel_hi:[1,0]
	v_pk_mul_f32 v[44:45], v[44:45], v[0:1] op_sel_hi:[1,0]
	s_waitcnt lgkmcnt(0)
	v_mfma_f32_32x32x16_bf16 v[66:81], v[86:89], v[178:181], v[66:81]
	ds_read_b128 v[86:89], v240 offset:14336
	v_mul_f32_e64 v42, v42, v0
	v_mul_f32_e64 v43, v43, v0
	v_mul_f32_e64 v40, v40, v0
	v_mul_f32_e64 v41, v41, v0
	v_pk_mul_f32 v[38:39], v[38:39], v[0:1] op_sel_hi:[1,0]
	v_pk_mul_f32 v[36:37], v[36:37], v[0:1] op_sel_hi:[1,0]
	v_pk_mul_f32 v[34:35], v[34:35], v[0:1] op_sel_hi:[1,0]
	v_pk_mul_f32 v[32:33], v[32:33], v[0:1] op_sel_hi:[1,0]
	s_waitcnt lgkmcnt(0)
	v_mfma_f32_32x32x16_bf16 v[66:81], v[86:89], v[174:177], v[66:81]
	ds_read_b128 v[86:89], v240 offset:15360
	v_mul_f32_e64 v30, v30, v0
	v_mul_f32_e64 v31, v31, v0
	v_mul_f32_e64 v28, v28, v0
	v_mul_f32_e64 v29, v29, v0
	v_pk_mul_f32 v[26:27], v[26:27], v[0:1] op_sel_hi:[1,0]
	v_pk_mul_f32 v[24:25], v[24:25], v[0:1] op_sel_hi:[1,0]
	v_pk_mul_f32 v[22:23], v[22:23], v[0:1] op_sel_hi:[1,0]
	v_pk_mul_f32 v[20:21], v[20:21], v[0:1] op_sel_hi:[1,0]
	s_waitcnt lgkmcnt(0)
	v_mfma_f32_32x32x16_bf16 v[66:81], v[86:89], v[170:173], v[66:81]
	s_waitcnt vmcnt(17)
	v_lshlrev_b32_e32 v86, 16, v206
	v_and_b32_e32 v87, 0xffff0000, v206
	v_mul_f32_e64 v18, v18, v0
	v_mul_f32_e64 v19, v19, v0
	s_nop 6
	v_pk_add_f32 v[66:67], v[86:87], v[66:67] neg_lo:[0,1] neg_hi:[0,1]
	v_lshlrev_b32_e32 v86, 16, v207
	v_and_b32_e32 v87, 0xffff0000, v207
	v_pk_add_f32 v[68:69], v[86:87], v[68:69] neg_lo:[0,1] neg_hi:[0,1]
	s_waitcnt vmcnt(16)
	v_lshlrev_b32_e32 v86, 16, v204
	v_and_b32_e32 v87, 0xffff0000, v204
	v_pk_add_f32 v[70:71], v[86:87], v[70:71] neg_lo:[0,1] neg_hi:[0,1]
	v_lshlrev_b32_e32 v86, 16, v205
	v_and_b32_e32 v87, 0xffff0000, v205
	v_pk_add_f32 v[72:73], v[86:87], v[72:73] neg_lo:[0,1] neg_hi:[0,1]
	s_waitcnt vmcnt(15)
	v_lshlrev_b32_e32 v86, 16, v202
	v_and_b32_e32 v87, 0xffff0000, v202
	v_pk_add_f32 v[74:75], v[86:87], v[74:75] neg_lo:[0,1] neg_hi:[0,1]
	v_lshlrev_b32_e32 v86, 16, v203
	v_and_b32_e32 v87, 0xffff0000, v203
	v_pk_add_f32 v[76:77], v[86:87], v[76:77] neg_lo:[0,1] neg_hi:[0,1]
	s_waitcnt vmcnt(14)
	v_lshlrev_b32_e32 v86, 16, v200
	v_and_b32_e32 v87, 0xffff0000, v200
	v_pk_add_f32 v[78:79], v[86:87], v[78:79] neg_lo:[0,1] neg_hi:[0,1]
	v_lshlrev_b32_e32 v86, 16, v201
	v_and_b32_e32 v87, 0xffff0000, v201
	v_pk_add_f32 v[80:81], v[86:87], v[80:81] neg_lo:[0,1] neg_hi:[0,1]
	v_lshl_add_u64 v[86:87], v[216:217], 0, s[6:7]
	global_load_dwordx2 v[226:227], v[86:87], off
	global_load_dwordx2 v[224:225], v[86:87], off offset:512
	global_load_dwordx2 v[222:223], v[86:87], off offset:1024
	global_load_dwordx2 v[220:221], v[86:87], off offset:1536
	global_load_dwordx2 v[206:207], v[86:87], off offset:2048
	global_load_dwordx2 v[204:205], v[86:87], off offset:2560
	global_load_dwordx2 v[202:203], v[86:87], off offset:3072
	global_load_dwordx2 v[200:201], v[86:87], off offset:3584
	v_cvt_pk_bf16_f32 v158, v66, v67
	v_cvt_pk_bf16_f32 v159, v68, v69
	ds_read_b128 v[66:69], v240 offset:16384
	ds_read_b128 v[86:89], v240 offset:17408
	v_cvt_pk_bf16_f32 v160, v70, v71
	v_cvt_pk_bf16_f32 v161, v72, v73
	v_cvt_pk_bf16_f32 v154, v74, v75
	v_cvt_pk_bf16_f32 v155, v76, v77
	v_cvt_pk_bf16_f32 v156, v78, v79
	v_cvt_pk_bf16_f32 v157, v80, v81
	s_waitcnt lgkmcnt(1)
	v_mfma_f32_32x32x16_bf16 v[66:81], v[66:69], v[82:85], 0
	ds_read_b128 v[242:245], v240 offset:25600
	s_waitcnt lgkmcnt(1)
	v_mfma_f32_32x32x16_bf16 v[66:81], v[86:89], v[194:197], v[66:81]
	ds_read_b128 v[86:89], v240 offset:18432
	s_waitcnt lgkmcnt(0)
	v_mfma_f32_32x32x16_bf16 v[66:81], v[86:89], v[190:193], v[66:81]
	ds_read_b128 v[86:89], v240 offset:19456
	s_waitcnt lgkmcnt(0)
	v_mfma_f32_32x32x16_bf16 v[66:81], v[86:89], v[186:189], v[66:81]
	ds_read_b128 v[86:89], v240 offset:20480
	s_waitcnt lgkmcnt(0)
	v_mfma_f32_32x32x16_bf16 v[66:81], v[86:89], v[182:185], v[66:81]
	ds_read_b128 v[86:89], v240 offset:21504
	s_waitcnt lgkmcnt(0)
	v_mfma_f32_32x32x16_bf16 v[66:81], v[86:89], v[178:181], v[66:81]
	ds_read_b128 v[86:89], v240 offset:22528
	s_waitcnt lgkmcnt(0)
	v_mfma_f32_32x32x16_bf16 v[66:81], v[86:89], v[174:177], v[66:81]
	ds_read_b128 v[86:89], v240 offset:23552
	s_waitcnt lgkmcnt(0)
	v_mfma_f32_32x32x16_bf16 v[66:81], v[86:89], v[170:173], v[66:81]
	ds_read_b128 v[86:89], v240 offset:49152
	s_waitcnt lgkmcnt(0)
; #define MFMA32(a, b, c) __builtin_amdgcn_mfma_f32_32x32x16_bf16((a), (b), (c), 0, 0, 0)
; #define B2_STORE() do { uint4* l_ = (uint4*)L + tid; \
;     l_[0] = pw0; l_[256] = pw1; l_[512] = pw2; l_[768] = pw3; l_[1024] = pq0; l_[1280] = pq1; l_[1536] = pq2; l_[1792] = pq3; \
;     l_[2048] = pk0; l_[2304] = pk1; l_[2560] = pk2; l_[2816] = pk3; l_[3072] = pa0; l_[3328] = pa1; } while (0)
; DI void phaseB2(const Params& p, int bh, char* smem, int n_begin, int n_end) {
;     ...
;         for (int s = 0; s < 2; ++s) o[it] = MFMA32(ld16(qg + (it * 4096 + (T * 2 + s) * 512) + lo8), pack8(S[T], s), o[it]);
; #pragma unroll
;       for (int jt = 0; jt < 2; ++jt)
; #pragma unroll
;         for (int s = 0; s < 2; ++s)
;           o[it] = MFMA32(ld16(ag + (it * 2048 + (jt * 2 + s) * 512) + lo8), Vb[jt][s], o[it]);
;     }
;     const float egl = __shfl(eglv, n);
; #pragma unroll
;     for (int T = 0; T < 4; ++T) {
;       f32x16 acc;
; #pragma unroll
;       for (int e = 0; e < 16; ++e) acc[e] = S[T][e] * egl;
; #pragma unroll
;       for (int jt = 0; jt < 2; ++jt)
; #pragma unroll
;         for (int s = 0; s < 2; ++s)
;           acc = MFMA32(ld16(kg + (T * 2048 + (jt * 2 + s) * 512) + lo8), Vb[jt][s], acc);
;       S[T] = acc;
;     }
;     asm volatile("s_waitcnt lgkmcnt(0)\n\ts_barrier" ::: "memory");
;     B2_STORE();
	v_mfma_f32_32x32x16_bf16 v[66:81], v[86:89], v[166:169], v[66:81]
	ds_read_b128 v[86:89], v240 offset:50176
	s_waitcnt lgkmcnt(0)
	v_mfma_f32_32x32x16_bf16 v[66:81], v[86:89], v[162:165], v[66:81]
	ds_read_b128 v[86:89], v240 offset:51200
	s_waitcnt lgkmcnt(0)
	v_mfma_f32_32x32x16_bf16 v[66:81], v[86:89], v[158:161], v[66:81]
	ds_read_b128 v[86:89], v240 offset:52224
	s_waitcnt lgkmcnt(0)
	v_mfma_f32_32x32x16_bf16 v[66:81], v[86:89], v[154:157], v[66:81]
	ds_read_b128 v[86:89], v240 offset:24576
	s_waitcnt lgkmcnt(0)
	v_mfma_f32_32x32x16_bf16 v[82:97], v[86:89], v[82:85], 0
	s_nop 8
	v_cvt_pk_bf16_f32 v0, v66, s0
	v_mfma_f32_32x32x16_bf16 v[82:97], v[242:245], v[194:197], v[82:97]
	ds_read_b128 v[194:197], v240 offset:26624
	s_waitcnt lgkmcnt(0)
	v_mfma_f32_32x32x16_bf16 v[82:97], v[194:197], v[190:193], v[82:97]
	ds_read_b128 v[190:193], v240 offset:27648
	s_waitcnt lgkmcnt(0)
	v_mfma_f32_32x32x16_bf16 v[82:97], v[190:193], v[186:189], v[82:97]
	ds_read_b128 v[186:189], v240 offset:28672
	s_waitcnt lgkmcnt(0)
	v_mfma_f32_32x32x16_bf16 v[82:97], v[186:189], v[182:185], v[82:97]
	ds_read_b128 v[182:185], v240 offset:29696
	s_waitcnt lgkmcnt(0)
	v_mfma_f32_32x32x16_bf16 v[82:97], v[182:185], v[178:181], v[82:97]
	ds_read_b128 v[178:181], v240 offset:30720
	s_waitcnt lgkmcnt(0)
	v_mfma_f32_32x32x16_bf16 v[82:97], v[178:181], v[174:177], v[82:97]
	ds_read_b128 v[174:177], v240 offset:31744
	s_waitcnt lgkmcnt(0)
	v_mfma_f32_32x32x16_bf16 v[82:97], v[174:177], v[170:173], v[82:97]
	ds_read_b128 v[170:173], v240 offset:53248
	s_waitcnt lgkmcnt(0)
	v_mfma_f32_32x32x16_bf16 v[82:97], v[170:173], v[166:169], v[82:97]
	ds_read_b128 v[170:173], v240 offset:54272
	s_waitcnt lgkmcnt(0)
	v_mfma_f32_32x32x16_bf16 v[82:97], v[170:173], v[162:165], v[82:97]
	ds_read_b128 v[170:173], v240 offset:55296
	s_waitcnt lgkmcnt(0)
	v_mfma_f32_32x32x16_bf16 v[82:97], v[170:173], v[158:161], v[82:97]
	ds_read_b128 v[170:173], v240 offset:56320
	s_waitcnt lgkmcnt(0)
	v_mfma_f32_32x32x16_bf16 v[82:97], v[170:173], v[154:157], v[82:97]
	ds_read_b128 v[170:173], v240 offset:32768
	s_waitcnt lgkmcnt(0)
	v_mfma_f32_32x32x16_bf16 v[2:17], v[170:173], v[166:169], v[2:17]
	ds_read_b128 v[170:173], v240 offset:33792
	s_waitcnt lgkmcnt(0)
	v_mfma_f32_32x32x16_bf16 v[2:17], v[170:173], v[162:165], v[2:17]
	ds_read_b128 v[170:173], v240 offset:34816
	s_waitcnt lgkmcnt(0)
	v_mfma_f32_32x32x16_bf16 v[2:17], v[170:173], v[158:161], v[2:17]
	ds_read_b128 v[170:173], v240 offset:35840
	s_waitcnt lgkmcnt(0)
	v_mfma_f32_32x32x16_bf16 v[2:17], v[170:173], v[154:157], v[2:17]
	ds_read_b128 v[170:173], v240 offset:36864
	s_waitcnt lgkmcnt(0)
	v_mfma_f32_32x32x16_bf16 v[50:65], v[170:173], v[166:169], v[50:65]
	ds_read_b128 v[170:173], v240 offset:37888
	s_waitcnt lgkmcnt(0)
	v_mfma_f32_32x32x16_bf16 v[50:65], v[170:173], v[162:165], v[50:65]
	ds_read_b128 v[170:173], v240 offset:38912
	s_waitcnt lgkmcnt(0)
	v_mfma_f32_32x32x16_bf16 v[50:65], v[170:173], v[158:161], v[50:65]
	ds_read_b128 v[170:173], v240 offset:39936
	s_waitcnt lgkmcnt(0)
	v_mfma_f32_32x32x16_bf16 v[50:65], v[170:173], v[154:157], v[50:65]
	ds_read_b128 v[170:173], v240 offset:40960
	s_waitcnt lgkmcnt(0)
	v_mfma_f32_32x32x16_bf16 v[34:49], v[170:173], v[166:169], v[34:49]
	ds_read_b128 v[170:173], v240 offset:41984
	s_waitcnt lgkmcnt(0)
	v_mfma_f32_32x32x16_bf16 v[34:49], v[170:173], v[162:165], v[34:49]
	ds_read_b128 v[170:173], v240 offset:43008
	s_waitcnt lgkmcnt(0)
	v_mfma_f32_32x32x16_bf16 v[34:49], v[170:173], v[158:161], v[34:49]
	ds_read_b128 v[170:173], v240 offset:44032
	s_waitcnt lgkmcnt(0)
	v_mfma_f32_32x32x16_bf16 v[34:49], v[170:173], v[154:157], v[34:49]
	ds_read_b128 v[170:173], v240 offset:45056
	s_waitcnt lgkmcnt(0)
	v_mfma_f32_32x32x16_bf16 v[18:33], v[170:173], v[166:169], v[18:33]
	ds_read_b128 v[166:169], v240 offset:46080
	s_waitcnt lgkmcnt(0)
	v_mfma_f32_32x32x16_bf16 v[18:33], v[166:169], v[162:165], v[18:33]
	ds_read_b128 v[162:165], v240 offset:47104
	s_waitcnt lgkmcnt(0)
	v_mfma_f32_32x32x16_bf16 v[18:33], v[162:165], v[158:161], v[18:33]
	ds_read_b128 v[158:161], v240 offset:48128
	s_waitcnt lgkmcnt(0)
	s_barrier
	s_waitcnt vmcnt(21)
	ds_write_b128 v229, v[98:101]
	s_waitcnt vmcnt(20)
	ds_write_b128 v229, v[102:105] offset:4096
	s_waitcnt vmcnt(19)
	ds_write_b128 v229, v[106:109] offset:8192
	s_waitcnt vmcnt(18)
	ds_write_b128 v229, v[110:113] offset:12288
	s_waitcnt vmcnt(17)
	ds_write_b128 v229, v[114:117] offset:16384
	s_waitcnt vmcnt(16)
	ds_write_b128 v229, v[118:121] offset:20480
	s_waitcnt vmcnt(15)
	ds_write_b128 v229, v[122:125] offset:24576
	s_waitcnt vmcnt(14)
	ds_write_b128 v229, v[126:129] offset:28672
	s_waitcnt vmcnt(13)
	ds_write_b128 v229, v[130:133] offset:32768
	s_waitcnt vmcnt(12)
	ds_write_b128 v229, v[134:137] offset:36864
	s_waitcnt vmcnt(11)
	ds_write_b128 v229, v[138:141] offset:40960
	s_waitcnt vmcnt(10)
	ds_write_b128 v229, v[142:145] offset:45056
	s_waitcnt vmcnt(9)
	ds_write_b128 v229, v[146:149] offset:49152
	s_waitcnt vmcnt(8)
	ds_write_b128 v229, v[150:153] offset:53248
	v_lshl_add_u64 v[98:99], v[218:219], 0, s[4:5]
	s_waitcnt lgkmcnt(0)
	s_barrier
; #define MFMA32(a, b, c) __builtin_amdgcn_mfma_f32_32x32x16_bf16((a), (b), (c), 0, 0, 0)
; DI bf16_t f2bf(float x) { return (bf16_t)(pack2(x, 0.f) & 0xffffu); }
; DI int crow(int reg, int hh) { return (reg & 3) + 8 * (reg >> 2) + 4 * hh; }
; #define B2_STORE() do { uint4* l_ = (uint4*)L + tid; \
;     l_[0] = pw0; l_[256] = pw1; l_[512] = pw2; l_[768] = pw3; l_[1024] = pq0; l_[1280] = pq1; l_[1536] = pq2; l_[1792] = pq3; \
;     l_[2048] = pk0; l_[2304] = pk1; l_[2560] = pk2; l_[2816] = pk3; l_[3072] = pa0; l_[3328] = pa1; } while (0)
; DI void phaseB2(const Params& p, int bh, char* smem, int n_begin, int n_end) {
;     ...
;           acc = MFMA32(ld16(kg + (T * 2048 + (jt * 2 + s) * 512) + lo8), Vb[jt][s], acc);
;       S[T] = acc;
;     }
;     asm volatile("s_waitcnt lgkmcnt(0)\n\ts_barrier" ::: "memory");
;     B2_STORE();
;     asm volatile("s_waitcnt lgkmcnt(0)\n\ts_barrier" ::: "memory");
;     {
;       bf16_t* og = p.ob + (size_t)(b * SEQ + n * 64) * 512 + hd * 128 + v0 + r;
; #pragma unroll
;       for (int it = 0; it < 2; ++it)
; #pragma unroll
;         for (int e = 0; e < 16; ++e) og[(size_t)(it * 32 + crow(e, hh)) * 512] = f2bf(o[it][e]);
;     }
;   }
;   if (n_end < 32) {
; #pragma unroll
;     for (int T = 0; T < 4; ++T)
; #pragma unroll
;       for (int q4 = 0; q4 < 4; ++q4)
;         *(float4*)(sst + T * 16 + q4 * 4) = make_float4(S[T][q4 * 4], S[T][q4 * 4 + 1], S[T][q4 * 4 + 2], S[T][q4 * 4 + 3]);
;   }
;   __syncthreads();
; __global__ void __launch_bounds__(256, 2) mega(Params p, int ph_lo, int ph_hi) {
;     ...
;         if (nb2 == 0) for (int u = blockIdx.x; u < 64; u += gridDim.x) phaseB2(p, u, smem, 0, B2_S1);
	global_store_short v[98:99], v0, off
	v_cvt_pk_bf16_f32 v0, v67, s0
	global_store_short v[98:99], v0, off offset:1024
	v_cvt_pk_bf16_f32 v0, v68, s0
	global_store_short v[98:99], v0, off offset:2048
	v_cvt_pk_bf16_f32 v0, v69, s0
	v_add_co_u32_e32 v66, vcc, s80, v98
	global_store_short v[98:99], v0, off offset:3072
	v_cvt_pk_bf16_f32 v0, v70, s0
	v_addc_co_u32_e32 v67, vcc, 0, v99, vcc
	global_store_short v[66:67], v0, off
	v_cvt_pk_bf16_f32 v0, v71, s0
	global_store_short v[66:67], v0, off offset:1024
	v_cvt_pk_bf16_f32 v0, v72, s0
	global_store_short v[66:67], v0, off offset:2048
	v_cvt_pk_bf16_f32 v0, v73, s0
	global_store_short v[66:67], v0, off offset:3072
	v_add_co_u32_e32 v66, vcc, s95, v98
	v_cvt_pk_bf16_f32 v0, v74, s0
	s_nop 0
	v_addc_co_u32_e32 v67, vcc, 0, v99, vcc
	global_store_short v[66:67], v0, off
	v_cvt_pk_bf16_f32 v0, v75, s0
	global_store_short v[66:67], v0, off offset:1024
	v_cvt_pk_bf16_f32 v0, v76, s0
	global_store_short v[66:67], v0, off offset:2048
	v_cvt_pk_bf16_f32 v0, v77, s0
	global_store_short v[66:67], v0, off offset:3072
	v_add_co_u32_e32 v66, vcc, s1, v98
	v_cvt_pk_bf16_f32 v0, v78, s0
	s_nop 0
	v_addc_co_u32_e32 v67, vcc, 0, v99, vcc
	global_store_short v[66:67], v0, off
	v_cvt_pk_bf16_f32 v0, v79, s0
	global_store_short v[66:67], v0, off offset:1024
	v_cvt_pk_bf16_f32 v0, v80, s0
	global_store_short v[66:67], v0, off offset:2048
	v_cvt_pk_bf16_f32 v0, v81, s0
	global_store_short v[66:67], v0, off offset:3072
	v_add_co_u32_e32 v66, vcc, s51, v98
	v_cvt_pk_bf16_f32 v0, v82, s0
	s_nop 0
	v_addc_co_u32_e32 v67, vcc, 0, v99, vcc
	global_store_short v[66:67], v0, off
	v_cvt_pk_bf16_f32 v0, v83, s0
	global_store_short v[66:67], v0, off offset:1024
	v_cvt_pk_bf16_f32 v0, v84, s0
	global_store_short v[66:67], v0, off offset:2048
	v_cvt_pk_bf16_f32 v0, v85, s0
	global_store_short v[66:67], v0, off offset:3072
	v_add_co_u32_e32 v66, vcc, s9, v98
	v_cvt_pk_bf16_f32 v0, v86, s0
	s_nop 0
	v_addc_co_u32_e32 v67, vcc, 0, v99, vcc
	global_store_short v[66:67], v0, off
	v_cvt_pk_bf16_f32 v0, v87, s0
	global_store_short v[66:67], v0, off offset:1024
	v_cvt_pk_bf16_f32 v0, v88, s0
	global_store_short v[66:67], v0, off offset:2048
	v_cvt_pk_bf16_f32 v0, v89, s0
	global_store_short v[66:67], v0, off offset:3072
	v_add_co_u32_e32 v66, vcc, s12, v98
	v_cvt_pk_bf16_f32 v0, v90, s0
	s_nop 0
	v_addc_co_u32_e32 v67, vcc, 0, v99, vcc
	s_waitcnt lgkmcnt(14)
	v_mfma_f32_32x32x16_bf16 v[18:33], v[158:161], v[154:157], v[18:33]
	global_store_short v[66:67], v0, off
	v_cvt_pk_bf16_f32 v0, v91, s0
	global_store_short v[66:67], v0, off offset:1024
	v_cvt_pk_bf16_f32 v0, v92, s0
	global_store_short v[66:67], v0, off offset:2048
	v_cvt_pk_bf16_f32 v0, v93, s0
	global_store_short v[66:67], v0, off offset:3072
	v_add_co_u32_e32 v66, vcc, s13, v98
	v_cvt_pk_bf16_f32 v0, v94, s0
	s_nop 0
	v_addc_co_u32_e32 v67, vcc, 0, v99, vcc
	global_store_short v[66:67], v0, off
	v_cvt_pk_bf16_f32 v0, v95, s0
	s_add_u32 s4, s4, 0x10000
	global_store_short v[66:67], v0, off offset:1024
	v_cvt_pk_bf16_f32 v0, v96, s0
	s_addc_u32 s5, s5, 0
	s_add_i32 s2, s2, 4
	global_store_short v[66:67], v0, off offset:2048
	v_cvt_pk_bf16_f32 v0, v97, s0
	s_cmp_lg_u32 s4, 0x130000
	global_store_short v[66:67], v0, off offset:3072
	s_cbranch_scc1 .LBB0_1774
	s_setprio 0
	s_ashr_i32 s1, s0, 31
	v_readlane_b32 s16, v253, 11
	s_lshl_b64 s[2:3], s[0:1], 16
	v_readlane_b32 s24, v253, 19
	v_readlane_b32 s25, v253, 20
	s_add_u32 s2, s24, s2
	v_readlane_b32 s1, v253, 56
	s_addc_u32 s3, s25, s3
	v_lshlrev_b64 v[66:67], 8, v[198:199]
	s_add_i32 s0, s0, s1
	s_add_i32 s8, s8, s1
	v_readlane_b32 s26, v253, 21
	v_readlane_b32 s27, v253, 22
	v_readlane_b32 s28, v253, 23
	v_readlane_b32 s29, v253, 24
	v_readlane_b32 s30, v253, 25
	v_readlane_b32 s31, v253, 26
	v_lshl_add_u64 v[66:67], s[2:3], 0, v[66:67]
	s_cmp_gt_i32 s0, 63
	v_readlane_b32 s17, v253, 12
	v_readlane_b32 s18, v253, 13
	v_readlane_b32 s19, v253, 14
	v_readlane_b32 s20, v253, 15
	v_readlane_b32 s21, v253, 16
	v_readlane_b32 s22, v253, 17
	v_readlane_b32 s23, v253, 18
	global_store_dwordx4 v[66:67], v[2:5], off
	global_store_dwordx4 v[66:67], v[6:9], off offset:16
	global_store_dwordx4 v[66:67], v[10:13], off offset:32
	global_store_dwordx4 v[66:67], v[14:17], off offset:48
	global_store_dwordx4 v[66:67], v[50:53], off offset:64
	global_store_dwordx4 v[66:67], v[54:57], off offset:80
	global_store_dwordx4 v[66:67], v[58:61], off offset:96
	global_store_dwordx4 v[66:67], v[62:65], off offset:112
	global_store_dwordx4 v[66:67], v[34:37], off offset:128
	global_store_dwordx4 v[66:67], v[38:41], off offset:144
	global_store_dwordx4 v[66:67], v[42:45], off offset:160
	global_store_dwordx4 v[66:67], v[46:49], off offset:176
	global_store_dwordx4 v[66:67], v[18:21], off offset:192
	global_store_dwordx4 v[66:67], v[22:25], off offset:208
	global_store_dwordx4 v[66:67], v[26:29], off offset:224
	global_store_dwordx4 v[66:67], v[30:33], off offset:240
	s_waitcnt lgkmcnt(0)
	s_barrier
	s_cbranch_scc0 .LBB0_1773
